# attention A+B: max/rescale check moved off the fast path (tile-sum guard, exact slow-path redo); bitwise-identical outputs
# speedup vs baseline: 1.0135x; 1.0135x over previous
; #define LAS __attribute__((address_space(3)))
; DI float fast_exp2(float x) { return __builtin_amdgcn_exp2f(x); }
; template <int DQK, int NMAP>
; DI void att_qk(const LAS unsigned char* Kb, int r, int h, const bf16x8 (&qfm)[DQK / NMAP / 16], int mp, f32x16 (&S)[2]) {
;     constexpr int DQM = DQK / NMAP, NKS = DQM / 16, KP = DQK * 2 + 16, CH = (NKS > 4) ? 3 : NKS;
;     const LAS unsigned char* kp = Kb + r * KP + (mp * DQM + 8 * h) * 2;
;     const f32x16 z = {0.f, 0.f, 0.f, 0.f, 0.f, 0.f, 0.f, 0.f, 0.f, 0.f, 0.f, 0.f, 0.f, 0.f, 0.f, 0.f};
; #pragma unroll
;     for (int c = 0; c < NKS / CH; ++c) {
;         bf16x8 kf[2 * CH];
; #pragma unroll
;         for (int s = 0; s < CH; ++s) { kf[2 * s] = *(const LAS bf16x8*)(kp + 32 * (c * CH + s)); kf[2 * s + 1] = *(const LAS bf16x8*)(kp + 32 * KP + 32 * (c * CH + s)); }
;         __builtin_amdgcn_sched_barrier(0);
;         __builtin_amdgcn_s_setprio(1);
; #pragma unroll
;         for (int s = 0; s < CH; ++s) {
;             if (c == 0 && s == 0) { S[0] = __builtin_amdgcn_mfma_f32_32x32x16_bf16(kf[0], qfm[0], z, 0, 0, 0); S[1] = __builtin_amdgcn_mfma_f32_32x32x16_bf16(kf[1], qfm[0], z, 0, 0, 0); }
;             else { S[0] = __builtin_amdgcn_mfma_f32_32x32x16_bf16(kf[2 * s], qfm[c * CH + s], S[0], 0, 0, 0); S[1] = __builtin_amdgcn_mfma_f32_32x32x16_bf16(kf[2 * s + 1], qfm[c * CH + s], S[1], 0, 0, 0); }
;         }
;         __builtin_amdgcn_s_setprio(0);
;         __builtin_amdgcn_sched_barrier(0);
;     }
; DI void att_sm_tail(f32x16 (&S)[2], bf16x8 (&pkm)[2][2], const float mrefm, float& lrunm) {
;     {
;         f32x16& s0 = S[0]; f32x16& s1 = S[1];
;         const f32x2 nm2 = {-mrefm, -mrefm};
;         f32x2 acc2 = {0.f, 0.f};
; #pragma unroll
;         for (int i = 0; i < 16; i += 2) {
;             f32x2 a = {s0[i], s0[i + 1]}, b = {s1[i], s1[i + 1]}; a += nm2; b += nm2;
;             a.x = fast_exp2(a.x); a.y = fast_exp2(a.y); b.x = fast_exp2(b.x); b.y = fast_exp2(b.y);
;             acc2 += a; acc2 += b; s0[i] = a.x; s0[i + 1] = a.y; s1[i] = b.x; s1[i + 1] = b.y;
;         }
;         lrunm += acc2.x + acc2.y;
; #pragma unroll
;         for (int s = 0; s < 2; ++s) {
;             u32x4 w0, w1;
;             w0.x = pk2(s0[8 * s + 0], s0[8 * s + 1]); w0.y = pk2(s0[8 * s + 2], s0[8 * s + 3]); w0.z = pk2(s0[8 * s + 4], s0[8 * s + 5]); w0.w = pk2(s0[8 * s + 6], s0[8 * s + 7]);
.LBB0_574:
	s_add_i32 s13, s12, 3
	s_cmp_lt_u32 s13, s9
	s_cselect_b32 s3, s13, s8
	s_lshl_b32 s4, s3, 6
	s_add_i32 s4, s4, s0
	s_cmp_lt_u32 s3, 4
	s_cselect_b32 s4, s1, s4
	s_ashr_i32 s5, s4, 31
	v_lshl_add_u64 v[2:3], s[4:5], 0, v[200:201]
	v_lshl_add_u64 v[6:7], s[4:5], 0, v[202:203]
	v_lshlrev_b64 v[2:3], 9, v[2:3]
	v_mad_u64_u32 v[8:9], s[4:5], v6, s78, v[208:209]
	v_lshl_add_u64 v[2:3], v[206:207], 0, v[2:3]
	v_mad_i32_i24 v9, v7, s78, v9
	global_load_dwordx4 v[2:5], v[2:3], off
	s_cmp_ge_u32 s12, s9
	global_load_dwordx4 v[6:9], v[8:9], off
	s_cbranch_scc1 .LBB0_580
	s_bitcmp1_b32 s12, 0
	s_cselect_b32 s3, 0x2400, 0
	v_add_u32_e32 v0, s3, v244
	ds_read_b128 v[10:13], v0
	ds_read_b128 v[80:83], v0 offset:32
	ds_read_b128 v[84:87], v0 offset:4608
	ds_read_b128 v[88:91], v0 offset:4640
	s_setprio 1
	s_waitcnt lgkmcnt(3)
	v_mfma_f32_32x32x16_bf16 v[112:127], v[10:13], v[156:159], 0
	s_waitcnt lgkmcnt(1)
	v_mfma_f32_32x32x16_bf16 v[128:143], v[84:87], v[156:159], 0
	v_mfma_f32_32x32x16_bf16 v[112:127], v[80:83], v[160:163], v[112:127]
	s_waitcnt lgkmcnt(0)
	v_mfma_f32_32x32x16_bf16 v[128:143], v[88:91], v[160:163], v[128:143]
	s_setprio 0
	ds_read_b128 v[10:13], v0 offset:64
	ds_read_b128 v[180:183], v0 offset:96
	ds_read_b128 v[96:99], v0 offset:4672
	ds_read_b128 v[184:187], v0 offset:4704
	s_setprio 1
	s_waitcnt lgkmcnt(3)
	v_mfma_f32_32x32x16_bf16 v[80:95], v[10:13], v[164:167], 0
	s_waitcnt lgkmcnt(1)
	v_mfma_f32_32x32x16_bf16 v[96:111], v[96:99], v[164:167], 0
	v_mfma_f32_32x32x16_bf16 v[80:95], v[180:183], v[168:171], v[80:95]
	s_waitcnt lgkmcnt(0)
	v_mfma_f32_32x32x16_bf16 v[96:111], v[184:187], v[168:171], v[96:111]
	s_setprio 0
	v_add_u32_e32 v0, v238, v237
	ds_read_b64_tr_b16 v[188:189], v0 offset:18432
	ds_read_b64_tr_b16 v[190:191], v0 offset:19584
	ds_read_b64_tr_b16 v[184:185], v0 offset:20736
	ds_read_b64_tr_b16 v[186:187], v0 offset:21888
	ds_read_b64_tr_b16 v[180:181], v0 offset:23040
	ds_read_b64_tr_b16 v[182:183], v0 offset:24192
	ds_read_b64_tr_b16 v[10:11], v0 offset:25344
	ds_read_b64_tr_b16 v[12:13], v0 offset:26496
	s_nop 1
	v_pk_add_f32 v[14:15], v[112:113], v[212:213] op_sel_hi:[1,0] neg_lo:[0,1] neg_hi:[0,1]
	v_pk_add_f32 v[112:113], v[128:129], v[212:213] op_sel_hi:[1,0] neg_lo:[0,1] neg_hi:[0,1]
	v_exp_f32_e32 v14, v14
	v_exp_f32_e32 v15, v15
	v_exp_f32_e32 v112, v112
	v_exp_f32_e32 v113, v113
	v_pk_add_f32 v[114:115], v[114:115], v[212:213] op_sel_hi:[1,0] neg_lo:[0,1] neg_hi:[0,1]
	v_pk_add_f32 v[128:129], v[130:131], v[212:213] op_sel_hi:[1,0] neg_lo:[0,1] neg_hi:[0,1]
	v_exp_f32_e32 v114, v114
	v_exp_f32_e32 v115, v115
	v_exp_f32_e32 v128, v128
	v_exp_f32_e32 v129, v129
	v_pk_add_f32 v[116:117], v[116:117], v[212:213] op_sel_hi:[1,0] neg_lo:[0,1] neg_hi:[0,1]
	v_pk_add_f32 v[130:131], v[14:15], 0 op_sel_hi:[1,0]
	v_pk_add_f32 v[132:133], v[132:133], v[212:213] op_sel_hi:[1,0] neg_lo:[0,1] neg_hi:[0,1]
	v_exp_f32_e32 v116, v116
	v_exp_f32_e32 v117, v117
	v_pk_add_f32 v[130:131], v[112:113], v[130:131]
	v_exp_f32_e32 v132, v132
	v_exp_f32_e32 v133, v133
	v_pk_add_f32 v[118:119], v[118:119], v[212:213] op_sel_hi:[1,0] neg_lo:[0,1] neg_hi:[0,1]
	v_pk_add_f32 v[130:131], v[114:115], v[130:131]
	v_pk_add_f32 v[134:135], v[134:135], v[212:213] op_sel_hi:[1,0] neg_lo:[0,1] neg_hi:[0,1]
	v_exp_f32_e32 v118, v118
	v_exp_f32_e32 v119, v119
	v_pk_add_f32 v[130:131], v[128:129], v[130:131]
	v_exp_f32_e32 v134, v134
	v_exp_f32_e32 v135, v135
	v_pk_add_f32 v[120:121], v[120:121], v[212:213] op_sel_hi:[1,0] neg_lo:[0,1] neg_hi:[0,1]
	v_pk_add_f32 v[130:131], v[116:117], v[130:131]
	v_pk_add_f32 v[136:137], v[136:137], v[212:213] op_sel_hi:[1,0] neg_lo:[0,1] neg_hi:[0,1]
	v_exp_f32_e32 v246, v120
	v_exp_f32_e32 v247, v121
	v_pk_add_f32 v[130:131], v[132:133], v[130:131]
	v_exp_f32_e32 v136, v136
	v_exp_f32_e32 v137, v137
	v_pk_add_f32 v[120:121], v[122:123], v[212:213] op_sel_hi:[1,0] neg_lo:[0,1] neg_hi:[0,1]
	v_pk_add_f32 v[130:131], v[118:119], v[130:131]
	v_pk_add_f32 v[122:123], v[138:139], v[212:213] op_sel_hi:[1,0] neg_lo:[0,1] neg_hi:[0,1]
	v_exp_f32_e32 v138, v120
	v_exp_f32_e32 v139, v121
	v_pk_add_f32 v[130:131], v[134:135], v[130:131]
	v_exp_f32_e32 v248, v122
	v_exp_f32_e32 v249, v123
	v_pk_add_f32 v[122:123], v[124:125], v[212:213] op_sel_hi:[1,0] neg_lo:[0,1] neg_hi:[0,1]
	v_pk_add_f32 v[120:121], v[246:247], v[130:131]
	v_pk_add_f32 v[124:125], v[140:141], v[212:213] op_sel_hi:[1,0] neg_lo:[0,1] neg_hi:[0,1]
	v_exp_f32_e32 v130, v122
	v_exp_f32_e32 v131, v123
	v_pk_add_f32 v[120:121], v[136:137], v[120:121]
	v_exp_f32_e32 v140, v124
	v_exp_f32_e32 v141, v125
	v_pk_add_f32 v[122:123], v[126:127], v[212:213] op_sel_hi:[1,0] neg_lo:[0,1] neg_hi:[0,1]
	v_pk_add_f32 v[120:121], v[138:139], v[120:121]
	v_pk_add_f32 v[124:125], v[142:143], v[212:213] op_sel_hi:[1,0] neg_lo:[0,1] neg_hi:[0,1]
	v_exp_f32_e32 v142, v122
	v_exp_f32_e32 v143, v123
	v_pk_add_f32 v[120:121], v[248:249], v[120:121]
	v_exp_f32_e32 v250, v124
	v_exp_f32_e32 v251, v125
	v_pk_add_f32 v[120:121], v[130:131], v[120:121]
	v_cvt_pk_bf16_f32 v122, v116, v117
	v_pk_add_f32 v[120:121], v[140:141], v[120:121]
	v_cvt_pk_bf16_f32 v123, v118, v119
	v_pk_add_f32 v[120:121], v[142:143], v[120:121]
	v_cvt_pk_bf16_f32 v112, v112, v113
	v_pk_add_f32 v[120:121], v[250:251], v[120:121]
	v_cvt_pk_bf16_f32 v113, v128, v129
	v_add_f32_e32 v120, v120, v121
	v_mov_b32_e32 v231, v120
	v_cvt_pk_bf16_f32 v120, v14, v15
	v_cvt_pk_bf16_f32 v121, v114, v115
	v_cvt_pk_bf16_f32 v114, v132, v133
	v_cvt_pk_bf16_f32 v115, v134, v135
	v_cvt_pk_bf16_f32 v124, v246, v247
	v_cvt_pk_bf16_f32 v125, v138, v139
	v_cvt_pk_bf16_f32 v126, v130, v131
	v_cvt_pk_bf16_f32 v127, v142, v143
; DI void att_sm_tail(f32x16 (&S)[2], bf16x8 (&pkm)[2][2], const float mrefm, float& lrunm) {
;     {
;         f32x16& s0 = S[0]; f32x16& s1 = S[1];
;         const f32x2 nm2 = {-mrefm, -mrefm};
;         f32x2 acc2 = {0.f, 0.f};
; #pragma unroll
;         for (int i = 0; i < 16; i += 2) {
;             f32x2 a = {s0[i], s0[i + 1]}, b = {s1[i], s1[i + 1]}; a += nm2; b += nm2;
;             a.x = fast_exp2(a.x); a.y = fast_exp2(a.y); b.x = fast_exp2(b.x); b.y = fast_exp2(b.y);
;             acc2 += a; acc2 += b; s0[i] = a.x; s0[i + 1] = a.y; s1[i] = b.x; s1[i + 1] = b.y;
;         }
;         lrunm += acc2.x + acc2.y;
; #pragma unroll
;         for (int s = 0; s < 2; ++s) {
;             u32x4 w0, w1;
;             w0.x = pk2(s0[8 * s + 0], s0[8 * s + 1]); w0.y = pk2(s0[8 * s + 2], s0[8 * s + 3]); w0.z = pk2(s0[8 * s + 4], s0[8 * s + 5]); w0.w = pk2(s0[8 * s + 6], s0[8 * s + 7]);
;             w1.x = pk2(s1[8 * s + 0], s1[8 * s + 1]); w1.y = pk2(s1[8 * s + 2], s1[8 * s + 3]); w1.z = pk2(s1[8 * s + 4], s1[8 * s + 5]); w1.w = pk2(s1[8 * s + 6], s1[8 * s + 7]);
;             pkm[0][s] = __builtin_bit_cast(bf16x8, w0); pkm[1][s] = __builtin_bit_cast(bf16x8, w1);
;         }
;     }
; }
; DI void att_pvmm1(const s16x4 (&lo)[4], const s16x4 (&hi)[4], const bf16x8 (&pkm)[2][2], f32x16& oe) {
; #pragma unroll
;     for (int q = 0; q < 4; ++q) { const bf16x8 vf = (bf16x8){lo[q][0], lo[q][1], lo[q][2], lo[q][3], hi[q][0], hi[q][1], hi[q][2], hi[q][3]};
;         oe = __builtin_amdgcn_mfma_f32_32x32x16_bf16(vf, pkm[q >> 1][q & 1], oe, 0, 0, 0); }
; }
; DI void att_vload(const LAS unsigned char* vb, int e, s16x4 (&lo)[4], s16x4 (&hi)[4]) {
;     constexpr int VP = 144;
; #pragma unroll
;     for (int q = 0; q < 4; ++q) { const LAS unsigned char* p = vb + (16 * q) * VP + 64 * e;
;         lo[q] = __builtin_bit_cast(s16x4, __builtin_amdgcn_ds_read_tr16_b64_v4i16((LAS s16x4*)p));
;         hi[q] = __builtin_bit_cast(s16x4, __builtin_amdgcn_ds_read_tr16_b64_v4i16((LAS s16x4*)(p + 8 * VP))); }
; }
; template <int NMAP>
; DI void att_pvmm(const s16x4 (&lo)[4], const s16x4 (&hi)[4], const bf16x8 (&pk)[NMAP][2][2], f32x16 (&o)[NMAP][2], int e) {
;     __builtin_amdgcn_s_setprio(1);
; #pragma unroll
;     for (int q = 0; q < 4; ++q) { const bf16x8 vf = (bf16x8){lo[q][0], lo[q][1], lo[q][2], lo[q][3], hi[q][0], hi[q][1], hi[q][2], hi[q][3]};
; #pragma unroll
	v_cvt_pk_bf16_f32 v116, v136, v137
	v_cvt_pk_bf16_f32 v117, v248, v249
	v_cvt_pk_bf16_f32 v118, v140, v141
	v_cvt_pk_bf16_f32 v119, v250, v251
	v_add_f32_e64 v14, v80, -v210
	v_add_f32_e64 v15, v81, -v210
	v_add_f32_e64 v80, v96, -v210
	v_add_f32_e64 v81, v97, -v210
	v_exp_f32_e32 v14, v14
	v_exp_f32_e32 v15, v15
	v_exp_f32_e32 v96, v80
	v_exp_f32_e32 v97, v81
	v_pk_add_f32 v[82:83], v[82:83], v[210:211] op_sel_hi:[1,0] neg_lo:[0,1] neg_hi:[0,1]
	v_pk_add_f32 v[98:99], v[98:99], v[210:211] op_sel_hi:[1,0] neg_lo:[0,1] neg_hi:[0,1]
	v_exp_f32_e32 v82, v82
	v_exp_f32_e32 v83, v83
	v_exp_f32_e32 v98, v98
	v_exp_f32_e32 v99, v99
	v_pk_add_f32 v[84:85], v[84:85], v[210:211] op_sel_hi:[1,0] neg_lo:[0,1] neg_hi:[0,1]
	v_pk_add_f32 v[80:81], v[14:15], 0 op_sel_hi:[1,0]
	v_pk_add_f32 v[100:101], v[100:101], v[210:211] op_sel_hi:[1,0] neg_lo:[0,1] neg_hi:[0,1]
	v_exp_f32_e32 v84, v84
	v_exp_f32_e32 v85, v85
	v_pk_add_f32 v[80:81], v[96:97], v[80:81]
	v_exp_f32_e32 v100, v100
	v_exp_f32_e32 v101, v101
	v_pk_add_f32 v[86:87], v[86:87], v[210:211] op_sel_hi:[1,0] neg_lo:[0,1] neg_hi:[0,1]
	v_pk_add_f32 v[80:81], v[82:83], v[80:81]
	v_pk_add_f32 v[102:103], v[102:103], v[210:211] op_sel_hi:[1,0] neg_lo:[0,1] neg_hi:[0,1]
	v_exp_f32_e32 v86, v86
	v_exp_f32_e32 v87, v87
	v_pk_add_f32 v[80:81], v[98:99], v[80:81]
	v_exp_f32_e32 v102, v102
	v_exp_f32_e32 v103, v103
	v_pk_add_f32 v[88:89], v[88:89], v[210:211] op_sel_hi:[1,0] neg_lo:[0,1] neg_hi:[0,1]
	v_pk_add_f32 v[80:81], v[84:85], v[80:81]
	v_pk_add_f32 v[104:105], v[104:105], v[210:211] op_sel_hi:[1,0] neg_lo:[0,1] neg_hi:[0,1]
	v_exp_f32_e32 v88, v88
	v_exp_f32_e32 v89, v89
	v_pk_add_f32 v[80:81], v[100:101], v[80:81]
	v_exp_f32_e32 v104, v104
	v_exp_f32_e32 v105, v105
	v_pk_add_f32 v[80:81], v[86:87], v[80:81]
	s_nop 0
	v_pk_add_f32 v[80:81], v[102:103], v[80:81]
	s_nop 0
	v_pk_add_f32 v[80:81], v[88:89], v[80:81]
	s_nop 0
	v_pk_add_f32 v[80:81], v[104:105], v[80:81]
	v_add_f32_e64 v90, v90, -v210
	v_add_f32_e64 v91, v91, -v210
	v_add_f32_e64 v106, v106, -v210
	v_add_f32_e64 v107, v107, -v210
	v_exp_f32_e32 v90, v90
	v_exp_f32_e32 v91, v91
	v_exp_f32_e32 v106, v106
	v_exp_f32_e32 v107, v107
	v_pk_add_f32 v[92:93], v[92:93], v[210:211] op_sel_hi:[1,0] neg_lo:[0,1] neg_hi:[0,1]
	v_pk_add_f32 v[108:109], v[108:109], v[210:211] op_sel_hi:[1,0] neg_lo:[0,1] neg_hi:[0,1]
	v_exp_f32_e32 v92, v92
	v_exp_f32_e32 v93, v93
	v_exp_f32_e32 v108, v108
	v_exp_f32_e32 v109, v109
	v_pk_add_f32 v[94:95], v[94:95], v[210:211] op_sel_hi:[1,0] neg_lo:[0,1] neg_hi:[0,1]
	v_pk_add_f32 v[80:81], v[90:91], v[80:81]
	v_pk_add_f32 v[110:111], v[110:111], v[210:211] op_sel_hi:[1,0] neg_lo:[0,1] neg_hi:[0,1]
	v_exp_f32_e32 v94, v94
	v_exp_f32_e32 v95, v95
	v_pk_add_f32 v[80:81], v[106:107], v[80:81]
	v_exp_f32_e32 v110, v110
	v_exp_f32_e32 v111, v111
	v_pk_add_f32 v[80:81], v[92:93], v[80:81]
	s_nop 0
	v_pk_add_f32 v[80:81], v[108:109], v[80:81]
	s_nop 0
	v_pk_add_f32 v[80:81], v[94:95], v[80:81]
	s_nop 0
	v_pk_add_f32 v[80:81], v[110:111], v[80:81]
	s_nop 0
	v_add_f32_e32 v80, v80, v81
	v_cmp_nge_f32_e32 vcc, 0x43800000, v231
	s_mov_b64 s[4:5], vcc
	v_cmp_nge_f32_e32 vcc, 0x43800000, v80
	s_or_b64 vcc, vcc, s[4:5]
	s_cbranch_vccnz .LB_slow0
	v_add_f32_e32 v245, v245, v231
	v_add_f32_e32 v236, v236, v80
	s_waitcnt lgkmcnt(6)
	v_mfma_f32_32x32x16_bf16 v[64:79], v[188:191], v[120:123], v[64:79]
	s_waitcnt lgkmcnt(4)
	v_mfma_f32_32x32x16_bf16 v[64:79], v[184:187], v[124:127], v[64:79]
	v_cvt_pk_bf16_f32 v80, v14, v15
	v_cvt_pk_bf16_f32 v81, v82, v83
	v_cvt_pk_bf16_f32 v82, v84, v85
	v_cvt_pk_bf16_f32 v83, v86, v87
	v_cvt_pk_bf16_f32 v84, v96, v97
	v_cvt_pk_bf16_f32 v85, v98, v99
	s_waitcnt lgkmcnt(2)
	v_mfma_f32_32x32x16_bf16 v[64:79], v[180:183], v[112:115], v[64:79]
	v_cvt_pk_bf16_f32 v86, v100, v101
	v_cvt_pk_bf16_f32 v87, v102, v103
	v_cvt_pk_bf16_f32 v88, v88, v89
	v_cvt_pk_bf16_f32 v89, v90, v91
	v_cvt_pk_bf16_f32 v90, v92, v93
	v_cvt_pk_bf16_f32 v91, v94, v95
	v_cvt_pk_bf16_f32 v92, v104, v105
	v_cvt_pk_bf16_f32 v93, v106, v107
	v_cvt_pk_bf16_f32 v94, v108, v109
	v_cvt_pk_bf16_f32 v95, v110, v111
	s_waitcnt lgkmcnt(0)
	v_mfma_f32_32x32x16_bf16 v[64:79], v[10:13], v[116:119], v[64:79]
	v_mfma_f32_32x32x16_bf16 v[48:63], v[188:191], v[80:83], v[48:63]
	v_mfma_f32_32x32x16_bf16 v[48:63], v[184:187], v[88:91], v[48:63]
	v_mfma_f32_32x32x16_bf16 v[48:63], v[180:183], v[84:87], v[48:63]
	v_mfma_f32_32x32x16_bf16 v[48:63], v[10:13], v[92:95], v[48:63]
	ds_read_b64_tr_b16 v[10:11], v0 offset:18496
	ds_read_b64_tr_b16 v[12:13], v0 offset:19648
	ds_read_b64_tr_b16 v[96:97], v0 offset:20800
	ds_read_b64_tr_b16 v[98:99], v0 offset:21952
	ds_read_b64_tr_b16 v[100:101], v0 offset:23104
	ds_read_b64_tr_b16 v[102:103], v0 offset:24256
	ds_read_b64_tr_b16 v[104:105], v0 offset:25408
	ds_read_b64_tr_b16 v[106:107], v0 offset:26560
	s_setprio 1
	s_waitcnt lgkmcnt(6)
	v_mfma_f32_32x32x16_bf16 v[32:47], v[10:13], v[120:123], v[32:47]
	v_mfma_f32_32x32x16_bf16 v[16:31], v[10:13], v[80:83], v[16:31]
	s_waitcnt lgkmcnt(4)
	v_mfma_f32_32x32x16_bf16 v[32:47], v[96:99], v[124:127], v[32:47]
	v_mfma_f32_32x32x16_bf16 v[16:31], v[96:99], v[88:91], v[16:31]
	s_waitcnt lgkmcnt(2)
	v_mfma_f32_32x32x16_bf16 v[32:47], v[100:103], v[112:115], v[32:47]
	v_mfma_f32_32x32x16_bf16 v[16:31], v[100:103], v[84:87], v[16:31]
	s_waitcnt lgkmcnt(0)
	v_mfma_f32_32x32x16_bf16 v[32:47], v[104:107], v[116:119], v[32:47]
	v_mfma_f32_32x32x16_bf16 v[16:31], v[104:107], v[92:95], v[16:31]
	s_setprio 0
; #define LAS __attribute__((address_space(3)))
; template <int DQK, int NMAP>
; DI void att_qk(const LAS unsigned char* Kb, int r, int h, const bf16x8 (&qfm)[DQK / NMAP / 16], int mp, f32x16 (&S)[2]) {
;     constexpr int DQM = DQK / NMAP, NKS = DQM / 16, KP = DQK * 2 + 16, CH = (NKS > 4) ? 3 : NKS;
;     const LAS unsigned char* kp = Kb + r * KP + (mp * DQM + 8 * h) * 2;
;     const f32x16 z = {0.f, 0.f, 0.f, 0.f, 0.f, 0.f, 0.f, 0.f, 0.f, 0.f, 0.f, 0.f, 0.f, 0.f, 0.f, 0.f};
; #pragma unroll
;     for (int c = 0; c < NKS / CH; ++c) {
;         bf16x8 kf[2 * CH];
; #pragma unroll
;         for (int s = 0; s < CH; ++s) { kf[2 * s] = *(const LAS bf16x8*)(kp + 32 * (c * CH + s)); kf[2 * s + 1] = *(const LAS bf16x8*)(kp + 32 * KP + 32 * (c * CH + s)); }
;         __builtin_amdgcn_sched_barrier(0);
;         __builtin_amdgcn_s_setprio(1);
; #pragma unroll
;         for (int s = 0; s < CH; ++s) {
;             if (c == 0 && s == 0) { S[0] = __builtin_amdgcn_mfma_f32_32x32x16_bf16(kf[0], qfm[0], z, 0, 0, 0); S[1] = __builtin_amdgcn_mfma_f32_32x32x16_bf16(kf[1], qfm[0], z, 0, 0, 0); }
;             else { S[0] = __builtin_amdgcn_mfma_f32_32x32x16_bf16(kf[2 * s], qfm[c * CH + s], S[0], 0, 0, 0); S[1] = __builtin_amdgcn_mfma_f32_32x32x16_bf16(kf[2 * s + 1], qfm[c * CH + s], S[1], 0, 0, 0); }
;         }
;         __builtin_amdgcn_s_setprio(0);
;         __builtin_amdgcn_sched_barrier(0);
;     }
.LBB0_580:
	s_add_i32 s14, s12, 1
	s_bitcmp1_b32 s14, 0
	s_cselect_b32 s3, 0x2400, 0
	s_add_i32 s3, s3, 0
	s_add_i32 s4, s12, 4
	s_cmp_lt_u32 s12, s76
	s_cselect_b32 s4, s4, s8
	s_lshl_b32 s5, s4, 6
	s_add_i32 s5, s5, s0
	s_cmp_lt_u32 s4, 4
	s_cselect_b32 s4, s1, s5
	s_ashr_i32 s5, s4, 31
	v_lshl_add_u64 v[10:11], s[4:5], 0, v[200:201]
	v_lshlrev_b64 v[10:11], 9, v[10:11]
	v_add3_u32 v0, s3, v239, v240
	v_lshl_add_u64 v[10:11], v[206:207], 0, v[10:11]
	s_waitcnt vmcnt(5)
	ds_write_b128 v0, v[148:151]
	s_waitcnt vmcnt(4)
	ds_write_b128 v242, v[152:155] offset:27648
	s_waitcnt lgkmcnt(0)
	s_barrier
	global_load_dwordx4 v[148:151], v[10:11], off
	v_lshl_add_u64 v[10:11], s[4:5], 0, v[202:203]
	v_mad_u64_u32 v[12:13], s[4:5], v10, s78, v[208:209]
	v_mad_i32_i24 v13, v11, s78, v13
	global_load_dwordx4 v[152:155], v[12:13], off
	s_cmp_ge_u32 s14, s9
	s_cbranch_scc1 .LBB0_586
	v_add_u32_e32 v0, s3, v243
	v_add_u32_e32 v0, v0, v204
	ds_read_b128 v[10:13], v0
	ds_read_b128 v[80:83], v0 offset:32
	ds_read_b128 v[84:87], v0 offset:4608
	ds_read_b128 v[88:91], v0 offset:4640
	s_setprio 1
	s_waitcnt lgkmcnt(3)
	v_mfma_f32_32x32x16_bf16 v[112:127], v[10:13], v[156:159], 0
	s_waitcnt lgkmcnt(1)
	v_mfma_f32_32x32x16_bf16 v[128:143], v[84:87], v[156:159], 0
	v_mfma_f32_32x32x16_bf16 v[112:127], v[80:83], v[160:163], v[112:127]
	s_waitcnt lgkmcnt(0)
	v_mfma_f32_32x32x16_bf16 v[128:143], v[88:91], v[160:163], v[128:143]
	s_setprio 0
	ds_read_b128 v[10:13], v0 offset:64
	ds_read_b128 v[180:183], v0 offset:96
	ds_read_b128 v[96:99], v0 offset:4672
	ds_read_b128 v[184:187], v0 offset:4704
	s_setprio 1
	s_waitcnt lgkmcnt(3)
	v_mfma_f32_32x32x16_bf16 v[80:95], v[10:13], v[164:167], 0
	s_waitcnt lgkmcnt(1)
	v_mfma_f32_32x32x16_bf16 v[96:111], v[96:99], v[164:167], 0
	v_mfma_f32_32x32x16_bf16 v[80:95], v[180:183], v[168:171], v[80:95]
	s_waitcnt lgkmcnt(0)
	v_mfma_f32_32x32x16_bf16 v[96:111], v[184:187], v[168:171], v[96:111]
	s_setprio 0
	v_add_u32_e32 v0, v238, v237
	ds_read_b64_tr_b16 v[190:191], v0 offset:28800
	ds_read_b64_tr_b16 v[180:181], v0 offset:29952
	ds_read_b64_tr_b16 v[182:183], v0 offset:31104
	ds_read_b64_tr_b16 v[10:11], v0 offset:32256
	ds_read_b64_tr_b16 v[188:189], v0 offset:27648
	ds_read_b64_tr_b16 v[12:13], v0 offset:33408
	ds_read_b64_tr_b16 v[184:185], v0 offset:34560
	ds_read_b64_tr_b16 v[186:187], v0 offset:35712
	s_nop 1
	v_pk_add_f32 v[14:15], v[112:113], v[212:213] op_sel_hi:[1,0] neg_lo:[0,1] neg_hi:[0,1]
	v_pk_add_f32 v[112:113], v[128:129], v[212:213] op_sel_hi:[1,0] neg_lo:[0,1] neg_hi:[0,1]
	v_exp_f32_e32 v14, v14
	v_exp_f32_e32 v15, v15
	v_exp_f32_e32 v112, v112
	v_exp_f32_e32 v113, v113
	v_pk_add_f32 v[114:115], v[114:115], v[212:213] op_sel_hi:[1,0] neg_lo:[0,1] neg_hi:[0,1]
	v_pk_add_f32 v[128:129], v[130:131], v[212:213] op_sel_hi:[1,0] neg_lo:[0,1] neg_hi:[0,1]
	v_exp_f32_e32 v114, v114
	v_exp_f32_e32 v115, v115
	v_exp_f32_e32 v128, v128
	v_exp_f32_e32 v129, v129
	v_pk_add_f32 v[116:117], v[116:117], v[212:213] op_sel_hi:[1,0] neg_lo:[0,1] neg_hi:[0,1]
	v_pk_add_f32 v[130:131], v[14:15], 0 op_sel_hi:[1,0]
	v_pk_add_f32 v[132:133], v[132:133], v[212:213] op_sel_hi:[1,0] neg_lo:[0,1] neg_hi:[0,1]
	v_exp_f32_e32 v116, v116
	v_exp_f32_e32 v117, v117
	v_pk_add_f32 v[130:131], v[112:113], v[130:131]
	v_exp_f32_e32 v132, v132
	v_exp_f32_e32 v133, v133
	v_pk_add_f32 v[118:119], v[118:119], v[212:213] op_sel_hi:[1,0] neg_lo:[0,1] neg_hi:[0,1]
	v_pk_add_f32 v[130:131], v[114:115], v[130:131]
	v_pk_add_f32 v[134:135], v[134:135], v[212:213] op_sel_hi:[1,0] neg_lo:[0,1] neg_hi:[0,1]
	v_exp_f32_e32 v118, v118
	v_exp_f32_e32 v119, v119
	v_pk_add_f32 v[130:131], v[128:129], v[130:131]
	v_exp_f32_e32 v134, v134
	v_exp_f32_e32 v135, v135
	v_pk_add_f32 v[120:121], v[120:121], v[212:213] op_sel_hi:[1,0] neg_lo:[0,1] neg_hi:[0,1]
	v_pk_add_f32 v[130:131], v[116:117], v[130:131]
	v_pk_add_f32 v[136:137], v[136:137], v[212:213] op_sel_hi:[1,0] neg_lo:[0,1] neg_hi:[0,1]
	v_exp_f32_e32 v246, v120
	v_exp_f32_e32 v247, v121
	v_pk_add_f32 v[130:131], v[132:133], v[130:131]
	v_exp_f32_e32 v136, v136
	v_exp_f32_e32 v137, v137
	v_pk_add_f32 v[120:121], v[122:123], v[212:213] op_sel_hi:[1,0] neg_lo:[0,1] neg_hi:[0,1]
	v_pk_add_f32 v[130:131], v[118:119], v[130:131]
	v_pk_add_f32 v[122:123], v[138:139], v[212:213] op_sel_hi:[1,0] neg_lo:[0,1] neg_hi:[0,1]
	v_exp_f32_e32 v138, v120
	v_exp_f32_e32 v139, v121
	v_pk_add_f32 v[130:131], v[134:135], v[130:131]
	v_exp_f32_e32 v248, v122
	v_exp_f32_e32 v249, v123
	v_pk_add_f32 v[122:123], v[124:125], v[212:213] op_sel_hi:[1,0] neg_lo:[0,1] neg_hi:[0,1]
	v_pk_add_f32 v[120:121], v[246:247], v[130:131]
	v_pk_add_f32 v[124:125], v[140:141], v[212:213] op_sel_hi:[1,0] neg_lo:[0,1] neg_hi:[0,1]
	v_exp_f32_e32 v130, v122
	v_exp_f32_e32 v131, v123
	v_pk_add_f32 v[120:121], v[136:137], v[120:121]
	v_exp_f32_e32 v140, v124
	v_exp_f32_e32 v141, v125
	v_pk_add_f32 v[122:123], v[126:127], v[212:213] op_sel_hi:[1,0] neg_lo:[0,1] neg_hi:[0,1]
	v_pk_add_f32 v[120:121], v[138:139], v[120:121]
	v_pk_add_f32 v[124:125], v[142:143], v[212:213] op_sel_hi:[1,0] neg_lo:[0,1] neg_hi:[0,1]
	v_exp_f32_e32 v142, v122
	v_exp_f32_e32 v143, v123
	v_pk_add_f32 v[120:121], v[248:249], v[120:121]
	v_exp_f32_e32 v250, v124
	v_exp_f32_e32 v251, v125
	v_pk_add_f32 v[120:121], v[130:131], v[120:121]
	v_cvt_pk_bf16_f32 v122, v116, v117
	v_pk_add_f32 v[120:121], v[140:141], v[120:121]
	v_cvt_pk_bf16_f32 v123, v118, v119
	v_pk_add_f32 v[120:121], v[142:143], v[120:121]
	v_cvt_pk_bf16_f32 v112, v112, v113
	v_pk_add_f32 v[120:121], v[250:251], v[120:121]
	v_cvt_pk_bf16_f32 v113, v128, v129
	v_add_f32_e32 v120, v120, v121
	v_mov_b32_e32 v231, v120
; DI void att_sm_tail(f32x16 (&S)[2], bf16x8 (&pkm)[2][2], const float mrefm, float& lrunm) {
;     {
;         f32x16& s0 = S[0]; f32x16& s1 = S[1];
;         const f32x2 nm2 = {-mrefm, -mrefm};
;         f32x2 acc2 = {0.f, 0.f};
; #pragma unroll
;         for (int i = 0; i < 16; i += 2) {
;             f32x2 a = {s0[i], s0[i + 1]}, b = {s1[i], s1[i + 1]}; a += nm2; b += nm2;
;             a.x = fast_exp2(a.x); a.y = fast_exp2(a.y); b.x = fast_exp2(b.x); b.y = fast_exp2(b.y);
;             acc2 += a; acc2 += b; s0[i] = a.x; s0[i + 1] = a.y; s1[i] = b.x; s1[i + 1] = b.y;
;         }
;         lrunm += acc2.x + acc2.y;
; #pragma unroll
;         for (int s = 0; s < 2; ++s) {
;             u32x4 w0, w1;
;             w0.x = pk2(s0[8 * s + 0], s0[8 * s + 1]); w0.y = pk2(s0[8 * s + 2], s0[8 * s + 3]); w0.z = pk2(s0[8 * s + 4], s0[8 * s + 5]); w0.w = pk2(s0[8 * s + 6], s0[8 * s + 7]);
;             w1.x = pk2(s1[8 * s + 0], s1[8 * s + 1]); w1.y = pk2(s1[8 * s + 2], s1[8 * s + 3]); w1.z = pk2(s1[8 * s + 4], s1[8 * s + 5]); w1.w = pk2(s1[8 * s + 6], s1[8 * s + 7]);
;             pkm[0][s] = __builtin_bit_cast(bf16x8, w0); pkm[1][s] = __builtin_bit_cast(bf16x8, w1);
;         }
;     }
; }
; DI void att_pvmm1(const s16x4 (&lo)[4], const s16x4 (&hi)[4], const bf16x8 (&pkm)[2][2], f32x16& oe) {
; #pragma unroll
;     for (int q = 0; q < 4; ++q) { const bf16x8 vf = (bf16x8){lo[q][0], lo[q][1], lo[q][2], lo[q][3], hi[q][0], hi[q][1], hi[q][2], hi[q][3]};
;         oe = __builtin_amdgcn_mfma_f32_32x32x16_bf16(vf, pkm[q >> 1][q & 1], oe, 0, 0, 0); }
; }
; DI void att_vload(const LAS unsigned char* vb, int e, s16x4 (&lo)[4], s16x4 (&hi)[4]) {
;     constexpr int VP = 144;
; #pragma unroll
;     for (int q = 0; q < 4; ++q) { const LAS unsigned char* p = vb + (16 * q) * VP + 64 * e;
;         lo[q] = __builtin_bit_cast(s16x4, __builtin_amdgcn_ds_read_tr16_b64_v4i16((LAS s16x4*)p));
;         hi[q] = __builtin_bit_cast(s16x4, __builtin_amdgcn_ds_read_tr16_b64_v4i16((LAS s16x4*)(p + 8 * VP))); }
; }
; template <int NMAP>
; DI void att_pvmm(const s16x4 (&lo)[4], const s16x4 (&hi)[4], const bf16x8 (&pk)[NMAP][2][2], f32x16 (&o)[NMAP][2], int e) {
;     __builtin_amdgcn_s_setprio(1);
; #pragma unroll
;     for (int q = 0; q < 4; ++q) { const bf16x8 vf = (bf16x8){lo[q][0], lo[q][1], lo[q][2], lo[q][3], hi[q][0], hi[q][1], hi[q][2], hi[q][3]};
; #pragma unroll
	v_cvt_pk_bf16_f32 v120, v14, v15
	v_cvt_pk_bf16_f32 v121, v114, v115
	v_cvt_pk_bf16_f32 v114, v132, v133
	v_cvt_pk_bf16_f32 v115, v134, v135
	v_cvt_pk_bf16_f32 v124, v246, v247
	v_cvt_pk_bf16_f32 v125, v138, v139
	v_cvt_pk_bf16_f32 v126, v130, v131
	v_cvt_pk_bf16_f32 v127, v142, v143
	v_cvt_pk_bf16_f32 v116, v136, v137
	v_cvt_pk_bf16_f32 v117, v248, v249
	v_cvt_pk_bf16_f32 v118, v140, v141
	v_cvt_pk_bf16_f32 v119, v250, v251
	v_add_f32_e64 v14, v80, -v210
	v_add_f32_e64 v15, v81, -v210
	v_add_f32_e64 v80, v96, -v210
	v_add_f32_e64 v81, v97, -v210
	v_exp_f32_e32 v14, v14
	v_exp_f32_e32 v15, v15
	v_exp_f32_e32 v96, v80
	v_exp_f32_e32 v97, v81
	v_pk_add_f32 v[82:83], v[82:83], v[210:211] op_sel_hi:[1,0] neg_lo:[0,1] neg_hi:[0,1]
	v_pk_add_f32 v[98:99], v[98:99], v[210:211] op_sel_hi:[1,0] neg_lo:[0,1] neg_hi:[0,1]
	v_exp_f32_e32 v82, v82
	v_exp_f32_e32 v83, v83
	v_exp_f32_e32 v98, v98
	v_exp_f32_e32 v99, v99
	v_pk_add_f32 v[84:85], v[84:85], v[210:211] op_sel_hi:[1,0] neg_lo:[0,1] neg_hi:[0,1]
	v_pk_add_f32 v[80:81], v[14:15], 0 op_sel_hi:[1,0]
	v_pk_add_f32 v[100:101], v[100:101], v[210:211] op_sel_hi:[1,0] neg_lo:[0,1] neg_hi:[0,1]
	v_exp_f32_e32 v84, v84
	v_exp_f32_e32 v85, v85
	v_pk_add_f32 v[80:81], v[96:97], v[80:81]
	v_exp_f32_e32 v100, v100
	v_exp_f32_e32 v101, v101
	v_pk_add_f32 v[86:87], v[86:87], v[210:211] op_sel_hi:[1,0] neg_lo:[0,1] neg_hi:[0,1]
	v_pk_add_f32 v[80:81], v[82:83], v[80:81]
	v_pk_add_f32 v[102:103], v[102:103], v[210:211] op_sel_hi:[1,0] neg_lo:[0,1] neg_hi:[0,1]
	v_exp_f32_e32 v86, v86
	v_exp_f32_e32 v87, v87
	v_pk_add_f32 v[80:81], v[98:99], v[80:81]
	v_exp_f32_e32 v102, v102
	v_exp_f32_e32 v103, v103
	v_pk_add_f32 v[88:89], v[88:89], v[210:211] op_sel_hi:[1,0] neg_lo:[0,1] neg_hi:[0,1]
	v_pk_add_f32 v[80:81], v[84:85], v[80:81]
	v_pk_add_f32 v[104:105], v[104:105], v[210:211] op_sel_hi:[1,0] neg_lo:[0,1] neg_hi:[0,1]
	v_exp_f32_e32 v88, v88
	v_exp_f32_e32 v89, v89
	v_pk_add_f32 v[80:81], v[100:101], v[80:81]
	v_exp_f32_e32 v104, v104
	v_exp_f32_e32 v105, v105
	v_pk_add_f32 v[80:81], v[86:87], v[80:81]
	s_nop 0
	v_pk_add_f32 v[80:81], v[102:103], v[80:81]
	s_nop 0
	v_pk_add_f32 v[80:81], v[88:89], v[80:81]
	s_nop 0
	v_pk_add_f32 v[80:81], v[104:105], v[80:81]
	v_add_f32_e64 v90, v90, -v210
	v_add_f32_e64 v91, v91, -v210
	v_add_f32_e64 v106, v106, -v210
	v_add_f32_e64 v107, v107, -v210
	v_exp_f32_e32 v90, v90
	v_exp_f32_e32 v91, v91
	v_exp_f32_e32 v106, v106
	v_exp_f32_e32 v107, v107
	v_pk_add_f32 v[92:93], v[92:93], v[210:211] op_sel_hi:[1,0] neg_lo:[0,1] neg_hi:[0,1]
	v_pk_add_f32 v[108:109], v[108:109], v[210:211] op_sel_hi:[1,0] neg_lo:[0,1] neg_hi:[0,1]
	v_exp_f32_e32 v92, v92
	v_exp_f32_e32 v93, v93
	v_exp_f32_e32 v108, v108
	v_exp_f32_e32 v109, v109
	v_pk_add_f32 v[94:95], v[94:95], v[210:211] op_sel_hi:[1,0] neg_lo:[0,1] neg_hi:[0,1]
	v_pk_add_f32 v[80:81], v[90:91], v[80:81]
	v_pk_add_f32 v[110:111], v[110:111], v[210:211] op_sel_hi:[1,0] neg_lo:[0,1] neg_hi:[0,1]
	v_exp_f32_e32 v94, v94
	v_exp_f32_e32 v95, v95
	v_pk_add_f32 v[80:81], v[106:107], v[80:81]
	v_exp_f32_e32 v110, v110
	v_exp_f32_e32 v111, v111
	v_pk_add_f32 v[80:81], v[92:93], v[80:81]
	s_nop 0
	v_pk_add_f32 v[80:81], v[108:109], v[80:81]
	s_nop 0
	v_pk_add_f32 v[80:81], v[94:95], v[80:81]
	s_nop 0
	v_pk_add_f32 v[80:81], v[110:111], v[80:81]
	s_nop 0
	v_add_f32_e32 v80, v80, v81
	v_cmp_nge_f32_e32 vcc, 0x43800000, v231
	s_mov_b64 s[4:5], vcc
	v_cmp_nge_f32_e32 vcc, 0x43800000, v80
	s_or_b64 vcc, vcc, s[4:5]
	s_cbranch_vccnz .LB_slow1
	v_add_f32_e32 v245, v245, v231
	v_add_f32_e32 v236, v236, v80
	s_waitcnt lgkmcnt(3)
	v_mfma_f32_32x32x16_bf16 v[64:79], v[188:191], v[120:123], v[64:79]
	v_mfma_f32_32x32x16_bf16 v[64:79], v[180:183], v[124:127], v[64:79]
	v_cvt_pk_bf16_f32 v80, v14, v15
	v_cvt_pk_bf16_f32 v81, v82, v83
	v_cvt_pk_bf16_f32 v82, v84, v85
	v_cvt_pk_bf16_f32 v83, v86, v87
	v_cvt_pk_bf16_f32 v84, v96, v97
	v_cvt_pk_bf16_f32 v85, v98, v99
	s_waitcnt lgkmcnt(2)
	v_mfma_f32_32x32x16_bf16 v[64:79], v[10:13], v[112:115], v[64:79]
	v_cvt_pk_bf16_f32 v86, v100, v101
	v_cvt_pk_bf16_f32 v87, v102, v103
	v_cvt_pk_bf16_f32 v88, v88, v89
	v_cvt_pk_bf16_f32 v89, v90, v91
	v_cvt_pk_bf16_f32 v90, v92, v93
	v_cvt_pk_bf16_f32 v91, v94, v95
	v_cvt_pk_bf16_f32 v92, v104, v105
	v_cvt_pk_bf16_f32 v93, v106, v107
	v_cvt_pk_bf16_f32 v94, v108, v109
	v_cvt_pk_bf16_f32 v95, v110, v111
	s_waitcnt lgkmcnt(0)
	v_mfma_f32_32x32x16_bf16 v[64:79], v[184:187], v[116:119], v[64:79]
	v_mfma_f32_32x32x16_bf16 v[48:63], v[188:191], v[80:83], v[48:63]
	v_mfma_f32_32x32x16_bf16 v[48:63], v[180:183], v[88:91], v[48:63]
	v_mfma_f32_32x32x16_bf16 v[48:63], v[10:13], v[84:87], v[48:63]
	v_mfma_f32_32x32x16_bf16 v[48:63], v[184:187], v[92:95], v[48:63]
	ds_read_b64_tr_b16 v[12:13], v0 offset:28864
	ds_read_b64_tr_b16 v[96:97], v0 offset:30016
	ds_read_b64_tr_b16 v[98:99], v0 offset:31168
	ds_read_b64_tr_b16 v[100:101], v0 offset:32320
	ds_read_b64_tr_b16 v[10:11], v0 offset:27712
	ds_read_b64_tr_b16 v[102:103], v0 offset:33472
	ds_read_b64_tr_b16 v[104:105], v0 offset:34624
	ds_read_b64_tr_b16 v[106:107], v0 offset:35776
	s_setprio 1
	s_waitcnt lgkmcnt(3)
	v_mfma_f32_32x32x16_bf16 v[32:47], v[10:13], v[120:123], v[32:47]
	v_mfma_f32_32x32x16_bf16 v[16:31], v[10:13], v[80:83], v[16:31]
	v_mfma_f32_32x32x16_bf16 v[32:47], v[96:99], v[124:127], v[32:47]
	v_mfma_f32_32x32x16_bf16 v[16:31], v[96:99], v[88:91], v[16:31]
	s_waitcnt lgkmcnt(2)
	v_mfma_f32_32x32x16_bf16 v[32:47], v[100:103], v[112:115], v[32:47]
	v_mfma_f32_32x32x16_bf16 v[16:31], v[100:103], v[84:87], v[16:31]
	s_waitcnt lgkmcnt(0)
	v_mfma_f32_32x32x16_bf16 v[32:47], v[104:107], v[116:119], v[32:47]
	v_mfma_f32_32x32x16_bf16 v[16:31], v[104:107], v[92:95], v[16:31]
	s_setprio 0
; #define LAS __attribute__((address_space(3)))
; template <int DQK, int NMAP>
; DI void att_qk(const LAS unsigned char* Kb, int r, int h, const bf16x8 (&qfm)[DQK / NMAP / 16], int mp, f32x16 (&S)[2]) {
;     constexpr int DQM = DQK / NMAP, NKS = DQM / 16, KP = DQK * 2 + 16, CH = (NKS > 4) ? 3 : NKS;
;     const LAS unsigned char* kp = Kb + r * KP + (mp * DQM + 8 * h) * 2;
;     const f32x16 z = {0.f, 0.f, 0.f, 0.f, 0.f, 0.f, 0.f, 0.f, 0.f, 0.f, 0.f, 0.f, 0.f, 0.f, 0.f, 0.f};
; #pragma unroll
;     for (int c = 0; c < NKS / CH; ++c) {
;         bf16x8 kf[2 * CH];
; #pragma unroll
;         for (int s = 0; s < CH; ++s) { kf[2 * s] = *(const LAS bf16x8*)(kp + 32 * (c * CH + s)); kf[2 * s + 1] = *(const LAS bf16x8*)(kp + 32 * KP + 32 * (c * CH + s)); }
;         __builtin_amdgcn_sched_barrier(0);
;         __builtin_amdgcn_s_setprio(1);
; #pragma unroll
;         for (int s = 0; s < CH; ++s) {
;             if (c == 0 && s == 0) { S[0] = __builtin_amdgcn_mfma_f32_32x32x16_bf16(kf[0], qfm[0], z, 0, 0, 0); S[1] = __builtin_amdgcn_mfma_f32_32x32x16_bf16(kf[1], qfm[0], z, 0, 0, 0); }
;             else { S[0] = __builtin_amdgcn_mfma_f32_32x32x16_bf16(kf[2 * s], qfm[c * CH + s], S[0], 0, 0, 0); S[1] = __builtin_amdgcn_mfma_f32_32x32x16_bf16(kf[2 * s + 1], qfm[c * CH + s], S[1], 0, 0, 0); }
;         }
;         __builtin_amdgcn_s_setprio(0);
;         __builtin_amdgcn_sched_barrier(0);
;     }
.LBB0_586:
	s_bitcmp1_b32 s12, 0
	s_cselect_b32 s3, 0x2400, 0
	s_add_i32 s3, s3, 0
	s_add_i32 s4, s12, 5
	s_cmp_lt_u32 s4, s9
	s_cselect_b32 s4, s4, s8
	s_lshl_b32 s5, s4, 6
	s_add_i32 s5, s5, s0
	s_cmp_lt_u32 s4, 4
	s_cselect_b32 s4, s1, s5
	s_ashr_i32 s5, s4, 31
	v_lshl_add_u64 v[10:11], s[4:5], 0, v[200:201]
	v_lshlrev_b64 v[10:11], 9, v[10:11]
	v_add3_u32 v0, s3, v239, v240
	v_lshl_add_u64 v[10:11], v[206:207], 0, v[10:11]
	s_waitcnt vmcnt(5)
	ds_write_b128 v0, v[176:179]
	s_waitcnt vmcnt(4)
	ds_write_b128 v242, v[172:175] offset:36864
	s_waitcnt lgkmcnt(0)
	s_barrier
	global_load_dwordx4 v[176:179], v[10:11], off
	v_lshl_add_u64 v[10:11], s[4:5], 0, v[202:203]
	v_mad_u64_u32 v[12:13], s[4:5], v10, s78, v[208:209]
	v_mad_i32_i24 v13, v11, s78, v13
	global_load_dwordx4 v[172:175], v[12:13], off
	s_cmp_ge_u32 s12, s11
	s_cbranch_scc1 .LBB0_592
	v_add_u32_e32 v0, s3, v243
	v_add_u32_e32 v0, v0, v204
	ds_read_b128 v[10:13], v0
	ds_read_b128 v[80:83], v0 offset:32
	ds_read_b128 v[84:87], v0 offset:4608
	ds_read_b128 v[88:91], v0 offset:4640
	s_setprio 1
	s_waitcnt lgkmcnt(3)
	v_mfma_f32_32x32x16_bf16 v[112:127], v[10:13], v[156:159], 0
	s_waitcnt lgkmcnt(1)
	v_mfma_f32_32x32x16_bf16 v[128:143], v[84:87], v[156:159], 0
	v_mfma_f32_32x32x16_bf16 v[112:127], v[80:83], v[160:163], v[112:127]
	s_waitcnt lgkmcnt(0)
	v_mfma_f32_32x32x16_bf16 v[128:143], v[88:91], v[160:163], v[128:143]
	s_setprio 0
	ds_read_b128 v[10:13], v0 offset:64
	ds_read_b128 v[180:183], v0 offset:96
	ds_read_b128 v[96:99], v0 offset:4672
	ds_read_b128 v[184:187], v0 offset:4704
	s_setprio 1
	s_waitcnt lgkmcnt(3)
	v_mfma_f32_32x32x16_bf16 v[80:95], v[10:13], v[164:167], 0
	s_waitcnt lgkmcnt(1)
	v_mfma_f32_32x32x16_bf16 v[96:111], v[96:99], v[164:167], 0
	v_mfma_f32_32x32x16_bf16 v[80:95], v[180:183], v[168:171], v[80:95]
	s_waitcnt lgkmcnt(0)
	v_mfma_f32_32x32x16_bf16 v[96:111], v[184:187], v[168:171], v[96:111]
	s_setprio 0
	v_add_u32_e32 v0, v238, v237
	ds_read_b64_tr_b16 v[188:189], v0 offset:36864
	ds_read_b64_tr_b16 v[190:191], v0 offset:38016
	ds_read_b64_tr_b16 v[184:185], v0 offset:39168
	ds_read_b64_tr_b16 v[186:187], v0 offset:40320
	ds_read_b64_tr_b16 v[180:181], v0 offset:41472
	ds_read_b64_tr_b16 v[182:183], v0 offset:42624
	ds_read_b64_tr_b16 v[10:11], v0 offset:43776
	ds_read_b64_tr_b16 v[12:13], v0 offset:44928
	s_nop 1
	v_pk_add_f32 v[14:15], v[112:113], v[212:213] op_sel_hi:[1,0] neg_lo:[0,1] neg_hi:[0,1]
	v_pk_add_f32 v[112:113], v[128:129], v[212:213] op_sel_hi:[1,0] neg_lo:[0,1] neg_hi:[0,1]
	v_exp_f32_e32 v14, v14
	v_exp_f32_e32 v15, v15
	v_exp_f32_e32 v112, v112
	v_exp_f32_e32 v113, v113
	v_pk_add_f32 v[114:115], v[114:115], v[212:213] op_sel_hi:[1,0] neg_lo:[0,1] neg_hi:[0,1]
	v_pk_add_f32 v[128:129], v[130:131], v[212:213] op_sel_hi:[1,0] neg_lo:[0,1] neg_hi:[0,1]
	v_exp_f32_e32 v114, v114
	v_exp_f32_e32 v115, v115
	v_exp_f32_e32 v128, v128
	v_exp_f32_e32 v129, v129
	v_pk_add_f32 v[116:117], v[116:117], v[212:213] op_sel_hi:[1,0] neg_lo:[0,1] neg_hi:[0,1]
	v_pk_add_f32 v[130:131], v[14:15], 0 op_sel_hi:[1,0]
	v_pk_add_f32 v[132:133], v[132:133], v[212:213] op_sel_hi:[1,0] neg_lo:[0,1] neg_hi:[0,1]
	v_exp_f32_e32 v116, v116
	v_exp_f32_e32 v117, v117
	v_pk_add_f32 v[130:131], v[112:113], v[130:131]
	v_exp_f32_e32 v132, v132
	v_exp_f32_e32 v133, v133
	v_pk_add_f32 v[118:119], v[118:119], v[212:213] op_sel_hi:[1,0] neg_lo:[0,1] neg_hi:[0,1]
	v_pk_add_f32 v[130:131], v[114:115], v[130:131]
	v_pk_add_f32 v[134:135], v[134:135], v[212:213] op_sel_hi:[1,0] neg_lo:[0,1] neg_hi:[0,1]
	v_exp_f32_e32 v118, v118
	v_exp_f32_e32 v119, v119
	v_pk_add_f32 v[130:131], v[128:129], v[130:131]
	v_exp_f32_e32 v134, v134
	v_exp_f32_e32 v135, v135
	v_pk_add_f32 v[120:121], v[120:121], v[212:213] op_sel_hi:[1,0] neg_lo:[0,1] neg_hi:[0,1]
	v_pk_add_f32 v[130:131], v[116:117], v[130:131]
	v_pk_add_f32 v[136:137], v[136:137], v[212:213] op_sel_hi:[1,0] neg_lo:[0,1] neg_hi:[0,1]
	v_exp_f32_e32 v246, v120
	v_exp_f32_e32 v247, v121
	v_pk_add_f32 v[130:131], v[132:133], v[130:131]
	v_exp_f32_e32 v136, v136
	v_exp_f32_e32 v137, v137
	v_pk_add_f32 v[120:121], v[122:123], v[212:213] op_sel_hi:[1,0] neg_lo:[0,1] neg_hi:[0,1]
	v_pk_add_f32 v[130:131], v[118:119], v[130:131]
	v_pk_add_f32 v[122:123], v[138:139], v[212:213] op_sel_hi:[1,0] neg_lo:[0,1] neg_hi:[0,1]
	v_exp_f32_e32 v138, v120
	v_exp_f32_e32 v139, v121
	v_pk_add_f32 v[130:131], v[134:135], v[130:131]
	v_exp_f32_e32 v248, v122
	v_exp_f32_e32 v249, v123
	v_pk_add_f32 v[122:123], v[124:125], v[212:213] op_sel_hi:[1,0] neg_lo:[0,1] neg_hi:[0,1]
	v_pk_add_f32 v[120:121], v[246:247], v[130:131]
	v_pk_add_f32 v[124:125], v[140:141], v[212:213] op_sel_hi:[1,0] neg_lo:[0,1] neg_hi:[0,1]
	v_exp_f32_e32 v130, v122
	v_exp_f32_e32 v131, v123
	v_pk_add_f32 v[120:121], v[136:137], v[120:121]
	v_exp_f32_e32 v140, v124
	v_exp_f32_e32 v141, v125
	v_pk_add_f32 v[122:123], v[126:127], v[212:213] op_sel_hi:[1,0] neg_lo:[0,1] neg_hi:[0,1]
	v_pk_add_f32 v[120:121], v[138:139], v[120:121]
	v_pk_add_f32 v[124:125], v[142:143], v[212:213] op_sel_hi:[1,0] neg_lo:[0,1] neg_hi:[0,1]
	v_exp_f32_e32 v142, v122
	v_exp_f32_e32 v143, v123
	v_pk_add_f32 v[120:121], v[248:249], v[120:121]
	v_exp_f32_e32 v250, v124
	v_exp_f32_e32 v251, v125
	v_pk_add_f32 v[120:121], v[130:131], v[120:121]
	v_cvt_pk_bf16_f32 v122, v116, v117
	v_pk_add_f32 v[120:121], v[140:141], v[120:121]
	v_cvt_pk_bf16_f32 v123, v118, v119
	v_pk_add_f32 v[120:121], v[142:143], v[120:121]
	v_cvt_pk_bf16_f32 v112, v112, v113
	v_pk_add_f32 v[120:121], v[250:251], v[120:121]
	v_cvt_pk_bf16_f32 v113, v128, v129
	v_add_f32_e32 v120, v120, v121
	v_mov_b32_e32 v231, v120
	v_cvt_pk_bf16_f32 v120, v14, v15
; DI void att_sm_tail(f32x16 (&S)[2], bf16x8 (&pkm)[2][2], const float mrefm, float& lrunm) {
;     {
;         f32x16& s0 = S[0]; f32x16& s1 = S[1];
;         const f32x2 nm2 = {-mrefm, -mrefm};
;         f32x2 acc2 = {0.f, 0.f};
; #pragma unroll
;         for (int i = 0; i < 16; i += 2) {
;             f32x2 a = {s0[i], s0[i + 1]}, b = {s1[i], s1[i + 1]}; a += nm2; b += nm2;
;             a.x = fast_exp2(a.x); a.y = fast_exp2(a.y); b.x = fast_exp2(b.x); b.y = fast_exp2(b.y);
;             acc2 += a; acc2 += b; s0[i] = a.x; s0[i + 1] = a.y; s1[i] = b.x; s1[i + 1] = b.y;
;         }
;         lrunm += acc2.x + acc2.y;
; #pragma unroll
;         for (int s = 0; s < 2; ++s) {
;             u32x4 w0, w1;
;             w0.x = pk2(s0[8 * s + 0], s0[8 * s + 1]); w0.y = pk2(s0[8 * s + 2], s0[8 * s + 3]); w0.z = pk2(s0[8 * s + 4], s0[8 * s + 5]); w0.w = pk2(s0[8 * s + 6], s0[8 * s + 7]);
;             w1.x = pk2(s1[8 * s + 0], s1[8 * s + 1]); w1.y = pk2(s1[8 * s + 2], s1[8 * s + 3]); w1.z = pk2(s1[8 * s + 4], s1[8 * s + 5]); w1.w = pk2(s1[8 * s + 6], s1[8 * s + 7]);
;             pkm[0][s] = __builtin_bit_cast(bf16x8, w0); pkm[1][s] = __builtin_bit_cast(bf16x8, w1);
;         }
;     }
; }
; DI void att_pvmm1(const s16x4 (&lo)[4], const s16x4 (&hi)[4], const bf16x8 (&pkm)[2][2], f32x16& oe) {
; #pragma unroll
;     for (int q = 0; q < 4; ++q) { const bf16x8 vf = (bf16x8){lo[q][0], lo[q][1], lo[q][2], lo[q][3], hi[q][0], hi[q][1], hi[q][2], hi[q][3]};
;         oe = __builtin_amdgcn_mfma_f32_32x32x16_bf16(vf, pkm[q >> 1][q & 1], oe, 0, 0, 0); }
; }
; DI void att_vload(const LAS unsigned char* vb, int e, s16x4 (&lo)[4], s16x4 (&hi)[4]) {
;     constexpr int VP = 144;
; #pragma unroll
;     for (int q = 0; q < 4; ++q) { const LAS unsigned char* p = vb + (16 * q) * VP + 64 * e;
;         lo[q] = __builtin_bit_cast(s16x4, __builtin_amdgcn_ds_read_tr16_b64_v4i16((LAS s16x4*)p));
;         hi[q] = __builtin_bit_cast(s16x4, __builtin_amdgcn_ds_read_tr16_b64_v4i16((LAS s16x4*)(p + 8 * VP))); }
; }
; template <int NMAP>
; DI void att_pvmm(const s16x4 (&lo)[4], const s16x4 (&hi)[4], const bf16x8 (&pk)[NMAP][2][2], f32x16 (&o)[NMAP][2], int e) {
;     __builtin_amdgcn_s_setprio(1);
; #pragma unroll
;     for (int q = 0; q < 4; ++q) { const bf16x8 vf = (bf16x8){lo[q][0], lo[q][1], lo[q][2], lo[q][3], hi[q][0], hi[q][1], hi[q][2], hi[q][3]};
; #pragma unroll
	v_cvt_pk_bf16_f32 v121, v114, v115
	v_cvt_pk_bf16_f32 v114, v132, v133
	v_cvt_pk_bf16_f32 v115, v134, v135
	v_cvt_pk_bf16_f32 v124, v246, v247
	v_cvt_pk_bf16_f32 v125, v138, v139
	v_cvt_pk_bf16_f32 v126, v130, v131
	v_cvt_pk_bf16_f32 v127, v142, v143
	v_cvt_pk_bf16_f32 v116, v136, v137
	v_cvt_pk_bf16_f32 v117, v248, v249
	v_cvt_pk_bf16_f32 v118, v140, v141
	v_cvt_pk_bf16_f32 v119, v250, v251
	v_add_f32_e64 v14, v80, -v210
	v_add_f32_e64 v15, v81, -v210
	v_add_f32_e64 v80, v96, -v210
	v_add_f32_e64 v81, v97, -v210
	v_exp_f32_e32 v14, v14
	v_exp_f32_e32 v15, v15
	v_exp_f32_e32 v96, v80
	v_exp_f32_e32 v97, v81
	v_pk_add_f32 v[82:83], v[82:83], v[210:211] op_sel_hi:[1,0] neg_lo:[0,1] neg_hi:[0,1]
	v_pk_add_f32 v[98:99], v[98:99], v[210:211] op_sel_hi:[1,0] neg_lo:[0,1] neg_hi:[0,1]
	v_exp_f32_e32 v82, v82
	v_exp_f32_e32 v83, v83
	v_exp_f32_e32 v98, v98
	v_exp_f32_e32 v99, v99
	v_pk_add_f32 v[84:85], v[84:85], v[210:211] op_sel_hi:[1,0] neg_lo:[0,1] neg_hi:[0,1]
	v_pk_add_f32 v[80:81], v[14:15], 0 op_sel_hi:[1,0]
	v_pk_add_f32 v[100:101], v[100:101], v[210:211] op_sel_hi:[1,0] neg_lo:[0,1] neg_hi:[0,1]
	v_exp_f32_e32 v84, v84
	v_exp_f32_e32 v85, v85
	v_pk_add_f32 v[80:81], v[96:97], v[80:81]
	v_exp_f32_e32 v100, v100
	v_exp_f32_e32 v101, v101
	v_pk_add_f32 v[86:87], v[86:87], v[210:211] op_sel_hi:[1,0] neg_lo:[0,1] neg_hi:[0,1]
	v_pk_add_f32 v[80:81], v[82:83], v[80:81]
	v_pk_add_f32 v[102:103], v[102:103], v[210:211] op_sel_hi:[1,0] neg_lo:[0,1] neg_hi:[0,1]
	v_exp_f32_e32 v86, v86
	v_exp_f32_e32 v87, v87
	v_pk_add_f32 v[80:81], v[98:99], v[80:81]
	v_exp_f32_e32 v102, v102
	v_exp_f32_e32 v103, v103
	v_pk_add_f32 v[88:89], v[88:89], v[210:211] op_sel_hi:[1,0] neg_lo:[0,1] neg_hi:[0,1]
	v_pk_add_f32 v[80:81], v[84:85], v[80:81]
	v_pk_add_f32 v[104:105], v[104:105], v[210:211] op_sel_hi:[1,0] neg_lo:[0,1] neg_hi:[0,1]
	v_exp_f32_e32 v88, v88
	v_exp_f32_e32 v89, v89
	v_pk_add_f32 v[80:81], v[100:101], v[80:81]
	v_exp_f32_e32 v104, v104
	v_exp_f32_e32 v105, v105
	v_pk_add_f32 v[80:81], v[86:87], v[80:81]
	s_nop 0
	v_pk_add_f32 v[80:81], v[102:103], v[80:81]
	s_nop 0
	v_pk_add_f32 v[80:81], v[88:89], v[80:81]
	s_nop 0
	v_pk_add_f32 v[80:81], v[104:105], v[80:81]
	v_add_f32_e64 v90, v90, -v210
	v_add_f32_e64 v91, v91, -v210
	v_add_f32_e64 v106, v106, -v210
	v_add_f32_e64 v107, v107, -v210
	v_exp_f32_e32 v90, v90
	v_exp_f32_e32 v91, v91
	v_exp_f32_e32 v106, v106
	v_exp_f32_e32 v107, v107
	v_pk_add_f32 v[92:93], v[92:93], v[210:211] op_sel_hi:[1,0] neg_lo:[0,1] neg_hi:[0,1]
	v_pk_add_f32 v[108:109], v[108:109], v[210:211] op_sel_hi:[1,0] neg_lo:[0,1] neg_hi:[0,1]
	v_exp_f32_e32 v92, v92
	v_exp_f32_e32 v93, v93
	v_exp_f32_e32 v108, v108
	v_exp_f32_e32 v109, v109
	v_pk_add_f32 v[94:95], v[94:95], v[210:211] op_sel_hi:[1,0] neg_lo:[0,1] neg_hi:[0,1]
	v_pk_add_f32 v[80:81], v[90:91], v[80:81]
	v_pk_add_f32 v[110:111], v[110:111], v[210:211] op_sel_hi:[1,0] neg_lo:[0,1] neg_hi:[0,1]
	v_exp_f32_e32 v94, v94
	v_exp_f32_e32 v95, v95
	v_pk_add_f32 v[80:81], v[106:107], v[80:81]
	v_exp_f32_e32 v110, v110
	v_exp_f32_e32 v111, v111
	v_pk_add_f32 v[80:81], v[92:93], v[80:81]
	s_nop 0
	v_pk_add_f32 v[80:81], v[108:109], v[80:81]
	s_nop 0
	v_pk_add_f32 v[80:81], v[94:95], v[80:81]
	s_nop 0
	v_pk_add_f32 v[80:81], v[110:111], v[80:81]
	s_nop 0
	v_add_f32_e32 v80, v80, v81
	v_cmp_nge_f32_e32 vcc, 0x43800000, v231
	s_mov_b64 s[4:5], vcc
	v_cmp_nge_f32_e32 vcc, 0x43800000, v80
	s_or_b64 vcc, vcc, s[4:5]
	s_cbranch_vccnz .LB_slow2
	v_add_f32_e32 v245, v245, v231
	v_add_f32_e32 v236, v236, v80
	s_waitcnt lgkmcnt(6)
	v_mfma_f32_32x32x16_bf16 v[64:79], v[188:191], v[120:123], v[64:79]
	s_waitcnt lgkmcnt(4)
	v_mfma_f32_32x32x16_bf16 v[64:79], v[184:187], v[124:127], v[64:79]
	v_cvt_pk_bf16_f32 v80, v14, v15
	v_cvt_pk_bf16_f32 v81, v82, v83
	v_cvt_pk_bf16_f32 v82, v84, v85
	v_cvt_pk_bf16_f32 v83, v86, v87
	v_cvt_pk_bf16_f32 v84, v96, v97
	v_cvt_pk_bf16_f32 v85, v98, v99
	s_waitcnt lgkmcnt(2)
	v_mfma_f32_32x32x16_bf16 v[64:79], v[180:183], v[112:115], v[64:79]
	v_cvt_pk_bf16_f32 v86, v100, v101
	v_cvt_pk_bf16_f32 v87, v102, v103
	v_cvt_pk_bf16_f32 v88, v88, v89
	v_cvt_pk_bf16_f32 v89, v90, v91
	v_cvt_pk_bf16_f32 v90, v92, v93
	v_cvt_pk_bf16_f32 v91, v94, v95
	v_cvt_pk_bf16_f32 v92, v104, v105
	v_cvt_pk_bf16_f32 v93, v106, v107
	v_cvt_pk_bf16_f32 v94, v108, v109
	v_cvt_pk_bf16_f32 v95, v110, v111
	s_waitcnt lgkmcnt(0)
	v_mfma_f32_32x32x16_bf16 v[64:79], v[10:13], v[116:119], v[64:79]
	v_mfma_f32_32x32x16_bf16 v[48:63], v[188:191], v[80:83], v[48:63]
	v_mfma_f32_32x32x16_bf16 v[48:63], v[184:187], v[88:91], v[48:63]
	v_mfma_f32_32x32x16_bf16 v[48:63], v[180:183], v[84:87], v[48:63]
	v_mfma_f32_32x32x16_bf16 v[48:63], v[10:13], v[92:95], v[48:63]
	ds_read_b64_tr_b16 v[10:11], v0 offset:36928
	ds_read_b64_tr_b16 v[12:13], v0 offset:38080
	ds_read_b64_tr_b16 v[96:97], v0 offset:39232
	ds_read_b64_tr_b16 v[98:99], v0 offset:40384
	ds_read_b64_tr_b16 v[100:101], v0 offset:41536
	ds_read_b64_tr_b16 v[102:103], v0 offset:42688
	ds_read_b64_tr_b16 v[104:105], v0 offset:43840
	ds_read_b64_tr_b16 v[106:107], v0 offset:44992
	s_setprio 1
	s_waitcnt lgkmcnt(6)
	v_mfma_f32_32x32x16_bf16 v[32:47], v[10:13], v[120:123], v[32:47]
	v_mfma_f32_32x32x16_bf16 v[16:31], v[10:13], v[80:83], v[16:31]
	s_waitcnt lgkmcnt(4)
	v_mfma_f32_32x32x16_bf16 v[32:47], v[96:99], v[124:127], v[32:47]
	v_mfma_f32_32x32x16_bf16 v[16:31], v[96:99], v[88:91], v[16:31]
	s_waitcnt lgkmcnt(2)
	v_mfma_f32_32x32x16_bf16 v[32:47], v[100:103], v[112:115], v[32:47]
	v_mfma_f32_32x32x16_bf16 v[16:31], v[100:103], v[84:87], v[16:31]
	s_waitcnt lgkmcnt(0)
	v_mfma_f32_32x32x16_bf16 v[32:47], v[104:107], v[116:119], v[32:47]
	v_mfma_f32_32x32x16_bf16 v[16:31], v[104:107], v[92:95], v[16:31]
	s_setprio 0

; template <int DQK, int NMAP>
; DI void att_qk(const LAS unsigned char* Kb, int r, int h, const bf16x8 (&qfm)[DQK / NMAP / 16], int mp, f32x16 (&S)[2]) {
;     constexpr int DQM = DQK / NMAP, NKS = DQM / 16, KP = DQK * 2 + 16, CH = (NKS > 4) ? 3 : NKS;
;     const LAS unsigned char* kp = Kb + r * KP + (mp * DQM + 8 * h) * 2;
;     const f32x16 z = {0.f, 0.f, 0.f, 0.f, 0.f, 0.f, 0.f, 0.f, 0.f, 0.f, 0.f, 0.f, 0.f, 0.f, 0.f, 0.f};
; #pragma unroll
;     for (int c = 0; c < NKS / CH; ++c) {
;         bf16x8 kf[2 * CH];
; #pragma unroll
;         for (int s = 0; s < CH; ++s) { kf[2 * s] = *(const LAS bf16x8*)(kp + 32 * (c * CH + s)); kf[2 * s + 1] = *(const LAS bf16x8*)(kp + 32 * KP + 32 * (c * CH + s)); }
;         __builtin_amdgcn_sched_barrier(0);
;         __builtin_amdgcn_s_setprio(1);
; #pragma unroll
;         for (int s = 0; s < CH; ++s) {
;             if (c == 0 && s == 0) { S[0] = __builtin_amdgcn_mfma_f32_32x32x16_bf16(kf[0], qfm[0], z, 0, 0, 0); S[1] = __builtin_amdgcn_mfma_f32_32x32x16_bf16(kf[1], qfm[0], z, 0, 0, 0); }
;             else { S[0] = __builtin_amdgcn_mfma_f32_32x32x16_bf16(kf[2 * s], qfm[c * CH + s], S[0], 0, 0, 0); S[1] = __builtin_amdgcn_mfma_f32_32x32x16_bf16(kf[2 * s + 1], qfm[c * CH + s], S[1], 0, 0, 0); }
;         }
;         __builtin_amdgcn_s_setprio(0);
;         __builtin_amdgcn_sched_barrier(0);
;     }
; template <int MODE>
; DI void att_sm_head(f32x16 (&S)[2], float& mrefm, float& lrunm, f32x16 (&om)[2], bool latent, const MaskP& mk, int h) {
;     ...
;         float ma = fmaxf(fmaxf(s0[0], s0[1]), s0[2]), mb = fmaxf(fmaxf(s1[0], s1[1]), s1[2]);
; #pragma unroll
;         for (int i = 3; i < 15; i += 2) { ma = fmaxf(fmaxf(ma, s0[i]), s0[i + 1]); mb = fmaxf(fmaxf(mb, s1[i]), s1[i + 1]); }
;         ma = fmaxf(fmaxf(ma, s0[15]), fmaxf(mb, s1[15]));
;         { auto rr = __builtin_amdgcn_permlane32_swap(__float_as_uint(ma), __float_as_uint(ma), false, false); ma = fmaxf(__uint_as_float(rr[0]), __uint_as_float(rr[1])); }
;         const bool uninit = mrefm < -1e29f;
;         const bool need = uninit || (ma - mrefm > 8.0f);
;         if (__any(need)) {
;             const float mnew = need ? ma : mrefm;
;             const float f = uninit ? 1.0f : fast_exp2(mrefm - mnew);
;             mrefm = mnew; lrunm *= f;
; #pragma unroll
;             for (int e = 0; e < 2; ++e)
; #pragma unroll
.LB_slow0:
	s_bitcmp1_b32 s12, 0
	s_cselect_b32 s3, 0x2400, 0
	v_add_u32_e32 v0, s3, v244
	ds_read_b128 v[10:13], v0
	ds_read_b128 v[80:83], v0 offset:32
	ds_read_b128 v[84:87], v0 offset:4608
	ds_read_b128 v[88:91], v0 offset:4640
	s_setprio 1
	s_waitcnt lgkmcnt(3)
	v_mfma_f32_32x32x16_bf16 v[112:127], v[10:13], v[156:159], 0
	s_waitcnt lgkmcnt(1)
	v_mfma_f32_32x32x16_bf16 v[128:143], v[84:87], v[156:159], 0
	v_mfma_f32_32x32x16_bf16 v[112:127], v[80:83], v[160:163], v[112:127]
	s_waitcnt lgkmcnt(0)
	v_mfma_f32_32x32x16_bf16 v[128:143], v[88:91], v[160:163], v[128:143]
	s_setprio 0
	s_nop 10
	v_max_f32_e32 v11, v129, v129
	v_max_f32_e32 v12, v128, v128
	v_max_f32_e32 v11, v12, v11
	v_max3_f32 v10, v112, v113, v114
	v_max3_f32 v11, v11, v130, v131
	v_max3_f32 v10, v10, v115, v116
	v_max3_f32 v11, v11, v132, v133
	v_max3_f32 v10, v10, v117, v118
	v_max3_f32 v11, v11, v134, v135
	v_max3_f32 v10, v10, v119, v120
	v_max3_f32 v11, v11, v136, v137
	v_max3_f32 v10, v10, v121, v122
	v_max3_f32 v11, v11, v138, v139
	v_max3_f32 v10, v10, v123, v124
	v_max3_f32 v11, v11, v140, v141
	v_max3_f32 v10, v10, v125, v126
	v_max3_f32 v11, v11, v142, v143
	v_max3_f32 v10, v10, v127, v11
	v_mov_b32_e32 v11, v10
	s_nop 1
	v_permlane32_swap_b32_e32 v10, v11
	v_max_f32_e32 v11, v11, v11
	v_max_f32_e32 v10, v10, v10
	v_max_f32_e32 v10, v10, v11
	v_sub_f32_e32 v11, v10, v212
	v_cmp_gt_f32_e64 s[4:5], s22, v212
	v_cmp_lt_f32_e32 vcc, s23, v11
	s_or_b64 vcc, s[4:5], vcc
	s_cbranch_vccz .LB_rescA0
	v_cndmask_b32_e32 v11, v212, v10, vcc
	v_sub_f32_e32 v10, v212, v11
	v_exp_f32_e32 v10, v10
	v_mov_b32_e32 v212, v11
	v_cndmask_b32_e64 v10, v10, 1.0, s[4:5]
	v_mul_f32_e32 v245, v245, v10
	v_pk_mul_f32 v[78:79], v[78:79], v[10:11] op_sel_hi:[1,0]
	v_pk_mul_f32 v[76:77], v[76:77], v[10:11] op_sel_hi:[1,0]
	v_pk_mul_f32 v[74:75], v[74:75], v[10:11] op_sel_hi:[1,0]
	v_pk_mul_f32 v[72:73], v[72:73], v[10:11] op_sel_hi:[1,0]
	v_pk_mul_f32 v[70:71], v[70:71], v[10:11] op_sel_hi:[1,0]
	v_pk_mul_f32 v[68:69], v[68:69], v[10:11] op_sel_hi:[1,0]
	v_pk_mul_f32 v[66:67], v[66:67], v[10:11] op_sel_hi:[1,0]
	v_pk_mul_f32 v[64:65], v[64:65], v[10:11] op_sel_hi:[1,0]
	v_pk_mul_f32 v[46:47], v[46:47], v[10:11] op_sel_hi:[1,0]
	v_pk_mul_f32 v[44:45], v[44:45], v[10:11] op_sel_hi:[1,0]
	v_pk_mul_f32 v[42:43], v[42:43], v[10:11] op_sel_hi:[1,0]
	v_pk_mul_f32 v[40:41], v[40:41], v[10:11] op_sel_hi:[1,0]
	v_pk_mul_f32 v[38:39], v[38:39], v[10:11] op_sel_hi:[1,0]
	v_pk_mul_f32 v[36:37], v[36:37], v[10:11] op_sel_hi:[1,0]
	v_pk_mul_f32 v[34:35], v[34:35], v[10:11] op_sel_hi:[1,0]
	v_pk_mul_f32 v[32:33], v[32:33], v[10:11] op_sel_hi:[1,0]

; DI unsigned pk2(float lo, float hi) { f32x2 v = {lo, hi}; bf16x2_t b = __builtin_convertvector(v, bf16x2_t); return __builtin_bit_cast(unsigned, b); }
; DI float fast_exp2(float x) { return __builtin_amdgcn_exp2f(x); }
; DI void att_sm_tail(f32x16 (&S)[2], bf16x8 (&pkm)[2][2], const float mrefm, float& lrunm) {
;     {
;         f32x16& s0 = S[0]; f32x16& s1 = S[1];
;         const f32x2 nm2 = {-mrefm, -mrefm};
;         f32x2 acc2 = {0.f, 0.f};
; #pragma unroll
;         for (int i = 0; i < 16; i += 2) {
;             f32x2 a = {s0[i], s0[i + 1]}, b = {s1[i], s1[i + 1]}; a += nm2; b += nm2;
;             a.x = fast_exp2(a.x); a.y = fast_exp2(a.y); b.x = fast_exp2(b.x); b.y = fast_exp2(b.y);
;             acc2 += a; acc2 += b; s0[i] = a.x; s0[i + 1] = a.y; s1[i] = b.x; s1[i + 1] = b.y;
;         }
;         lrunm += acc2.x + acc2.y;
; #pragma unroll
;         for (int s = 0; s < 2; ++s) {
;             u32x4 w0, w1;
;             w0.x = pk2(s0[8 * s + 0], s0[8 * s + 1]); w0.y = pk2(s0[8 * s + 2], s0[8 * s + 3]); w0.z = pk2(s0[8 * s + 4], s0[8 * s + 5]); w0.w = pk2(s0[8 * s + 6], s0[8 * s + 7]);
;             w1.x = pk2(s1[8 * s + 0], s1[8 * s + 1]); w1.y = pk2(s1[8 * s + 2], s1[8 * s + 3]); w1.z = pk2(s1[8 * s + 4], s1[8 * s + 5]); w1.w = pk2(s1[8 * s + 6], s1[8 * s + 7]);
;             pkm[0][s] = __builtin_bit_cast(bf16x8, w0); pkm[1][s] = __builtin_bit_cast(bf16x8, w1);
;         }
;     }
; }
; DI void att_pvmm1(const s16x4 (&lo)[4], const s16x4 (&hi)[4], const bf16x8 (&pkm)[2][2], f32x16& oe) {
; #pragma unroll
;     for (int q = 0; q < 4; ++q) { const bf16x8 vf = (bf16x8){lo[q][0], lo[q][1], lo[q][2], lo[q][3], hi[q][0], hi[q][1], hi[q][2], hi[q][3]};
;         oe = __builtin_amdgcn_mfma_f32_32x32x16_bf16(vf, pkm[q >> 1][q & 1], oe, 0, 0, 0); }
; }
.LB_rescB0:
	v_pk_add_f32 v[14:15], v[112:113], v[212:213] op_sel_hi:[1,0] neg_lo:[0,1] neg_hi:[0,1]
	v_pk_add_f32 v[112:113], v[128:129], v[212:213] op_sel_hi:[1,0] neg_lo:[0,1] neg_hi:[0,1]
	v_exp_f32_e32 v14, v14
	v_exp_f32_e32 v15, v15
	v_exp_f32_e32 v112, v112
	v_exp_f32_e32 v113, v113
	v_pk_add_f32 v[114:115], v[114:115], v[212:213] op_sel_hi:[1,0] neg_lo:[0,1] neg_hi:[0,1]
	v_pk_add_f32 v[128:129], v[130:131], v[212:213] op_sel_hi:[1,0] neg_lo:[0,1] neg_hi:[0,1]
	v_exp_f32_e32 v114, v114
	v_exp_f32_e32 v115, v115
	v_exp_f32_e32 v128, v128
	v_exp_f32_e32 v129, v129
	v_pk_add_f32 v[116:117], v[116:117], v[212:213] op_sel_hi:[1,0] neg_lo:[0,1] neg_hi:[0,1]
	v_pk_add_f32 v[130:131], v[14:15], 0 op_sel_hi:[1,0]
	v_pk_add_f32 v[132:133], v[132:133], v[212:213] op_sel_hi:[1,0] neg_lo:[0,1] neg_hi:[0,1]
	v_exp_f32_e32 v116, v116
	v_exp_f32_e32 v117, v117
	v_pk_add_f32 v[130:131], v[112:113], v[130:131]
	v_exp_f32_e32 v132, v132
	v_exp_f32_e32 v133, v133
	v_pk_add_f32 v[118:119], v[118:119], v[212:213] op_sel_hi:[1,0] neg_lo:[0,1] neg_hi:[0,1]
	v_pk_add_f32 v[130:131], v[114:115], v[130:131]
	v_pk_add_f32 v[134:135], v[134:135], v[212:213] op_sel_hi:[1,0] neg_lo:[0,1] neg_hi:[0,1]
	v_exp_f32_e32 v118, v118
	v_exp_f32_e32 v119, v119
	v_pk_add_f32 v[130:131], v[128:129], v[130:131]
	v_exp_f32_e32 v134, v134
	v_exp_f32_e32 v135, v135
	v_pk_add_f32 v[120:121], v[120:121], v[212:213] op_sel_hi:[1,0] neg_lo:[0,1] neg_hi:[0,1]
	v_pk_add_f32 v[130:131], v[116:117], v[130:131]
	v_pk_add_f32 v[136:137], v[136:137], v[212:213] op_sel_hi:[1,0] neg_lo:[0,1] neg_hi:[0,1]
	v_exp_f32_e32 v246, v120
	v_exp_f32_e32 v247, v121
	v_pk_add_f32 v[130:131], v[132:133], v[130:131]
	v_exp_f32_e32 v136, v136
	v_exp_f32_e32 v137, v137
	v_pk_add_f32 v[120:121], v[122:123], v[212:213] op_sel_hi:[1,0] neg_lo:[0,1] neg_hi:[0,1]
	v_pk_add_f32 v[130:131], v[118:119], v[130:131]
	v_pk_add_f32 v[122:123], v[138:139], v[212:213] op_sel_hi:[1,0] neg_lo:[0,1] neg_hi:[0,1]
	v_exp_f32_e32 v138, v120
	v_exp_f32_e32 v139, v121
	v_pk_add_f32 v[130:131], v[134:135], v[130:131]
	v_exp_f32_e32 v248, v122
	v_exp_f32_e32 v249, v123
	v_pk_add_f32 v[122:123], v[124:125], v[212:213] op_sel_hi:[1,0] neg_lo:[0,1] neg_hi:[0,1]
	v_pk_add_f32 v[120:121], v[246:247], v[130:131]
	v_pk_add_f32 v[124:125], v[140:141], v[212:213] op_sel_hi:[1,0] neg_lo:[0,1] neg_hi:[0,1]
	v_exp_f32_e32 v130, v122
	v_exp_f32_e32 v131, v123
	v_pk_add_f32 v[120:121], v[136:137], v[120:121]
	v_exp_f32_e32 v140, v124
	v_exp_f32_e32 v141, v125
	v_pk_add_f32 v[122:123], v[126:127], v[212:213] op_sel_hi:[1,0] neg_lo:[0,1] neg_hi:[0,1]
	v_pk_add_f32 v[120:121], v[138:139], v[120:121]
	v_pk_add_f32 v[124:125], v[142:143], v[212:213] op_sel_hi:[1,0] neg_lo:[0,1] neg_hi:[0,1]
	v_exp_f32_e32 v142, v122
	v_exp_f32_e32 v143, v123
	v_pk_add_f32 v[120:121], v[248:249], v[120:121]
	v_exp_f32_e32 v250, v124
	v_exp_f32_e32 v251, v125
	v_pk_add_f32 v[120:121], v[130:131], v[120:121]
	v_cvt_pk_bf16_f32 v122, v116, v117
	v_pk_add_f32 v[120:121], v[140:141], v[120:121]
	v_cvt_pk_bf16_f32 v123, v118, v119
	v_pk_add_f32 v[120:121], v[142:143], v[120:121]
	v_cvt_pk_bf16_f32 v112, v112, v113
	v_pk_add_f32 v[120:121], v[250:251], v[120:121]
	v_cvt_pk_bf16_f32 v113, v128, v129
	v_add_f32_e32 v120, v120, v121
	v_add_f32_e32 v245, v245, v120
	v_cvt_pk_bf16_f32 v120, v14, v15
	v_cvt_pk_bf16_f32 v121, v114, v115
	v_cvt_pk_bf16_f32 v114, v132, v133
	v_cvt_pk_bf16_f32 v115, v134, v135
	v_cvt_pk_bf16_f32 v124, v246, v247
	v_cvt_pk_bf16_f32 v125, v138, v139
	v_cvt_pk_bf16_f32 v126, v130, v131
	v_cvt_pk_bf16_f32 v127, v142, v143
	v_cvt_pk_bf16_f32 v116, v136, v137
	v_cvt_pk_bf16_f32 v117, v248, v249
	v_cvt_pk_bf16_f32 v118, v140, v141
	v_cvt_pk_bf16_f32 v119, v250, v251
	s_waitcnt lgkmcnt(6)
	v_mfma_f32_32x32x16_bf16 v[64:79], v[188:191], v[120:123], v[64:79]
	v_add_f32_e64 v14, v80, -v210
	v_add_f32_e64 v15, v81, -v210
	v_add_f32_e64 v80, v96, -v210
	v_add_f32_e64 v81, v97, -v210
	v_exp_f32_e32 v14, v14
	v_exp_f32_e32 v15, v15
	v_exp_f32_e32 v96, v80
	v_exp_f32_e32 v97, v81
	v_pk_add_f32 v[82:83], v[82:83], v[210:211] op_sel_hi:[1,0] neg_lo:[0,1] neg_hi:[0,1]
	v_pk_add_f32 v[98:99], v[98:99], v[210:211] op_sel_hi:[1,0] neg_lo:[0,1] neg_hi:[0,1]
	v_exp_f32_e32 v82, v82
	v_exp_f32_e32 v83, v83
	v_exp_f32_e32 v98, v98
	v_exp_f32_e32 v99, v99
	v_pk_add_f32 v[84:85], v[84:85], v[210:211] op_sel_hi:[1,0] neg_lo:[0,1] neg_hi:[0,1]
	v_pk_add_f32 v[80:81], v[14:15], 0 op_sel_hi:[1,0]
	v_pk_add_f32 v[100:101], v[100:101], v[210:211] op_sel_hi:[1,0] neg_lo:[0,1] neg_hi:[0,1]
	v_exp_f32_e32 v84, v84
	v_exp_f32_e32 v85, v85
	v_pk_add_f32 v[80:81], v[96:97], v[80:81]
	v_exp_f32_e32 v100, v100
	v_exp_f32_e32 v101, v101
	v_pk_add_f32 v[86:87], v[86:87], v[210:211] op_sel_hi:[1,0] neg_lo:[0,1] neg_hi:[0,1]
	v_pk_add_f32 v[80:81], v[82:83], v[80:81]
	v_pk_add_f32 v[102:103], v[102:103], v[210:211] op_sel_hi:[1,0] neg_lo:[0,1] neg_hi:[0,1]
	v_exp_f32_e32 v86, v86
	v_exp_f32_e32 v87, v87
	v_pk_add_f32 v[80:81], v[98:99], v[80:81]
	v_exp_f32_e32 v102, v102
	v_exp_f32_e32 v103, v103
	v_pk_add_f32 v[88:89], v[88:89], v[210:211] op_sel_hi:[1,0] neg_lo:[0,1] neg_hi:[0,1]
	v_pk_add_f32 v[80:81], v[84:85], v[80:81]
	v_pk_add_f32 v[104:105], v[104:105], v[210:211] op_sel_hi:[1,0] neg_lo:[0,1] neg_hi:[0,1]
	v_exp_f32_e32 v88, v88
	v_exp_f32_e32 v89, v89
	v_pk_add_f32 v[80:81], v[100:101], v[80:81]
	v_exp_f32_e32 v104, v104
	v_exp_f32_e32 v105, v105
	v_pk_add_f32 v[80:81], v[86:87], v[80:81]
	s_nop 0
	v_pk_add_f32 v[80:81], v[102:103], v[80:81]
	s_nop 0
	v_pk_add_f32 v[80:81], v[88:89], v[80:81]
	s_nop 0
	v_pk_add_f32 v[80:81], v[104:105], v[80:81]
	s_waitcnt lgkmcnt(4)
; template <int MODE>
; DI void att_sm_head(f32x16 (&S)[2], float& mrefm, float& lrunm, f32x16 (&om)[2], bool latent, const MaskP& mk, int h) {
;     {
;         f32x16& s0 = S[0]; f32x16& s1 = S[1];
;         if (MODE == 1 && latent) {
;             const LAS float* rl = mk.rpbl + (mk.lt - mk.qrow + 7) * 31 + (15 - mk.qcol);
; #pragma unroll
;             for (int i = 0; i < 16; ++i) { const int kc = crow(i, h);
;                 { const bool ok = (kc >= mk.cs) && (kc < mk.cs + 16); const float bz = rl[ok ? kc : mk.qcol]; s0[i] = ok ? s0[i] + bz : -1e30f; }
;                 { const int kc2 = kc + 32; const bool ok = (kc2 >= mk.cs) && (kc2 < mk.cs + 16); const float bz = rl[ok ? kc2 : mk.qcol]; s1[i] = ok ? s1[i] + bz : -1e30f; } }
;         }
;         if (MODE == 2 && latent) {
;             const int kb = 64 * mk.lt;
; #pragma unroll
;             for (int i = 0; i < 16; ++i) { const int d0 = kb + crow(i, h) - mk.qpos, d1 = d0 + 32;
;                 if (d0 > 128 || d0 < -128) s0[i] = -1e30f; if (d1 > 128 || d1 < -128) s1[i] = -1e30f; }
;         }
;         float ma = fmaxf(fmaxf(s0[0], s0[1]), s0[2]), mb = fmaxf(fmaxf(s1[0], s1[1]), s1[2]);
; #pragma unroll
; DI void att_sm_tail(f32x16 (&S)[2], bf16x8 (&pkm)[2][2], const float mrefm, float& lrunm) {
;     {
;         f32x16& s0 = S[0]; f32x16& s1 = S[1];
;         const f32x2 nm2 = {-mrefm, -mrefm};
;         f32x2 acc2 = {0.f, 0.f};
; #pragma unroll
;         for (int i = 0; i < 16; i += 2) {
;             f32x2 a = {s0[i], s0[i + 1]}, b = {s1[i], s1[i + 1]}; a += nm2; b += nm2;
;             a.x = fast_exp2(a.x); a.y = fast_exp2(a.y); b.x = fast_exp2(b.x); b.y = fast_exp2(b.y);
;             acc2 += a; acc2 += b; s0[i] = a.x; s0[i + 1] = a.y; s1[i] = b.x; s1[i + 1] = b.y;
;         }
;         lrunm += acc2.x + acc2.y;
; #pragma unroll
;         for (int s = 0; s < 2; ++s) {
;             u32x4 w0, w1;
;             w0.x = pk2(s0[8 * s + 0], s0[8 * s + 1]); w0.y = pk2(s0[8 * s + 2], s0[8 * s + 3]); w0.z = pk2(s0[8 * s + 4], s0[8 * s + 5]); w0.w = pk2(s0[8 * s + 6], s0[8 * s + 7]);
;             w1.x = pk2(s1[8 * s + 0], s1[8 * s + 1]); w1.y = pk2(s1[8 * s + 2], s1[8 * s + 3]); w1.z = pk2(s1[8 * s + 4], s1[8 * s + 5]); w1.w = pk2(s1[8 * s + 6], s1[8 * s + 7]);
;             pkm[0][s] = __builtin_bit_cast(bf16x8, w0); pkm[1][s] = __builtin_bit_cast(bf16x8, w1);
;         }
;     }
; }
	v_mfma_f32_32x32x16_bf16 v[64:79], v[184:187], v[124:127], v[64:79]
	v_add_f32_e64 v90, v90, -v210
	v_add_f32_e64 v91, v91, -v210
	v_add_f32_e64 v106, v106, -v210
	v_add_f32_e64 v107, v107, -v210
	v_exp_f32_e32 v90, v90
	v_exp_f32_e32 v91, v91
	v_exp_f32_e32 v106, v106
	v_exp_f32_e32 v107, v107
	v_pk_add_f32 v[92:93], v[92:93], v[210:211] op_sel_hi:[1,0] neg_lo:[0,1] neg_hi:[0,1]
	v_pk_add_f32 v[108:109], v[108:109], v[210:211] op_sel_hi:[1,0] neg_lo:[0,1] neg_hi:[0,1]
	v_exp_f32_e32 v92, v92
	v_exp_f32_e32 v93, v93
	v_exp_f32_e32 v108, v108
	v_exp_f32_e32 v109, v109
	v_pk_add_f32 v[94:95], v[94:95], v[210:211] op_sel_hi:[1,0] neg_lo:[0,1] neg_hi:[0,1]
	v_pk_add_f32 v[80:81], v[90:91], v[80:81]
	v_pk_add_f32 v[110:111], v[110:111], v[210:211] op_sel_hi:[1,0] neg_lo:[0,1] neg_hi:[0,1]
	v_exp_f32_e32 v94, v94
	v_exp_f32_e32 v95, v95
	v_pk_add_f32 v[80:81], v[106:107], v[80:81]
	v_exp_f32_e32 v110, v110
	v_exp_f32_e32 v111, v111
	v_pk_add_f32 v[80:81], v[92:93], v[80:81]
	s_nop 0
	v_pk_add_f32 v[80:81], v[108:109], v[80:81]
	s_nop 0
	v_pk_add_f32 v[80:81], v[94:95], v[80:81]
	s_nop 0
	v_pk_add_f32 v[80:81], v[110:111], v[80:81]
	s_nop 0
	v_add_f32_e32 v80, v80, v81
	v_add_f32_e32 v236, v236, v80
	v_cvt_pk_bf16_f32 v80, v14, v15
	v_cvt_pk_bf16_f32 v81, v82, v83
	v_cvt_pk_bf16_f32 v82, v84, v85
	v_cvt_pk_bf16_f32 v83, v86, v87
	v_cvt_pk_bf16_f32 v84, v96, v97
	v_cvt_pk_bf16_f32 v85, v98, v99
	s_waitcnt lgkmcnt(2)
	v_mfma_f32_32x32x16_bf16 v[64:79], v[180:183], v[112:115], v[64:79]
	v_cvt_pk_bf16_f32 v86, v100, v101
	v_cvt_pk_bf16_f32 v87, v102, v103
	v_cvt_pk_bf16_f32 v88, v88, v89
	v_cvt_pk_bf16_f32 v89, v90, v91
	v_cvt_pk_bf16_f32 v90, v92, v93
	v_cvt_pk_bf16_f32 v91, v94, v95
	v_cvt_pk_bf16_f32 v92, v104, v105
	v_cvt_pk_bf16_f32 v93, v106, v107
	v_cvt_pk_bf16_f32 v94, v108, v109
	v_cvt_pk_bf16_f32 v95, v110, v111
	s_waitcnt lgkmcnt(0)
	v_mfma_f32_32x32x16_bf16 v[64:79], v[10:13], v[116:119], v[64:79]
	v_mfma_f32_32x32x16_bf16 v[48:63], v[188:191], v[80:83], v[48:63]
	v_mfma_f32_32x32x16_bf16 v[48:63], v[184:187], v[88:91], v[48:63]
	v_mfma_f32_32x32x16_bf16 v[48:63], v[180:183], v[84:87], v[48:63]
	v_mfma_f32_32x32x16_bf16 v[48:63], v[10:13], v[92:95], v[48:63]
	ds_read_b64_tr_b16 v[10:11], v0 offset:18496
	ds_read_b64_tr_b16 v[12:13], v0 offset:19648
	ds_read_b64_tr_b16 v[96:97], v0 offset:20800
	ds_read_b64_tr_b16 v[98:99], v0 offset:21952
	ds_read_b64_tr_b16 v[100:101], v0 offset:23104
	ds_read_b64_tr_b16 v[102:103], v0 offset:24256
	ds_read_b64_tr_b16 v[104:105], v0 offset:25408
	ds_read_b64_tr_b16 v[106:107], v0 offset:26560
	s_setprio 1
	s_waitcnt lgkmcnt(6)
	v_mfma_f32_32x32x16_bf16 v[32:47], v[10:13], v[120:123], v[32:47]
	v_mfma_f32_32x32x16_bf16 v[16:31], v[10:13], v[80:83], v[16:31]
	s_waitcnt lgkmcnt(4)
	v_mfma_f32_32x32x16_bf16 v[32:47], v[96:99], v[124:127], v[32:47]
	v_mfma_f32_32x32x16_bf16 v[16:31], v[96:99], v[88:91], v[16:31]
	s_waitcnt lgkmcnt(2)
	v_mfma_f32_32x32x16_bf16 v[32:47], v[100:103], v[112:115], v[32:47]
	v_mfma_f32_32x32x16_bf16 v[16:31], v[100:103], v[84:87], v[16:31]
	s_waitcnt lgkmcnt(0)
	v_mfma_f32_32x32x16_bf16 v[32:47], v[104:107], v[116:119], v[32:47]
	v_mfma_f32_32x32x16_bf16 v[16:31], v[104:107], v[92:95], v[16:31]
	s_setprio 0
	s_branch .LBB0_580
.LB_slow1:
	v_add_u32_e32 v0, s3, v243
	v_add_u32_e32 v0, v0, v204
	ds_read_b128 v[10:13], v0
	ds_read_b128 v[80:83], v0 offset:32
	ds_read_b128 v[84:87], v0 offset:4608
	ds_read_b128 v[88:91], v0 offset:4640
	s_setprio 1
	s_waitcnt lgkmcnt(3)
	v_mfma_f32_32x32x16_bf16 v[112:127], v[10:13], v[156:159], 0
	s_waitcnt lgkmcnt(1)
	v_mfma_f32_32x32x16_bf16 v[128:143], v[84:87], v[156:159], 0
	v_mfma_f32_32x32x16_bf16 v[112:127], v[80:83], v[160:163], v[112:127]
	s_waitcnt lgkmcnt(0)
	v_mfma_f32_32x32x16_bf16 v[128:143], v[88:91], v[160:163], v[128:143]
	s_setprio 0
	s_nop 10
	v_max_f32_e32 v11, v129, v129
	v_max_f32_e32 v12, v128, v128
	v_max_f32_e32 v11, v12, v11
	v_max3_f32 v10, v112, v113, v114
	v_max3_f32 v11, v11, v130, v131
	v_max3_f32 v10, v10, v115, v116
	v_max3_f32 v11, v11, v132, v133
	v_max3_f32 v10, v10, v117, v118
	v_max3_f32 v11, v11, v134, v135
	v_max3_f32 v10, v10, v119, v120
	v_max3_f32 v11, v11, v136, v137
	v_max3_f32 v10, v10, v121, v122
	v_max3_f32 v11, v11, v138, v139
	v_max3_f32 v10, v10, v123, v124
	v_max3_f32 v11, v11, v140, v141
	v_max3_f32 v10, v10, v125, v126
	v_max3_f32 v11, v11, v142, v143
	v_max3_f32 v10, v10, v127, v11
	v_mov_b32_e32 v11, v10
	s_nop 1
	v_permlane32_swap_b32_e32 v10, v11
	v_max_f32_e32 v11, v11, v11
	v_max_f32_e32 v10, v10, v10
	v_max_f32_e32 v10, v10, v11
	v_sub_f32_e32 v11, v10, v212
	v_cmp_gt_f32_e64 s[4:5], s22, v212
	v_cmp_lt_f32_e32 vcc, s23, v11
	s_or_b64 vcc, s[4:5], vcc
	s_cbranch_vccz .LB_rescA1
	v_cndmask_b32_e32 v11, v212, v10, vcc
	v_sub_f32_e32 v10, v212, v11
	v_exp_f32_e32 v10, v10
	v_mov_b32_e32 v212, v11
	v_cndmask_b32_e64 v10, v10, 1.0, s[4:5]
	v_mul_f32_e32 v245, v245, v10
	v_pk_mul_f32 v[78:79], v[78:79], v[10:11] op_sel_hi:[1,0]
	v_pk_mul_f32 v[76:77], v[76:77], v[10:11] op_sel_hi:[1,0]
	v_pk_mul_f32 v[74:75], v[74:75], v[10:11] op_sel_hi:[1,0]
	v_pk_mul_f32 v[72:73], v[72:73], v[10:11] op_sel_hi:[1,0]
	v_pk_mul_f32 v[70:71], v[70:71], v[10:11] op_sel_hi:[1,0]
	v_pk_mul_f32 v[68:69], v[68:69], v[10:11] op_sel_hi:[1,0]
	v_pk_mul_f32 v[66:67], v[66:67], v[10:11] op_sel_hi:[1,0]
	v_pk_mul_f32 v[64:65], v[64:65], v[10:11] op_sel_hi:[1,0]
	v_pk_mul_f32 v[46:47], v[46:47], v[10:11] op_sel_hi:[1,0]
	v_pk_mul_f32 v[44:45], v[44:45], v[10:11] op_sel_hi:[1,0]
	v_pk_mul_f32 v[42:43], v[42:43], v[10:11] op_sel_hi:[1,0]
	v_pk_mul_f32 v[40:41], v[40:41], v[10:11] op_sel_hi:[1,0]
	v_pk_mul_f32 v[38:39], v[38:39], v[10:11] op_sel_hi:[1,0]
	v_pk_mul_f32 v[36:37], v[36:37], v[10:11] op_sel_hi:[1,0]
	v_pk_mul_f32 v[34:35], v[34:35], v[10:11] op_sel_hi:[1,0]
	v_pk_mul_f32 v[32:33], v[32:33], v[10:11] op_sel_hi:[1,0]

; DI unsigned pk2(float lo, float hi) { f32x2 v = {lo, hi}; bf16x2_t b = __builtin_convertvector(v, bf16x2_t); return __builtin_bit_cast(unsigned, b); }
; DI float fast_exp2(float x) { return __builtin_amdgcn_exp2f(x); }
; DI void att_sm_tail(f32x16 (&S)[2], bf16x8 (&pkm)[2][2], const float mrefm, float& lrunm) {
;     {
;         f32x16& s0 = S[0]; f32x16& s1 = S[1];
;         const f32x2 nm2 = {-mrefm, -mrefm};
;         f32x2 acc2 = {0.f, 0.f};
; #pragma unroll
;         for (int i = 0; i < 16; i += 2) {
;             f32x2 a = {s0[i], s0[i + 1]}, b = {s1[i], s1[i + 1]}; a += nm2; b += nm2;
;             a.x = fast_exp2(a.x); a.y = fast_exp2(a.y); b.x = fast_exp2(b.x); b.y = fast_exp2(b.y);
;             acc2 += a; acc2 += b; s0[i] = a.x; s0[i + 1] = a.y; s1[i] = b.x; s1[i + 1] = b.y;
;         }
;         lrunm += acc2.x + acc2.y;
; #pragma unroll
;         for (int s = 0; s < 2; ++s) {
;             u32x4 w0, w1;
;             w0.x = pk2(s0[8 * s + 0], s0[8 * s + 1]); w0.y = pk2(s0[8 * s + 2], s0[8 * s + 3]); w0.z = pk2(s0[8 * s + 4], s0[8 * s + 5]); w0.w = pk2(s0[8 * s + 6], s0[8 * s + 7]);
;             w1.x = pk2(s1[8 * s + 0], s1[8 * s + 1]); w1.y = pk2(s1[8 * s + 2], s1[8 * s + 3]); w1.z = pk2(s1[8 * s + 4], s1[8 * s + 5]); w1.w = pk2(s1[8 * s + 6], s1[8 * s + 7]);
;             pkm[0][s] = __builtin_bit_cast(bf16x8, w0); pkm[1][s] = __builtin_bit_cast(bf16x8, w1);
;         }
;     }
; }
.LB_rescB1:
	v_pk_add_f32 v[14:15], v[112:113], v[212:213] op_sel_hi:[1,0] neg_lo:[0,1] neg_hi:[0,1]
	v_pk_add_f32 v[112:113], v[128:129], v[212:213] op_sel_hi:[1,0] neg_lo:[0,1] neg_hi:[0,1]
	v_exp_f32_e32 v14, v14
	v_exp_f32_e32 v15, v15
	v_exp_f32_e32 v112, v112
	v_exp_f32_e32 v113, v113
	v_pk_add_f32 v[114:115], v[114:115], v[212:213] op_sel_hi:[1,0] neg_lo:[0,1] neg_hi:[0,1]
	v_pk_add_f32 v[128:129], v[130:131], v[212:213] op_sel_hi:[1,0] neg_lo:[0,1] neg_hi:[0,1]
	v_exp_f32_e32 v114, v114
	v_exp_f32_e32 v115, v115
	v_exp_f32_e32 v128, v128
	v_exp_f32_e32 v129, v129
	v_pk_add_f32 v[116:117], v[116:117], v[212:213] op_sel_hi:[1,0] neg_lo:[0,1] neg_hi:[0,1]
	v_pk_add_f32 v[130:131], v[14:15], 0 op_sel_hi:[1,0]
	v_pk_add_f32 v[132:133], v[132:133], v[212:213] op_sel_hi:[1,0] neg_lo:[0,1] neg_hi:[0,1]
	v_exp_f32_e32 v116, v116
	v_exp_f32_e32 v117, v117
	v_pk_add_f32 v[130:131], v[112:113], v[130:131]
	v_exp_f32_e32 v132, v132
	v_exp_f32_e32 v133, v133
	v_pk_add_f32 v[118:119], v[118:119], v[212:213] op_sel_hi:[1,0] neg_lo:[0,1] neg_hi:[0,1]
	v_pk_add_f32 v[130:131], v[114:115], v[130:131]
	v_pk_add_f32 v[134:135], v[134:135], v[212:213] op_sel_hi:[1,0] neg_lo:[0,1] neg_hi:[0,1]
	v_exp_f32_e32 v118, v118
	v_exp_f32_e32 v119, v119
	v_pk_add_f32 v[130:131], v[128:129], v[130:131]
	v_exp_f32_e32 v134, v134
	v_exp_f32_e32 v135, v135
	v_pk_add_f32 v[120:121], v[120:121], v[212:213] op_sel_hi:[1,0] neg_lo:[0,1] neg_hi:[0,1]
	v_pk_add_f32 v[130:131], v[116:117], v[130:131]
	v_pk_add_f32 v[136:137], v[136:137], v[212:213] op_sel_hi:[1,0] neg_lo:[0,1] neg_hi:[0,1]
	v_exp_f32_e32 v246, v120
	v_exp_f32_e32 v247, v121
	v_pk_add_f32 v[130:131], v[132:133], v[130:131]
	v_exp_f32_e32 v136, v136
	v_exp_f32_e32 v137, v137
	v_pk_add_f32 v[120:121], v[122:123], v[212:213] op_sel_hi:[1,0] neg_lo:[0,1] neg_hi:[0,1]
	v_pk_add_f32 v[130:131], v[118:119], v[130:131]
	v_pk_add_f32 v[122:123], v[138:139], v[212:213] op_sel_hi:[1,0] neg_lo:[0,1] neg_hi:[0,1]
	v_exp_f32_e32 v138, v120
	v_exp_f32_e32 v139, v121
	v_pk_add_f32 v[130:131], v[134:135], v[130:131]
	v_exp_f32_e32 v248, v122
	v_exp_f32_e32 v249, v123
	v_pk_add_f32 v[122:123], v[124:125], v[212:213] op_sel_hi:[1,0] neg_lo:[0,1] neg_hi:[0,1]
	v_pk_add_f32 v[120:121], v[246:247], v[130:131]
	v_pk_add_f32 v[124:125], v[140:141], v[212:213] op_sel_hi:[1,0] neg_lo:[0,1] neg_hi:[0,1]
	v_exp_f32_e32 v130, v122
	v_exp_f32_e32 v131, v123
	v_pk_add_f32 v[120:121], v[136:137], v[120:121]
	v_exp_f32_e32 v140, v124
	v_exp_f32_e32 v141, v125
	v_pk_add_f32 v[122:123], v[126:127], v[212:213] op_sel_hi:[1,0] neg_lo:[0,1] neg_hi:[0,1]
	v_pk_add_f32 v[120:121], v[138:139], v[120:121]
	v_pk_add_f32 v[124:125], v[142:143], v[212:213] op_sel_hi:[1,0] neg_lo:[0,1] neg_hi:[0,1]
	v_exp_f32_e32 v142, v122
	v_exp_f32_e32 v143, v123
	v_pk_add_f32 v[120:121], v[248:249], v[120:121]
	v_exp_f32_e32 v250, v124
	v_exp_f32_e32 v251, v125
	v_pk_add_f32 v[120:121], v[130:131], v[120:121]
	v_cvt_pk_bf16_f32 v122, v116, v117
	v_pk_add_f32 v[120:121], v[140:141], v[120:121]
	v_cvt_pk_bf16_f32 v123, v118, v119
	v_pk_add_f32 v[120:121], v[142:143], v[120:121]
	v_cvt_pk_bf16_f32 v112, v112, v113
	v_pk_add_f32 v[120:121], v[250:251], v[120:121]
	v_cvt_pk_bf16_f32 v113, v128, v129
	v_add_f32_e32 v120, v120, v121
	v_add_f32_e32 v245, v245, v120
	v_cvt_pk_bf16_f32 v120, v14, v15
	v_cvt_pk_bf16_f32 v121, v114, v115
	v_cvt_pk_bf16_f32 v114, v132, v133
	v_cvt_pk_bf16_f32 v115, v134, v135
	v_cvt_pk_bf16_f32 v124, v246, v247
	v_cvt_pk_bf16_f32 v125, v138, v139
	v_cvt_pk_bf16_f32 v126, v130, v131
	v_cvt_pk_bf16_f32 v127, v142, v143
	v_cvt_pk_bf16_f32 v116, v136, v137
	v_cvt_pk_bf16_f32 v117, v248, v249
	v_cvt_pk_bf16_f32 v118, v140, v141
	v_cvt_pk_bf16_f32 v119, v250, v251
	s_waitcnt lgkmcnt(3)
; DI unsigned pk2(float lo, float hi) { f32x2 v = {lo, hi}; bf16x2_t b = __builtin_convertvector(v, bf16x2_t); return __builtin_bit_cast(unsigned, b); }
; DI float fast_exp2(float x) { return __builtin_amdgcn_exp2f(x); }
; DI void att_sm_tail(f32x16 (&S)[2], bf16x8 (&pkm)[2][2], const float mrefm, float& lrunm) {
;     {
;         f32x16& s0 = S[0]; f32x16& s1 = S[1];
;         const f32x2 nm2 = {-mrefm, -mrefm};
;         f32x2 acc2 = {0.f, 0.f};
; #pragma unroll
;         for (int i = 0; i < 16; i += 2) {
;             f32x2 a = {s0[i], s0[i + 1]}, b = {s1[i], s1[i + 1]}; a += nm2; b += nm2;
;             a.x = fast_exp2(a.x); a.y = fast_exp2(a.y); b.x = fast_exp2(b.x); b.y = fast_exp2(b.y);
;             acc2 += a; acc2 += b; s0[i] = a.x; s0[i + 1] = a.y; s1[i] = b.x; s1[i + 1] = b.y;
;         }
;         lrunm += acc2.x + acc2.y;
; #pragma unroll
;         for (int s = 0; s < 2; ++s) {
;             u32x4 w0, w1;
;             w0.x = pk2(s0[8 * s + 0], s0[8 * s + 1]); w0.y = pk2(s0[8 * s + 2], s0[8 * s + 3]); w0.z = pk2(s0[8 * s + 4], s0[8 * s + 5]); w0.w = pk2(s0[8 * s + 6], s0[8 * s + 7]);
;             w1.x = pk2(s1[8 * s + 0], s1[8 * s + 1]); w1.y = pk2(s1[8 * s + 2], s1[8 * s + 3]); w1.z = pk2(s1[8 * s + 4], s1[8 * s + 5]); w1.w = pk2(s1[8 * s + 6], s1[8 * s + 7]);
;             pkm[0][s] = __builtin_bit_cast(bf16x8, w0); pkm[1][s] = __builtin_bit_cast(bf16x8, w1);
;         }
;     }
; }
	v_mfma_f32_32x32x16_bf16 v[64:79], v[188:191], v[120:123], v[64:79]
	v_add_f32_e64 v14, v80, -v210
	v_add_f32_e64 v15, v81, -v210
	v_add_f32_e64 v80, v96, -v210
	v_add_f32_e64 v81, v97, -v210
	v_exp_f32_e32 v14, v14
	v_exp_f32_e32 v15, v15
	v_exp_f32_e32 v96, v80
	v_exp_f32_e32 v97, v81
	v_pk_add_f32 v[82:83], v[82:83], v[210:211] op_sel_hi:[1,0] neg_lo:[0,1] neg_hi:[0,1]
	v_pk_add_f32 v[98:99], v[98:99], v[210:211] op_sel_hi:[1,0] neg_lo:[0,1] neg_hi:[0,1]
	v_exp_f32_e32 v82, v82
	v_exp_f32_e32 v83, v83
	v_exp_f32_e32 v98, v98
	v_exp_f32_e32 v99, v99
	v_pk_add_f32 v[84:85], v[84:85], v[210:211] op_sel_hi:[1,0] neg_lo:[0,1] neg_hi:[0,1]
	v_pk_add_f32 v[80:81], v[14:15], 0 op_sel_hi:[1,0]
	v_pk_add_f32 v[100:101], v[100:101], v[210:211] op_sel_hi:[1,0] neg_lo:[0,1] neg_hi:[0,1]
	v_exp_f32_e32 v84, v84
	v_exp_f32_e32 v85, v85
	v_pk_add_f32 v[80:81], v[96:97], v[80:81]
	v_exp_f32_e32 v100, v100
	v_exp_f32_e32 v101, v101
	v_pk_add_f32 v[86:87], v[86:87], v[210:211] op_sel_hi:[1,0] neg_lo:[0,1] neg_hi:[0,1]
	v_pk_add_f32 v[80:81], v[82:83], v[80:81]
	v_pk_add_f32 v[102:103], v[102:103], v[210:211] op_sel_hi:[1,0] neg_lo:[0,1] neg_hi:[0,1]
	v_exp_f32_e32 v86, v86
	v_exp_f32_e32 v87, v87
	v_pk_add_f32 v[80:81], v[98:99], v[80:81]
	v_exp_f32_e32 v102, v102
	v_exp_f32_e32 v103, v103
	v_pk_add_f32 v[88:89], v[88:89], v[210:211] op_sel_hi:[1,0] neg_lo:[0,1] neg_hi:[0,1]
	v_pk_add_f32 v[80:81], v[84:85], v[80:81]
	v_pk_add_f32 v[104:105], v[104:105], v[210:211] op_sel_hi:[1,0] neg_lo:[0,1] neg_hi:[0,1]
	v_exp_f32_e32 v88, v88
	v_exp_f32_e32 v89, v89
	v_pk_add_f32 v[80:81], v[100:101], v[80:81]
	v_exp_f32_e32 v104, v104
	v_exp_f32_e32 v105, v105
	v_pk_add_f32 v[80:81], v[86:87], v[80:81]
	s_nop 0
	v_pk_add_f32 v[80:81], v[102:103], v[80:81]
	s_nop 0
	v_pk_add_f32 v[80:81], v[88:89], v[80:81]
	s_nop 0
	v_pk_add_f32 v[80:81], v[104:105], v[80:81]
	v_mfma_f32_32x32x16_bf16 v[64:79], v[180:183], v[124:127], v[64:79]
	v_add_f32_e64 v90, v90, -v210
	v_add_f32_e64 v91, v91, -v210
	v_add_f32_e64 v106, v106, -v210
	v_add_f32_e64 v107, v107, -v210
	v_exp_f32_e32 v90, v90
	v_exp_f32_e32 v91, v91
	v_exp_f32_e32 v106, v106
	v_exp_f32_e32 v107, v107
	v_pk_add_f32 v[92:93], v[92:93], v[210:211] op_sel_hi:[1,0] neg_lo:[0,1] neg_hi:[0,1]
	v_pk_add_f32 v[108:109], v[108:109], v[210:211] op_sel_hi:[1,0] neg_lo:[0,1] neg_hi:[0,1]
	v_exp_f32_e32 v92, v92
	v_exp_f32_e32 v93, v93
	v_exp_f32_e32 v108, v108
	v_exp_f32_e32 v109, v109
	v_pk_add_f32 v[94:95], v[94:95], v[210:211] op_sel_hi:[1,0] neg_lo:[0,1] neg_hi:[0,1]
	v_pk_add_f32 v[80:81], v[90:91], v[80:81]
	v_pk_add_f32 v[110:111], v[110:111], v[210:211] op_sel_hi:[1,0] neg_lo:[0,1] neg_hi:[0,1]
	v_exp_f32_e32 v94, v94
	v_exp_f32_e32 v95, v95
	v_pk_add_f32 v[80:81], v[106:107], v[80:81]
	v_exp_f32_e32 v110, v110
	v_exp_f32_e32 v111, v111
	v_pk_add_f32 v[80:81], v[92:93], v[80:81]
	s_nop 0
	v_pk_add_f32 v[80:81], v[108:109], v[80:81]
	s_nop 0
	v_pk_add_f32 v[80:81], v[94:95], v[80:81]
	s_nop 0
	v_pk_add_f32 v[80:81], v[110:111], v[80:81]
	s_nop 0
	v_add_f32_e32 v80, v80, v81
	v_add_f32_e32 v236, v236, v80
	v_cvt_pk_bf16_f32 v80, v14, v15
	v_cvt_pk_bf16_f32 v81, v82, v83
	v_cvt_pk_bf16_f32 v82, v84, v85
	v_cvt_pk_bf16_f32 v83, v86, v87
	v_cvt_pk_bf16_f32 v84, v96, v97
	v_cvt_pk_bf16_f32 v85, v98, v99
	s_waitcnt lgkmcnt(2)
	v_mfma_f32_32x32x16_bf16 v[64:79], v[10:13], v[112:115], v[64:79]
	v_cvt_pk_bf16_f32 v86, v100, v101
	v_cvt_pk_bf16_f32 v87, v102, v103
	v_cvt_pk_bf16_f32 v88, v88, v89
	v_cvt_pk_bf16_f32 v89, v90, v91
	v_cvt_pk_bf16_f32 v90, v92, v93
	v_cvt_pk_bf16_f32 v91, v94, v95
	v_cvt_pk_bf16_f32 v92, v104, v105
	v_cvt_pk_bf16_f32 v93, v106, v107
	v_cvt_pk_bf16_f32 v94, v108, v109
	v_cvt_pk_bf16_f32 v95, v110, v111
	s_waitcnt lgkmcnt(0)
	v_mfma_f32_32x32x16_bf16 v[64:79], v[184:187], v[116:119], v[64:79]
	v_mfma_f32_32x32x16_bf16 v[48:63], v[188:191], v[80:83], v[48:63]
	v_mfma_f32_32x32x16_bf16 v[48:63], v[180:183], v[88:91], v[48:63]
	v_mfma_f32_32x32x16_bf16 v[48:63], v[10:13], v[84:87], v[48:63]
	v_mfma_f32_32x32x16_bf16 v[48:63], v[184:187], v[92:95], v[48:63]
	ds_read_b64_tr_b16 v[12:13], v0 offset:28864
	ds_read_b64_tr_b16 v[96:97], v0 offset:30016
	ds_read_b64_tr_b16 v[98:99], v0 offset:31168
	ds_read_b64_tr_b16 v[100:101], v0 offset:32320
	ds_read_b64_tr_b16 v[10:11], v0 offset:27712
	ds_read_b64_tr_b16 v[102:103], v0 offset:33472
	ds_read_b64_tr_b16 v[104:105], v0 offset:34624
	ds_read_b64_tr_b16 v[106:107], v0 offset:35776
	s_setprio 1
	s_waitcnt lgkmcnt(3)
	v_mfma_f32_32x32x16_bf16 v[32:47], v[10:13], v[120:123], v[32:47]
	v_mfma_f32_32x32x16_bf16 v[16:31], v[10:13], v[80:83], v[16:31]
	v_mfma_f32_32x32x16_bf16 v[32:47], v[96:99], v[124:127], v[32:47]
	v_mfma_f32_32x32x16_bf16 v[16:31], v[96:99], v[88:91], v[16:31]
	s_waitcnt lgkmcnt(2)
	v_mfma_f32_32x32x16_bf16 v[32:47], v[100:103], v[112:115], v[32:47]
	v_mfma_f32_32x32x16_bf16 v[16:31], v[100:103], v[84:87], v[16:31]
	s_waitcnt lgkmcnt(0)
	v_mfma_f32_32x32x16_bf16 v[32:47], v[104:107], v[116:119], v[32:47]
	v_mfma_f32_32x32x16_bf16 v[16:31], v[104:107], v[92:95], v[16:31]
	s_setprio 0
	s_branch .LBB0_586

; DI unsigned pk2(float lo, float hi) { f32x2 v = {lo, hi}; bf16x2_t b = __builtin_convertvector(v, bf16x2_t); return __builtin_bit_cast(unsigned, b); }
; DI float fast_exp2(float x) { return __builtin_amdgcn_exp2f(x); }
; DI void att_sm_tail(f32x16 (&S)[2], bf16x8 (&pkm)[2][2], const float mrefm, float& lrunm) {
;     {
;         f32x16& s0 = S[0]; f32x16& s1 = S[1];
;         const f32x2 nm2 = {-mrefm, -mrefm};
;         f32x2 acc2 = {0.f, 0.f};
; #pragma unroll
;         for (int i = 0; i < 16; i += 2) {
;             f32x2 a = {s0[i], s0[i + 1]}, b = {s1[i], s1[i + 1]}; a += nm2; b += nm2;
;             a.x = fast_exp2(a.x); a.y = fast_exp2(a.y); b.x = fast_exp2(b.x); b.y = fast_exp2(b.y);
;             acc2 += a; acc2 += b; s0[i] = a.x; s0[i + 1] = a.y; s1[i] = b.x; s1[i + 1] = b.y;
;         }
;         lrunm += acc2.x + acc2.y;
; #pragma unroll
;         for (int s = 0; s < 2; ++s) {
;             u32x4 w0, w1;
;             w0.x = pk2(s0[8 * s + 0], s0[8 * s + 1]); w0.y = pk2(s0[8 * s + 2], s0[8 * s + 3]); w0.z = pk2(s0[8 * s + 4], s0[8 * s + 5]); w0.w = pk2(s0[8 * s + 6], s0[8 * s + 7]);
;             w1.x = pk2(s1[8 * s + 0], s1[8 * s + 1]); w1.y = pk2(s1[8 * s + 2], s1[8 * s + 3]); w1.z = pk2(s1[8 * s + 4], s1[8 * s + 5]); w1.w = pk2(s1[8 * s + 6], s1[8 * s + 7]);
;             pkm[0][s] = __builtin_bit_cast(bf16x8, w0); pkm[1][s] = __builtin_bit_cast(bf16x8, w1);
;         }
;     }
; }
.LB_rescB2:
	v_pk_add_f32 v[14:15], v[112:113], v[212:213] op_sel_hi:[1,0] neg_lo:[0,1] neg_hi:[0,1]
	v_pk_add_f32 v[112:113], v[128:129], v[212:213] op_sel_hi:[1,0] neg_lo:[0,1] neg_hi:[0,1]
	v_exp_f32_e32 v14, v14
	v_exp_f32_e32 v15, v15
	v_exp_f32_e32 v112, v112
	v_exp_f32_e32 v113, v113
	v_pk_add_f32 v[114:115], v[114:115], v[212:213] op_sel_hi:[1,0] neg_lo:[0,1] neg_hi:[0,1]
	v_pk_add_f32 v[128:129], v[130:131], v[212:213] op_sel_hi:[1,0] neg_lo:[0,1] neg_hi:[0,1]
	v_exp_f32_e32 v114, v114
	v_exp_f32_e32 v115, v115
	v_exp_f32_e32 v128, v128
	v_exp_f32_e32 v129, v129
	v_pk_add_f32 v[116:117], v[116:117], v[212:213] op_sel_hi:[1,0] neg_lo:[0,1] neg_hi:[0,1]
	v_pk_add_f32 v[130:131], v[14:15], 0 op_sel_hi:[1,0]
	v_pk_add_f32 v[132:133], v[132:133], v[212:213] op_sel_hi:[1,0] neg_lo:[0,1] neg_hi:[0,1]
	v_exp_f32_e32 v116, v116
	v_exp_f32_e32 v117, v117
	v_pk_add_f32 v[130:131], v[112:113], v[130:131]
	v_exp_f32_e32 v132, v132
	v_exp_f32_e32 v133, v133
	v_pk_add_f32 v[118:119], v[118:119], v[212:213] op_sel_hi:[1,0] neg_lo:[0,1] neg_hi:[0,1]
	v_pk_add_f32 v[130:131], v[114:115], v[130:131]
	v_pk_add_f32 v[134:135], v[134:135], v[212:213] op_sel_hi:[1,0] neg_lo:[0,1] neg_hi:[0,1]
	v_exp_f32_e32 v118, v118
	v_exp_f32_e32 v119, v119
	v_pk_add_f32 v[130:131], v[128:129], v[130:131]
	v_exp_f32_e32 v134, v134
	v_exp_f32_e32 v135, v135
	v_pk_add_f32 v[120:121], v[120:121], v[212:213] op_sel_hi:[1,0] neg_lo:[0,1] neg_hi:[0,1]
	v_pk_add_f32 v[130:131], v[116:117], v[130:131]
	v_pk_add_f32 v[136:137], v[136:137], v[212:213] op_sel_hi:[1,0] neg_lo:[0,1] neg_hi:[0,1]
	v_exp_f32_e32 v246, v120
	v_exp_f32_e32 v247, v121
	v_pk_add_f32 v[130:131], v[132:133], v[130:131]
	v_exp_f32_e32 v136, v136
	v_exp_f32_e32 v137, v137
	v_pk_add_f32 v[120:121], v[122:123], v[212:213] op_sel_hi:[1,0] neg_lo:[0,1] neg_hi:[0,1]
	v_pk_add_f32 v[130:131], v[118:119], v[130:131]
	v_pk_add_f32 v[122:123], v[138:139], v[212:213] op_sel_hi:[1,0] neg_lo:[0,1] neg_hi:[0,1]
	v_exp_f32_e32 v138, v120
	v_exp_f32_e32 v139, v121
	v_pk_add_f32 v[130:131], v[134:135], v[130:131]
	v_exp_f32_e32 v248, v122
	v_exp_f32_e32 v249, v123
	v_pk_add_f32 v[122:123], v[124:125], v[212:213] op_sel_hi:[1,0] neg_lo:[0,1] neg_hi:[0,1]
	v_pk_add_f32 v[120:121], v[246:247], v[130:131]
	v_pk_add_f32 v[124:125], v[140:141], v[212:213] op_sel_hi:[1,0] neg_lo:[0,1] neg_hi:[0,1]
	v_exp_f32_e32 v130, v122
	v_exp_f32_e32 v131, v123
	v_pk_add_f32 v[120:121], v[136:137], v[120:121]
	v_exp_f32_e32 v140, v124
	v_exp_f32_e32 v141, v125
	v_pk_add_f32 v[122:123], v[126:127], v[212:213] op_sel_hi:[1,0] neg_lo:[0,1] neg_hi:[0,1]
	v_pk_add_f32 v[120:121], v[138:139], v[120:121]
	v_pk_add_f32 v[124:125], v[142:143], v[212:213] op_sel_hi:[1,0] neg_lo:[0,1] neg_hi:[0,1]
	v_exp_f32_e32 v142, v122
	v_exp_f32_e32 v143, v123
	v_pk_add_f32 v[120:121], v[248:249], v[120:121]
	v_exp_f32_e32 v250, v124
	v_exp_f32_e32 v251, v125
	v_pk_add_f32 v[120:121], v[130:131], v[120:121]
	v_cvt_pk_bf16_f32 v122, v116, v117
	v_pk_add_f32 v[120:121], v[140:141], v[120:121]
	v_cvt_pk_bf16_f32 v123, v118, v119
	v_pk_add_f32 v[120:121], v[142:143], v[120:121]
	v_cvt_pk_bf16_f32 v112, v112, v113
	v_pk_add_f32 v[120:121], v[250:251], v[120:121]
	v_cvt_pk_bf16_f32 v113, v128, v129
	v_add_f32_e32 v120, v120, v121
	v_add_f32_e32 v245, v245, v120
	v_cvt_pk_bf16_f32 v120, v14, v15
	v_cvt_pk_bf16_f32 v121, v114, v115
	v_cvt_pk_bf16_f32 v114, v132, v133
	v_cvt_pk_bf16_f32 v115, v134, v135
	v_cvt_pk_bf16_f32 v124, v246, v247
	v_cvt_pk_bf16_f32 v125, v138, v139
	v_cvt_pk_bf16_f32 v126, v130, v131
	v_cvt_pk_bf16_f32 v127, v142, v143
	v_cvt_pk_bf16_f32 v116, v136, v137
	v_cvt_pk_bf16_f32 v117, v248, v249
	v_cvt_pk_bf16_f32 v118, v140, v141
	v_cvt_pk_bf16_f32 v119, v250, v251
	s_waitcnt lgkmcnt(6)
; DI unsigned pk2(float lo, float hi) { f32x2 v = {lo, hi}; bf16x2_t b = __builtin_convertvector(v, bf16x2_t); return __builtin_bit_cast(unsigned, b); }
; DI float fast_exp2(float x) { return __builtin_amdgcn_exp2f(x); }
; DI void att_sm_tail(f32x16 (&S)[2], bf16x8 (&pkm)[2][2], const float mrefm, float& lrunm) {
;     {
;         f32x16& s0 = S[0]; f32x16& s1 = S[1];
;         const f32x2 nm2 = {-mrefm, -mrefm};
;         f32x2 acc2 = {0.f, 0.f};
; #pragma unroll
;         for (int i = 0; i < 16; i += 2) {
;             f32x2 a = {s0[i], s0[i + 1]}, b = {s1[i], s1[i + 1]}; a += nm2; b += nm2;
;             a.x = fast_exp2(a.x); a.y = fast_exp2(a.y); b.x = fast_exp2(b.x); b.y = fast_exp2(b.y);
;             acc2 += a; acc2 += b; s0[i] = a.x; s0[i + 1] = a.y; s1[i] = b.x; s1[i + 1] = b.y;
;         }
;         lrunm += acc2.x + acc2.y;
; #pragma unroll
;         for (int s = 0; s < 2; ++s) {
;             u32x4 w0, w1;
;             w0.x = pk2(s0[8 * s + 0], s0[8 * s + 1]); w0.y = pk2(s0[8 * s + 2], s0[8 * s + 3]); w0.z = pk2(s0[8 * s + 4], s0[8 * s + 5]); w0.w = pk2(s0[8 * s + 6], s0[8 * s + 7]);
;             w1.x = pk2(s1[8 * s + 0], s1[8 * s + 1]); w1.y = pk2(s1[8 * s + 2], s1[8 * s + 3]); w1.z = pk2(s1[8 * s + 4], s1[8 * s + 5]); w1.w = pk2(s1[8 * s + 6], s1[8 * s + 7]);
;             pkm[0][s] = __builtin_bit_cast(bf16x8, w0); pkm[1][s] = __builtin_bit_cast(bf16x8, w1);
;         }
;     }
; }
	v_mfma_f32_32x32x16_bf16 v[64:79], v[188:191], v[120:123], v[64:79]
	v_add_f32_e64 v14, v80, -v210
	v_add_f32_e64 v15, v81, -v210
	v_add_f32_e64 v80, v96, -v210
	v_add_f32_e64 v81, v97, -v210
	v_exp_f32_e32 v14, v14
	v_exp_f32_e32 v15, v15
	v_exp_f32_e32 v96, v80
	v_exp_f32_e32 v97, v81
	v_pk_add_f32 v[82:83], v[82:83], v[210:211] op_sel_hi:[1,0] neg_lo:[0,1] neg_hi:[0,1]
	v_pk_add_f32 v[98:99], v[98:99], v[210:211] op_sel_hi:[1,0] neg_lo:[0,1] neg_hi:[0,1]
	v_exp_f32_e32 v82, v82
	v_exp_f32_e32 v83, v83
	v_exp_f32_e32 v98, v98
	v_exp_f32_e32 v99, v99
	v_pk_add_f32 v[84:85], v[84:85], v[210:211] op_sel_hi:[1,0] neg_lo:[0,1] neg_hi:[0,1]
	v_pk_add_f32 v[80:81], v[14:15], 0 op_sel_hi:[1,0]
	v_pk_add_f32 v[100:101], v[100:101], v[210:211] op_sel_hi:[1,0] neg_lo:[0,1] neg_hi:[0,1]
	v_exp_f32_e32 v84, v84
	v_exp_f32_e32 v85, v85
	v_pk_add_f32 v[80:81], v[96:97], v[80:81]
	v_exp_f32_e32 v100, v100
	v_exp_f32_e32 v101, v101
	v_pk_add_f32 v[86:87], v[86:87], v[210:211] op_sel_hi:[1,0] neg_lo:[0,1] neg_hi:[0,1]
	v_pk_add_f32 v[80:81], v[82:83], v[80:81]
	v_pk_add_f32 v[102:103], v[102:103], v[210:211] op_sel_hi:[1,0] neg_lo:[0,1] neg_hi:[0,1]
	v_exp_f32_e32 v86, v86
	v_exp_f32_e32 v87, v87
	v_pk_add_f32 v[80:81], v[98:99], v[80:81]
	v_exp_f32_e32 v102, v102
	v_exp_f32_e32 v103, v103
	v_pk_add_f32 v[88:89], v[88:89], v[210:211] op_sel_hi:[1,0] neg_lo:[0,1] neg_hi:[0,1]
	v_pk_add_f32 v[80:81], v[84:85], v[80:81]
	v_pk_add_f32 v[104:105], v[104:105], v[210:211] op_sel_hi:[1,0] neg_lo:[0,1] neg_hi:[0,1]
	v_exp_f32_e32 v88, v88
	v_exp_f32_e32 v89, v89
	v_pk_add_f32 v[80:81], v[100:101], v[80:81]
	v_exp_f32_e32 v104, v104
	v_exp_f32_e32 v105, v105
	v_pk_add_f32 v[80:81], v[86:87], v[80:81]
	s_nop 0
	v_pk_add_f32 v[80:81], v[102:103], v[80:81]
	s_nop 0
	v_pk_add_f32 v[80:81], v[88:89], v[80:81]
	s_nop 0
	v_pk_add_f32 v[80:81], v[104:105], v[80:81]
	s_waitcnt lgkmcnt(4)
	v_mfma_f32_32x32x16_bf16 v[64:79], v[184:187], v[124:127], v[64:79]
	v_add_f32_e64 v90, v90, -v210
	v_add_f32_e64 v91, v91, -v210
	v_add_f32_e64 v106, v106, -v210
	v_add_f32_e64 v107, v107, -v210
	v_exp_f32_e32 v90, v90
	v_exp_f32_e32 v91, v91
	v_exp_f32_e32 v106, v106
	v_exp_f32_e32 v107, v107
	v_pk_add_f32 v[92:93], v[92:93], v[210:211] op_sel_hi:[1,0] neg_lo:[0,1] neg_hi:[0,1]
	v_pk_add_f32 v[108:109], v[108:109], v[210:211] op_sel_hi:[1,0] neg_lo:[0,1] neg_hi:[0,1]
	v_exp_f32_e32 v92, v92
	v_exp_f32_e32 v93, v93
	v_exp_f32_e32 v108, v108
	v_exp_f32_e32 v109, v109
	v_pk_add_f32 v[94:95], v[94:95], v[210:211] op_sel_hi:[1,0] neg_lo:[0,1] neg_hi:[0,1]
	v_pk_add_f32 v[80:81], v[90:91], v[80:81]
	v_pk_add_f32 v[110:111], v[110:111], v[210:211] op_sel_hi:[1,0] neg_lo:[0,1] neg_hi:[0,1]
	v_exp_f32_e32 v94, v94
	v_exp_f32_e32 v95, v95
	v_pk_add_f32 v[80:81], v[106:107], v[80:81]
	v_exp_f32_e32 v110, v110
	v_exp_f32_e32 v111, v111
	v_pk_add_f32 v[80:81], v[92:93], v[80:81]
	s_nop 0
	v_pk_add_f32 v[80:81], v[108:109], v[80:81]
	s_nop 0
	v_pk_add_f32 v[80:81], v[94:95], v[80:81]
	s_nop 0
	v_pk_add_f32 v[80:81], v[110:111], v[80:81]
	s_nop 0
	v_add_f32_e32 v80, v80, v81
	v_add_f32_e32 v236, v236, v80
	v_cvt_pk_bf16_f32 v80, v14, v15
	v_cvt_pk_bf16_f32 v81, v82, v83
	v_cvt_pk_bf16_f32 v82, v84, v85
	v_cvt_pk_bf16_f32 v83, v86, v87
	v_cvt_pk_bf16_f32 v84, v96, v97
	v_cvt_pk_bf16_f32 v85, v98, v99
	s_waitcnt lgkmcnt(2)
	v_mfma_f32_32x32x16_bf16 v[64:79], v[180:183], v[112:115], v[64:79]
	v_cvt_pk_bf16_f32 v86, v100, v101
	v_cvt_pk_bf16_f32 v87, v102, v103
	v_cvt_pk_bf16_f32 v88, v88, v89
	v_cvt_pk_bf16_f32 v89, v90, v91
	v_cvt_pk_bf16_f32 v90, v92, v93
	v_cvt_pk_bf16_f32 v91, v94, v95
	v_cvt_pk_bf16_f32 v92, v104, v105
	v_cvt_pk_bf16_f32 v93, v106, v107
	v_cvt_pk_bf16_f32 v94, v108, v109
	v_cvt_pk_bf16_f32 v95, v110, v111
	s_waitcnt lgkmcnt(0)
	v_mfma_f32_32x32x16_bf16 v[64:79], v[10:13], v[116:119], v[64:79]
	v_mfma_f32_32x32x16_bf16 v[48:63], v[188:191], v[80:83], v[48:63]
	v_mfma_f32_32x32x16_bf16 v[48:63], v[184:187], v[88:91], v[48:63]
	v_mfma_f32_32x32x16_bf16 v[48:63], v[180:183], v[84:87], v[48:63]
	v_mfma_f32_32x32x16_bf16 v[48:63], v[10:13], v[92:95], v[48:63]
	ds_read_b64_tr_b16 v[10:11], v0 offset:36928
	ds_read_b64_tr_b16 v[12:13], v0 offset:38080
	ds_read_b64_tr_b16 v[96:97], v0 offset:39232
	ds_read_b64_tr_b16 v[98:99], v0 offset:40384
	ds_read_b64_tr_b16 v[100:101], v0 offset:41536
	ds_read_b64_tr_b16 v[102:103], v0 offset:42688
	ds_read_b64_tr_b16 v[104:105], v0 offset:43840
	ds_read_b64_tr_b16 v[106:107], v0 offset:44992
	s_setprio 1
	s_waitcnt lgkmcnt(6)
	v_mfma_f32_32x32x16_bf16 v[32:47], v[10:13], v[120:123], v[32:47]
	v_mfma_f32_32x32x16_bf16 v[16:31], v[10:13], v[80:83], v[16:31]
	s_waitcnt lgkmcnt(4)
	v_mfma_f32_32x32x16_bf16 v[32:47], v[96:99], v[124:127], v[32:47]
	v_mfma_f32_32x32x16_bf16 v[16:31], v[96:99], v[88:91], v[16:31]
	s_waitcnt lgkmcnt(2)
	v_mfma_f32_32x32x16_bf16 v[32:47], v[100:103], v[112:115], v[32:47]
	v_mfma_f32_32x32x16_bf16 v[16:31], v[100:103], v[84:87], v[16:31]
	s_waitcnt lgkmcnt(0)
	v_mfma_f32_32x32x16_bf16 v[32:47], v[104:107], v[116:119], v[32:47]
	v_mfma_f32_32x32x16_bf16 v[16:31], v[104:107], v[92:95], v[16:31]
	s_setprio 0
	s_branch .LBB0_592

; DI unsigned pk2(float lo, float hi) { f32x2 v = {lo, hi}; bf16x2_t b = __builtin_convertvector(v, bf16x2_t); return __builtin_bit_cast(unsigned, b); }
; DI float fast_exp2(float x) { return __builtin_amdgcn_exp2f(x); }
; DI void att_sm_tail(f32x16 (&S)[2], bf16x8 (&pkm)[2][2], const float mrefm, float& lrunm) {
;     {
;         f32x16& s0 = S[0]; f32x16& s1 = S[1];
;         const f32x2 nm2 = {-mrefm, -mrefm};
;         f32x2 acc2 = {0.f, 0.f};
; #pragma unroll
;         for (int i = 0; i < 16; i += 2) {
;             f32x2 a = {s0[i], s0[i + 1]}, b = {s1[i], s1[i + 1]}; a += nm2; b += nm2;
;             a.x = fast_exp2(a.x); a.y = fast_exp2(a.y); b.x = fast_exp2(b.x); b.y = fast_exp2(b.y);
;             acc2 += a; acc2 += b; s0[i] = a.x; s0[i + 1] = a.y; s1[i] = b.x; s1[i + 1] = b.y;
;         }
;         lrunm += acc2.x + acc2.y;
; #pragma unroll
;         for (int s = 0; s < 2; ++s) {
;             u32x4 w0, w1;
;             w0.x = pk2(s0[8 * s + 0], s0[8 * s + 1]); w0.y = pk2(s0[8 * s + 2], s0[8 * s + 3]); w0.z = pk2(s0[8 * s + 4], s0[8 * s + 5]); w0.w = pk2(s0[8 * s + 6], s0[8 * s + 7]);
;             w1.x = pk2(s1[8 * s + 0], s1[8 * s + 1]); w1.y = pk2(s1[8 * s + 2], s1[8 * s + 3]); w1.z = pk2(s1[8 * s + 4], s1[8 * s + 5]); w1.w = pk2(s1[8 * s + 6], s1[8 * s + 7]);
;             pkm[0][s] = __builtin_bit_cast(bf16x8, w0); pkm[1][s] = __builtin_bit_cast(bf16x8, w1);
;         }
;     }
; }
.LBB0_655:
	s_or_b64 exec, exec, s[6:7]
	v_lshl_add_u64 v[6:7], s[0:1], 0, v[152:153]
	v_lshlrev_b64 v[6:7], 9, v[6:7]
	v_lshl_add_u64 v[6:7], v[162:163], 0, v[6:7]
	global_load_dwordx4 v[6:9], v[6:7], off
	s_cmp_ge_u32 s14, s8
	s_cbranch_scc1 .LBB0_659
	s_bitcmp1_b32 s14, 0
	s_cselect_b32 s0, 0x3400, 0
	v_add_u32_e32 v0, s0, v171
	ds_read_b128 v[10:13], v0
	ds_read_b128 v[132:135], v0 offset:32
	ds_read_b128 v[64:67], v0 offset:6656
	ds_read_b128 v[136:139], v0 offset:64
	ds_read_b128 v[140:143], v0 offset:6688
	ds_read_b128 v[174:177], v0 offset:6720
	s_setprio 1
	s_waitcnt lgkmcnt(5)
	v_mfma_f32_32x32x16_bf16 v[48:63], v[10:13], v[104:107], 0
	s_waitcnt lgkmcnt(3)
	v_mfma_f32_32x32x16_bf16 v[64:79], v[64:67], v[104:107], 0
	v_mfma_f32_32x32x16_bf16 v[48:63], v[132:135], v[108:111], v[48:63]
	s_waitcnt lgkmcnt(1)
	v_mfma_f32_32x32x16_bf16 v[64:79], v[140:143], v[108:111], v[64:79]
	v_mfma_f32_32x32x16_bf16 v[48:63], v[136:139], v[112:115], v[48:63]
	s_waitcnt lgkmcnt(0)
	v_mfma_f32_32x32x16_bf16 v[64:79], v[174:177], v[112:115], v[64:79]
	s_setprio 0
	ds_read_b128 v[10:13], v0 offset:96
	ds_read_b128 v[132:135], v0 offset:128
	ds_read_b128 v[136:139], v0 offset:6752
	ds_read_b128 v[140:143], v0 offset:160
	ds_read_b128 v[174:177], v0 offset:6784
	ds_read_b128 v[178:181], v0 offset:6816
	s_setprio 1
	s_waitcnt lgkmcnt(5)
	v_mfma_f32_32x32x16_bf16 v[48:63], v[10:13], v[116:119], v[48:63]
	s_waitcnt lgkmcnt(3)
	v_mfma_f32_32x32x16_bf16 v[64:79], v[136:139], v[116:119], v[64:79]
	v_mfma_f32_32x32x16_bf16 v[48:63], v[132:135], v[120:123], v[48:63]
	s_waitcnt lgkmcnt(1)
	v_mfma_f32_32x32x16_bf16 v[64:79], v[174:177], v[120:123], v[64:79]
	v_mfma_f32_32x32x16_bf16 v[48:63], v[140:143], v[124:127], v[48:63]
	s_waitcnt lgkmcnt(0)
	v_mfma_f32_32x32x16_bf16 v[64:79], v[178:181], v[124:127], v[64:79]
	s_setprio 0
	ds_read_b64_tr_b16 v[136:137], v173 offset:28928
	ds_read_b64_tr_b16 v[138:139], v173 offset:30080
	ds_read_b64_tr_b16 v[132:133], v173 offset:31232
	ds_read_b64_tr_b16 v[134:135], v173 offset:32384
	ds_read_b64_tr_b16 v[140:141], v173 offset:26624
	ds_read_b64_tr_b16 v[142:143], v173 offset:27776
	ds_read_b64_tr_b16 v[10:11], v173 offset:33536
	ds_read_b64_tr_b16 v[12:13], v173 offset:34688
	s_nop 2
	v_pk_add_f32 v[14:15], v[48:49], v[164:165] op_sel_hi:[1,0] neg_lo:[0,1] neg_hi:[0,1]
	v_pk_add_f32 v[48:49], v[64:65], v[164:165] op_sel_hi:[1,0] neg_lo:[0,1] neg_hi:[0,1]
	v_exp_f32_e32 v14, v14
	v_exp_f32_e32 v15, v15
	v_exp_f32_e32 v64, v48
	v_exp_f32_e32 v65, v49
	v_pk_add_f32 v[48:49], v[50:51], v[164:165] op_sel_hi:[1,0] neg_lo:[0,1] neg_hi:[0,1]
	v_pk_add_f32 v[50:51], v[66:67], v[164:165] op_sel_hi:[1,0] neg_lo:[0,1] neg_hi:[0,1]
	v_exp_f32_e32 v66, v48
	v_exp_f32_e32 v67, v49
	v_exp_f32_e32 v174, v50
	v_exp_f32_e32 v175, v51
	v_pk_add_f32 v[50:51], v[52:53], v[164:165] op_sel_hi:[1,0] neg_lo:[0,1] neg_hi:[0,1]
	v_pk_add_f32 v[48:49], v[14:15], 0 op_sel_hi:[1,0]
	v_pk_add_f32 v[52:53], v[68:69], v[164:165] op_sel_hi:[1,0] neg_lo:[0,1] neg_hi:[0,1]
	v_exp_f32_e32 v50, v50
	v_exp_f32_e32 v51, v51
	v_pk_add_f32 v[48:49], v[64:65], v[48:49]
	v_exp_f32_e32 v68, v52
	v_exp_f32_e32 v69, v53
	v_pk_add_f32 v[52:53], v[54:55], v[164:165] op_sel_hi:[1,0] neg_lo:[0,1] neg_hi:[0,1]
	v_pk_add_f32 v[48:49], v[66:67], v[48:49]
	v_pk_add_f32 v[54:55], v[70:71], v[164:165] op_sel_hi:[1,0] neg_lo:[0,1] neg_hi:[0,1]
	v_exp_f32_e32 v52, v52
	v_exp_f32_e32 v53, v53
	v_pk_add_f32 v[48:49], v[174:175], v[48:49]
	v_exp_f32_e32 v70, v54
	v_exp_f32_e32 v71, v55
	v_pk_add_f32 v[54:55], v[56:57], v[164:165] op_sel_hi:[1,0] neg_lo:[0,1] neg_hi:[0,1]
	v_pk_add_f32 v[48:49], v[50:51], v[48:49]
	v_pk_add_f32 v[56:57], v[72:73], v[164:165] op_sel_hi:[1,0] neg_lo:[0,1] neg_hi:[0,1]
	v_exp_f32_e32 v72, v54
	v_exp_f32_e32 v73, v55
	v_pk_add_f32 v[48:49], v[68:69], v[48:49]
	v_exp_f32_e32 v176, v56
	v_exp_f32_e32 v177, v57
	v_pk_add_f32 v[54:55], v[58:59], v[164:165] op_sel_hi:[1,0] neg_lo:[0,1] neg_hi:[0,1]
	v_pk_add_f32 v[48:49], v[52:53], v[48:49]
	v_pk_add_f32 v[56:57], v[74:75], v[164:165] op_sel_hi:[1,0] neg_lo:[0,1] neg_hi:[0,1]
	v_exp_f32_e32 v58, v54
	v_exp_f32_e32 v59, v55
	v_pk_add_f32 v[48:49], v[70:71], v[48:49]
	v_exp_f32_e32 v74, v56
	v_exp_f32_e32 v75, v57
	v_pk_add_f32 v[54:55], v[60:61], v[164:165] op_sel_hi:[1,0] neg_lo:[0,1] neg_hi:[0,1]
	v_pk_add_f32 v[48:49], v[72:73], v[48:49]
	v_pk_add_f32 v[56:57], v[76:77], v[164:165] op_sel_hi:[1,0] neg_lo:[0,1] neg_hi:[0,1]
	v_exp_f32_e32 v60, v54
	v_exp_f32_e32 v61, v55
	v_pk_add_f32 v[48:49], v[176:177], v[48:49]
	v_exp_f32_e32 v76, v56
	v_exp_f32_e32 v77, v57
	v_pk_add_f32 v[54:55], v[62:63], v[164:165] op_sel_hi:[1,0] neg_lo:[0,1] neg_hi:[0,1]
	v_pk_add_f32 v[48:49], v[58:59], v[48:49]
	v_pk_add_f32 v[56:57], v[78:79], v[164:165] op_sel_hi:[1,0] neg_lo:[0,1] neg_hi:[0,1]
	v_exp_f32_e32 v62, v54
	v_exp_f32_e32 v63, v55
	v_pk_add_f32 v[48:49], v[74:75], v[48:49]
	v_exp_f32_e32 v78, v56
	v_exp_f32_e32 v79, v57
	v_pk_add_f32 v[48:49], v[60:61], v[48:49]
	v_cvt_pk_bf16_f32 v50, v50, v51
	v_pk_add_f32 v[48:49], v[76:77], v[48:49]
	v_cvt_pk_bf16_f32 v51, v52, v53
	v_pk_add_f32 v[48:49], v[62:63], v[48:49]
	v_cvt_pk_bf16_f32 v52, v64, v65
	v_pk_add_f32 v[48:49], v[78:79], v[48:49]
	v_cvt_pk_bf16_f32 v53, v174, v175
	v_add_f32_e32 v0, v48, v49
	v_cmp_nge_f32_e32 vcc, 0x43800000, v0
	s_cbranch_vccnz .LA_slow0
	v_add_f32_e32 v172, v172, v0
	v_cvt_pk_bf16_f32 v48, v14, v15
	v_cvt_pk_bf16_f32 v49, v66, v67
	v_cvt_pk_bf16_f32 v54, v68, v69
	v_cvt_pk_bf16_f32 v55, v70, v71
	v_cvt_pk_bf16_f32 v56, v72, v73
	v_cvt_pk_bf16_f32 v57, v58, v59
	v_cvt_pk_bf16_f32 v58, v60, v61
	v_cvt_pk_bf16_f32 v59, v62, v63
	v_cvt_pk_bf16_f32 v60, v176, v177
	v_cvt_pk_bf16_f32 v61, v74, v75
	v_cvt_pk_bf16_f32 v62, v76, v77
	v_cvt_pk_bf16_f32 v63, v78, v79
	s_setprio 1
	s_waitcnt lgkmcnt(2)
	v_mfma_f32_32x32x16_bf16 v[32:47], v[140:143], v[48:51], v[32:47]
	v_mfma_f32_32x32x16_bf16 v[32:47], v[136:139], v[56:59], v[32:47]
	v_mfma_f32_32x32x16_bf16 v[32:47], v[132:135], v[52:55], v[32:47]
	s_waitcnt lgkmcnt(0)
	v_mfma_f32_32x32x16_bf16 v[32:47], v[10:13], v[60:63], v[32:47]
	s_setprio 0
	ds_read_b64_tr_b16 v[10:11], v173 offset:28992
	ds_read_b64_tr_b16 v[12:13], v173 offset:30144
	ds_read_b64_tr_b16 v[64:65], v173 offset:31296
	ds_read_b64_tr_b16 v[66:67], v173 offset:32448
	ds_read_b64_tr_b16 v[68:69], v173 offset:26688
	ds_read_b64_tr_b16 v[70:71], v173 offset:27840
	ds_read_b64_tr_b16 v[72:73], v173 offset:33600
	ds_read_b64_tr_b16 v[74:75], v173 offset:34752
	s_setprio 1
	s_waitcnt lgkmcnt(2)
	v_mfma_f32_32x32x16_bf16 v[16:31], v[68:71], v[48:51], v[16:31]
	v_mfma_f32_32x32x16_bf16 v[16:31], v[10:13], v[56:59], v[16:31]
	v_mfma_f32_32x32x16_bf16 v[16:31], v[64:67], v[52:55], v[16:31]
	s_waitcnt lgkmcnt(0)
	v_mfma_f32_32x32x16_bf16 v[16:31], v[72:75], v[60:63], v[16:31]
	s_setprio 0

; DI unsigned pk2(float lo, float hi) { f32x2 v = {lo, hi}; bf16x2_t b = __builtin_convertvector(v, bf16x2_t); return __builtin_bit_cast(unsigned, b); }
; DI float fast_exp2(float x) { return __builtin_amdgcn_exp2f(x); }
; DI void att_sm_tail(f32x16 (&S)[2], bf16x8 (&pkm)[2][2], const float mrefm, float& lrunm) {
;     {
;         f32x16& s0 = S[0]; f32x16& s1 = S[1];
;         const f32x2 nm2 = {-mrefm, -mrefm};
;         f32x2 acc2 = {0.f, 0.f};
; #pragma unroll
;         for (int i = 0; i < 16; i += 2) {
;             f32x2 a = {s0[i], s0[i + 1]}, b = {s1[i], s1[i + 1]}; a += nm2; b += nm2;
;             a.x = fast_exp2(a.x); a.y = fast_exp2(a.y); b.x = fast_exp2(b.x); b.y = fast_exp2(b.y);
;             acc2 += a; acc2 += b; s0[i] = a.x; s0[i + 1] = a.y; s1[i] = b.x; s1[i + 1] = b.y;
;         }
;         lrunm += acc2.x + acc2.y;
; #pragma unroll
;         for (int s = 0; s < 2; ++s) {
;             u32x4 w0, w1;
;             w0.x = pk2(s0[8 * s + 0], s0[8 * s + 1]); w0.y = pk2(s0[8 * s + 2], s0[8 * s + 3]); w0.z = pk2(s0[8 * s + 4], s0[8 * s + 5]); w0.w = pk2(s0[8 * s + 6], s0[8 * s + 7]);
;             w1.x = pk2(s1[8 * s + 0], s1[8 * s + 1]); w1.y = pk2(s1[8 * s + 2], s1[8 * s + 3]); w1.z = pk2(s1[8 * s + 4], s1[8 * s + 5]); w1.w = pk2(s1[8 * s + 6], s1[8 * s + 7]);
;             pkm[0][s] = __builtin_bit_cast(bf16x8, w0); pkm[1][s] = __builtin_bit_cast(bf16x8, w1);
;         }
;     }
; }
.LBB0_663:
	s_or_b64 exec, exec, s[6:7]
	v_lshl_add_u64 v[10:11], s[0:1], 0, v[152:153]
	v_lshlrev_b64 v[10:11], 9, v[10:11]
	v_lshl_add_u64 v[10:11], v[162:163], 0, v[10:11]
	global_load_dwordx4 v[100:103], v[10:11], off
	s_cmp_ge_u32 s3, s8
	s_cbranch_scc1 .LBB0_667
	v_add3_u32 v0, s16, v170, v156
	ds_read_b128 v[10:13], v0
	ds_read_b128 v[132:135], v0 offset:32
	ds_read_b128 v[64:67], v0 offset:6656
	ds_read_b128 v[136:139], v0 offset:64
	ds_read_b128 v[140:143], v0 offset:6688
	ds_read_b128 v[174:177], v0 offset:6720
	s_setprio 1
	s_waitcnt lgkmcnt(5)
	v_mfma_f32_32x32x16_bf16 v[48:63], v[10:13], v[104:107], 0
	s_waitcnt lgkmcnt(3)
	v_mfma_f32_32x32x16_bf16 v[64:79], v[64:67], v[104:107], 0
	v_mfma_f32_32x32x16_bf16 v[48:63], v[132:135], v[108:111], v[48:63]
	s_waitcnt lgkmcnt(1)
	v_mfma_f32_32x32x16_bf16 v[64:79], v[140:143], v[108:111], v[64:79]
	v_mfma_f32_32x32x16_bf16 v[48:63], v[136:139], v[112:115], v[48:63]
	s_waitcnt lgkmcnt(0)
	v_mfma_f32_32x32x16_bf16 v[64:79], v[174:177], v[112:115], v[64:79]
	s_setprio 0
	ds_read_b128 v[10:13], v0 offset:96
	ds_read_b128 v[132:135], v0 offset:128
	ds_read_b128 v[136:139], v0 offset:6752
	ds_read_b128 v[140:143], v0 offset:160
	ds_read_b128 v[174:177], v0 offset:6784
	ds_read_b128 v[178:181], v0 offset:6816
	s_setprio 1
	s_waitcnt lgkmcnt(5)
	v_mfma_f32_32x32x16_bf16 v[48:63], v[10:13], v[116:119], v[48:63]
	s_waitcnt lgkmcnt(3)
	v_mfma_f32_32x32x16_bf16 v[64:79], v[136:139], v[116:119], v[64:79]
	v_mfma_f32_32x32x16_bf16 v[48:63], v[132:135], v[120:123], v[48:63]
	s_waitcnt lgkmcnt(1)
	v_mfma_f32_32x32x16_bf16 v[64:79], v[174:177], v[120:123], v[64:79]
	v_mfma_f32_32x32x16_bf16 v[48:63], v[140:143], v[124:127], v[48:63]
	s_waitcnt lgkmcnt(0)
	v_mfma_f32_32x32x16_bf16 v[64:79], v[178:181], v[124:127], v[64:79]
	s_setprio 0
	ds_read_b64_tr_b16 v[140:141], v173 offset:35840
	ds_read_b64_tr_b16 v[142:143], v173 offset:36992
	ds_read_b64_tr_b16 v[136:137], v173 offset:38144
	ds_read_b64_tr_b16 v[138:139], v173 offset:39296
	ds_read_b64_tr_b16 v[132:133], v173 offset:40448
	ds_read_b64_tr_b16 v[134:135], v173 offset:41600
	ds_read_b64_tr_b16 v[10:11], v173 offset:42752
	ds_read_b64_tr_b16 v[12:13], v173 offset:43904
	s_nop 2
	v_pk_add_f32 v[14:15], v[48:49], v[164:165] op_sel_hi:[1,0] neg_lo:[0,1] neg_hi:[0,1]
	v_pk_add_f32 v[48:49], v[64:65], v[164:165] op_sel_hi:[1,0] neg_lo:[0,1] neg_hi:[0,1]
	v_exp_f32_e32 v14, v14
	v_exp_f32_e32 v15, v15
	v_exp_f32_e32 v64, v48
	v_exp_f32_e32 v65, v49
	v_pk_add_f32 v[48:49], v[50:51], v[164:165] op_sel_hi:[1,0] neg_lo:[0,1] neg_hi:[0,1]
	v_pk_add_f32 v[50:51], v[66:67], v[164:165] op_sel_hi:[1,0] neg_lo:[0,1] neg_hi:[0,1]
	v_exp_f32_e32 v66, v48
	v_exp_f32_e32 v67, v49
	v_exp_f32_e32 v174, v50
	v_exp_f32_e32 v175, v51
	v_pk_add_f32 v[50:51], v[52:53], v[164:165] op_sel_hi:[1,0] neg_lo:[0,1] neg_hi:[0,1]
	v_pk_add_f32 v[48:49], v[14:15], 0 op_sel_hi:[1,0]
	v_pk_add_f32 v[52:53], v[68:69], v[164:165] op_sel_hi:[1,0] neg_lo:[0,1] neg_hi:[0,1]
	v_exp_f32_e32 v50, v50
	v_exp_f32_e32 v51, v51
	v_pk_add_f32 v[48:49], v[64:65], v[48:49]
	v_exp_f32_e32 v68, v52
	v_exp_f32_e32 v69, v53
	v_pk_add_f32 v[52:53], v[54:55], v[164:165] op_sel_hi:[1,0] neg_lo:[0,1] neg_hi:[0,1]
	v_pk_add_f32 v[48:49], v[66:67], v[48:49]
	v_pk_add_f32 v[54:55], v[70:71], v[164:165] op_sel_hi:[1,0] neg_lo:[0,1] neg_hi:[0,1]
	v_exp_f32_e32 v52, v52
	v_exp_f32_e32 v53, v53
	v_pk_add_f32 v[48:49], v[174:175], v[48:49]
	v_exp_f32_e32 v70, v54
	v_exp_f32_e32 v71, v55
	v_pk_add_f32 v[54:55], v[56:57], v[164:165] op_sel_hi:[1,0] neg_lo:[0,1] neg_hi:[0,1]
	v_pk_add_f32 v[48:49], v[50:51], v[48:49]
	v_pk_add_f32 v[56:57], v[72:73], v[164:165] op_sel_hi:[1,0] neg_lo:[0,1] neg_hi:[0,1]
	v_exp_f32_e32 v72, v54
	v_exp_f32_e32 v73, v55
	v_pk_add_f32 v[48:49], v[68:69], v[48:49]
	v_exp_f32_e32 v176, v56
	v_exp_f32_e32 v177, v57
	v_pk_add_f32 v[54:55], v[58:59], v[164:165] op_sel_hi:[1,0] neg_lo:[0,1] neg_hi:[0,1]
	v_pk_add_f32 v[48:49], v[52:53], v[48:49]
	v_pk_add_f32 v[56:57], v[74:75], v[164:165] op_sel_hi:[1,0] neg_lo:[0,1] neg_hi:[0,1]
	v_exp_f32_e32 v58, v54
	v_exp_f32_e32 v59, v55
	v_pk_add_f32 v[48:49], v[70:71], v[48:49]
	v_exp_f32_e32 v74, v56
	v_exp_f32_e32 v75, v57
	v_pk_add_f32 v[54:55], v[60:61], v[164:165] op_sel_hi:[1,0] neg_lo:[0,1] neg_hi:[0,1]
	v_pk_add_f32 v[48:49], v[72:73], v[48:49]
	v_pk_add_f32 v[56:57], v[76:77], v[164:165] op_sel_hi:[1,0] neg_lo:[0,1] neg_hi:[0,1]
	v_exp_f32_e32 v60, v54
	v_exp_f32_e32 v61, v55
	v_pk_add_f32 v[48:49], v[176:177], v[48:49]
	v_exp_f32_e32 v76, v56
	v_exp_f32_e32 v77, v57
	v_pk_add_f32 v[54:55], v[62:63], v[164:165] op_sel_hi:[1,0] neg_lo:[0,1] neg_hi:[0,1]
	v_pk_add_f32 v[48:49], v[58:59], v[48:49]
	v_pk_add_f32 v[56:57], v[78:79], v[164:165] op_sel_hi:[1,0] neg_lo:[0,1] neg_hi:[0,1]
	v_exp_f32_e32 v62, v54
	v_exp_f32_e32 v63, v55
	v_pk_add_f32 v[48:49], v[74:75], v[48:49]
	v_exp_f32_e32 v78, v56
	v_exp_f32_e32 v79, v57
	v_pk_add_f32 v[48:49], v[60:61], v[48:49]
	v_cvt_pk_bf16_f32 v50, v50, v51
	v_pk_add_f32 v[48:49], v[76:77], v[48:49]
	v_cvt_pk_bf16_f32 v51, v52, v53
	v_pk_add_f32 v[48:49], v[62:63], v[48:49]
	v_cvt_pk_bf16_f32 v52, v64, v65
	v_pk_add_f32 v[48:49], v[78:79], v[48:49]
	v_cvt_pk_bf16_f32 v53, v174, v175
	v_add_f32_e32 v0, v48, v49
	v_cmp_nge_f32_e32 vcc, 0x43800000, v0
	s_cbranch_vccnz .LA_slow1
	v_add_f32_e32 v172, v172, v0
	v_cvt_pk_bf16_f32 v48, v14, v15
	v_cvt_pk_bf16_f32 v49, v66, v67
	v_cvt_pk_bf16_f32 v54, v68, v69
	v_cvt_pk_bf16_f32 v55, v70, v71
	v_cvt_pk_bf16_f32 v56, v72, v73
	v_cvt_pk_bf16_f32 v57, v58, v59
	v_cvt_pk_bf16_f32 v58, v60, v61
	v_cvt_pk_bf16_f32 v59, v62, v63
	v_cvt_pk_bf16_f32 v60, v176, v177
	v_cvt_pk_bf16_f32 v61, v74, v75
	v_cvt_pk_bf16_f32 v62, v76, v77
	v_cvt_pk_bf16_f32 v63, v78, v79
	s_setprio 1
	s_waitcnt lgkmcnt(6)
	v_mfma_f32_32x32x16_bf16 v[32:47], v[140:143], v[48:51], v[32:47]
	s_waitcnt lgkmcnt(4)
	v_mfma_f32_32x32x16_bf16 v[32:47], v[136:139], v[56:59], v[32:47]
	s_waitcnt lgkmcnt(2)
	v_mfma_f32_32x32x16_bf16 v[32:47], v[132:135], v[52:55], v[32:47]
	s_waitcnt lgkmcnt(0)
	v_mfma_f32_32x32x16_bf16 v[32:47], v[10:13], v[60:63], v[32:47]
	s_setprio 0
	ds_read_b64_tr_b16 v[10:11], v173 offset:35904
	ds_read_b64_tr_b16 v[12:13], v173 offset:37056
	ds_read_b64_tr_b16 v[64:65], v173 offset:38208
	ds_read_b64_tr_b16 v[66:67], v173 offset:39360
	ds_read_b64_tr_b16 v[68:69], v173 offset:40512
	ds_read_b64_tr_b16 v[70:71], v173 offset:41664
	ds_read_b64_tr_b16 v[72:73], v173 offset:42816
	ds_read_b64_tr_b16 v[74:75], v173 offset:43968
	s_setprio 1
	s_waitcnt lgkmcnt(6)
	v_mfma_f32_32x32x16_bf16 v[16:31], v[10:13], v[48:51], v[16:31]
	s_waitcnt lgkmcnt(4)
	v_mfma_f32_32x32x16_bf16 v[16:31], v[64:67], v[56:59], v[16:31]
	s_waitcnt lgkmcnt(2)
	v_mfma_f32_32x32x16_bf16 v[16:31], v[68:71], v[52:55], v[16:31]
	s_waitcnt lgkmcnt(0)
	v_mfma_f32_32x32x16_bf16 v[16:31], v[72:75], v[60:63], v[16:31]
	s_setprio 0

; DI unsigned pk2(float lo, float hi) { f32x2 v = {lo, hi}; bf16x2_t b = __builtin_convertvector(v, bf16x2_t); return __builtin_bit_cast(unsigned, b); }
; DI float fast_exp2(float x) { return __builtin_amdgcn_exp2f(x); }
; DI void att_sm_tail(f32x16 (&S)[2], bf16x8 (&pkm)[2][2], const float mrefm, float& lrunm) {
;     {
;         f32x16& s0 = S[0]; f32x16& s1 = S[1];
;         const f32x2 nm2 = {-mrefm, -mrefm};
;         f32x2 acc2 = {0.f, 0.f};
; #pragma unroll
;         for (int i = 0; i < 16; i += 2) {
;             f32x2 a = {s0[i], s0[i + 1]}, b = {s1[i], s1[i + 1]}; a += nm2; b += nm2;
;             a.x = fast_exp2(a.x); a.y = fast_exp2(a.y); b.x = fast_exp2(b.x); b.y = fast_exp2(b.y);
;             acc2 += a; acc2 += b; s0[i] = a.x; s0[i + 1] = a.y; s1[i] = b.x; s1[i + 1] = b.y;
;         }
;         lrunm += acc2.x + acc2.y;
; #pragma unroll
;         for (int s = 0; s < 2; ++s) {
;             u32x4 w0, w1;
;             w0.x = pk2(s0[8 * s + 0], s0[8 * s + 1]); w0.y = pk2(s0[8 * s + 2], s0[8 * s + 3]); w0.z = pk2(s0[8 * s + 4], s0[8 * s + 5]); w0.w = pk2(s0[8 * s + 6], s0[8 * s + 7]);
;             w1.x = pk2(s1[8 * s + 0], s1[8 * s + 1]); w1.y = pk2(s1[8 * s + 2], s1[8 * s + 3]); w1.z = pk2(s1[8 * s + 4], s1[8 * s + 5]); w1.w = pk2(s1[8 * s + 6], s1[8 * s + 7]);
;             pkm[0][s] = __builtin_bit_cast(bf16x8, w0); pkm[1][s] = __builtin_bit_cast(bf16x8, w1);
;         }
;     }
; }
.LBB0_671:
	s_or_b64 exec, exec, s[6:7]
	v_lshl_add_u64 v[10:11], s[0:1], 0, v[152:153]
	v_lshlrev_b64 v[10:11], 9, v[10:11]
	v_lshl_add_u64 v[10:11], v[162:163], 0, v[10:11]
	global_load_dwordx4 v[128:131], v[10:11], off
	s_cmp_ge_u32 s14, s11
	s_cbranch_scc1 .LBB0_675
	v_add3_u32 v0, s3, v170, v156
	ds_read_b128 v[10:13], v0
	ds_read_b128 v[132:135], v0 offset:32
	ds_read_b128 v[64:67], v0 offset:6656
	ds_read_b128 v[136:139], v0 offset:64
	ds_read_b128 v[140:143], v0 offset:6688
	ds_read_b128 v[174:177], v0 offset:6720
	s_setprio 1
	s_waitcnt lgkmcnt(5)
	v_mfma_f32_32x32x16_bf16 v[48:63], v[10:13], v[104:107], 0
	s_waitcnt lgkmcnt(3)
	v_mfma_f32_32x32x16_bf16 v[64:79], v[64:67], v[104:107], 0
	v_mfma_f32_32x32x16_bf16 v[48:63], v[132:135], v[108:111], v[48:63]
	s_waitcnt lgkmcnt(1)
	v_mfma_f32_32x32x16_bf16 v[64:79], v[140:143], v[108:111], v[64:79]
	v_mfma_f32_32x32x16_bf16 v[48:63], v[136:139], v[112:115], v[48:63]
	s_waitcnt lgkmcnt(0)
	v_mfma_f32_32x32x16_bf16 v[64:79], v[174:177], v[112:115], v[64:79]
	s_setprio 0
	ds_read_b128 v[10:13], v0 offset:96
	ds_read_b128 v[132:135], v0 offset:128
	ds_read_b128 v[136:139], v0 offset:6752
	ds_read_b128 v[140:143], v0 offset:160
	ds_read_b128 v[174:177], v0 offset:6784
	ds_read_b128 v[178:181], v0 offset:6816
	s_setprio 1
	s_waitcnt lgkmcnt(5)
	v_mfma_f32_32x32x16_bf16 v[48:63], v[10:13], v[116:119], v[48:63]
	s_waitcnt lgkmcnt(3)
	v_mfma_f32_32x32x16_bf16 v[64:79], v[136:139], v[116:119], v[64:79]
	v_mfma_f32_32x32x16_bf16 v[48:63], v[132:135], v[120:123], v[48:63]
	s_waitcnt lgkmcnt(1)
	v_mfma_f32_32x32x16_bf16 v[64:79], v[174:177], v[120:123], v[64:79]
	v_mfma_f32_32x32x16_bf16 v[48:63], v[140:143], v[124:127], v[48:63]
	s_waitcnt lgkmcnt(0)
	v_mfma_f32_32x32x16_bf16 v[64:79], v[178:181], v[124:127], v[64:79]
	s_setprio 0
	ds_read_b64_tr_b16 v[140:141], v173 offset:45056
	ds_read_b64_tr_b16 v[142:143], v173 offset:46208
	ds_read_b64_tr_b16 v[136:137], v173 offset:47360
	ds_read_b64_tr_b16 v[138:139], v173 offset:48512
	ds_read_b64_tr_b16 v[132:133], v173 offset:49664
	ds_read_b64_tr_b16 v[134:135], v173 offset:50816
	ds_read_b64_tr_b16 v[10:11], v173 offset:51968
	ds_read_b64_tr_b16 v[12:13], v173 offset:53120
	s_nop 2
	v_pk_add_f32 v[14:15], v[48:49], v[164:165] op_sel_hi:[1,0] neg_lo:[0,1] neg_hi:[0,1]
	v_pk_add_f32 v[48:49], v[64:65], v[164:165] op_sel_hi:[1,0] neg_lo:[0,1] neg_hi:[0,1]
	v_exp_f32_e32 v14, v14
	v_exp_f32_e32 v15, v15
	v_exp_f32_e32 v64, v48
	v_exp_f32_e32 v65, v49
	v_pk_add_f32 v[48:49], v[50:51], v[164:165] op_sel_hi:[1,0] neg_lo:[0,1] neg_hi:[0,1]
	v_pk_add_f32 v[50:51], v[66:67], v[164:165] op_sel_hi:[1,0] neg_lo:[0,1] neg_hi:[0,1]
	v_exp_f32_e32 v66, v48
	v_exp_f32_e32 v67, v49
	v_exp_f32_e32 v174, v50
	v_exp_f32_e32 v175, v51
	v_pk_add_f32 v[50:51], v[52:53], v[164:165] op_sel_hi:[1,0] neg_lo:[0,1] neg_hi:[0,1]
	v_pk_add_f32 v[48:49], v[14:15], 0 op_sel_hi:[1,0]
	v_pk_add_f32 v[52:53], v[68:69], v[164:165] op_sel_hi:[1,0] neg_lo:[0,1] neg_hi:[0,1]
	v_exp_f32_e32 v50, v50
	v_exp_f32_e32 v51, v51
	v_pk_add_f32 v[48:49], v[64:65], v[48:49]
	v_exp_f32_e32 v68, v52
	v_exp_f32_e32 v69, v53
	v_pk_add_f32 v[52:53], v[54:55], v[164:165] op_sel_hi:[1,0] neg_lo:[0,1] neg_hi:[0,1]
	v_pk_add_f32 v[48:49], v[66:67], v[48:49]
	v_pk_add_f32 v[54:55], v[70:71], v[164:165] op_sel_hi:[1,0] neg_lo:[0,1] neg_hi:[0,1]
	v_exp_f32_e32 v52, v52
	v_exp_f32_e32 v53, v53
	v_pk_add_f32 v[48:49], v[174:175], v[48:49]
	v_exp_f32_e32 v70, v54
	v_exp_f32_e32 v71, v55
	v_pk_add_f32 v[54:55], v[56:57], v[164:165] op_sel_hi:[1,0] neg_lo:[0,1] neg_hi:[0,1]
	v_pk_add_f32 v[48:49], v[50:51], v[48:49]
	v_pk_add_f32 v[56:57], v[72:73], v[164:165] op_sel_hi:[1,0] neg_lo:[0,1] neg_hi:[0,1]
	v_exp_f32_e32 v72, v54
	v_exp_f32_e32 v73, v55
	v_pk_add_f32 v[48:49], v[68:69], v[48:49]
	v_exp_f32_e32 v176, v56
	v_exp_f32_e32 v177, v57
	v_pk_add_f32 v[54:55], v[58:59], v[164:165] op_sel_hi:[1,0] neg_lo:[0,1] neg_hi:[0,1]
	v_pk_add_f32 v[48:49], v[52:53], v[48:49]
	v_pk_add_f32 v[56:57], v[74:75], v[164:165] op_sel_hi:[1,0] neg_lo:[0,1] neg_hi:[0,1]
	v_exp_f32_e32 v58, v54
	v_exp_f32_e32 v59, v55
	v_pk_add_f32 v[48:49], v[70:71], v[48:49]
	v_exp_f32_e32 v74, v56
	v_exp_f32_e32 v75, v57
	v_pk_add_f32 v[54:55], v[60:61], v[164:165] op_sel_hi:[1,0] neg_lo:[0,1] neg_hi:[0,1]
	v_pk_add_f32 v[48:49], v[72:73], v[48:49]
	v_pk_add_f32 v[56:57], v[76:77], v[164:165] op_sel_hi:[1,0] neg_lo:[0,1] neg_hi:[0,1]
	v_exp_f32_e32 v60, v54
	v_exp_f32_e32 v61, v55
	v_pk_add_f32 v[48:49], v[176:177], v[48:49]
	v_exp_f32_e32 v76, v56
	v_exp_f32_e32 v77, v57
	v_pk_add_f32 v[54:55], v[62:63], v[164:165] op_sel_hi:[1,0] neg_lo:[0,1] neg_hi:[0,1]
	v_pk_add_f32 v[48:49], v[58:59], v[48:49]
	v_pk_add_f32 v[56:57], v[78:79], v[164:165] op_sel_hi:[1,0] neg_lo:[0,1] neg_hi:[0,1]
	v_exp_f32_e32 v62, v54
	v_exp_f32_e32 v63, v55
	v_pk_add_f32 v[48:49], v[74:75], v[48:49]
	v_exp_f32_e32 v78, v56
	v_exp_f32_e32 v79, v57
	v_pk_add_f32 v[48:49], v[60:61], v[48:49]
	v_cvt_pk_bf16_f32 v50, v50, v51
	v_pk_add_f32 v[48:49], v[76:77], v[48:49]
	v_cvt_pk_bf16_f32 v51, v52, v53
	v_pk_add_f32 v[48:49], v[62:63], v[48:49]
	v_cvt_pk_bf16_f32 v52, v64, v65
	v_pk_add_f32 v[48:49], v[78:79], v[48:49]
	v_cvt_pk_bf16_f32 v53, v174, v175
	v_add_f32_e32 v0, v48, v49
	v_cmp_nge_f32_e32 vcc, 0x43800000, v0
	s_cbranch_vccnz .LA_slow2
	v_add_f32_e32 v172, v172, v0
	v_cvt_pk_bf16_f32 v48, v14, v15
	v_cvt_pk_bf16_f32 v49, v66, v67
	v_cvt_pk_bf16_f32 v54, v68, v69
	v_cvt_pk_bf16_f32 v55, v70, v71
	v_cvt_pk_bf16_f32 v56, v72, v73
	v_cvt_pk_bf16_f32 v57, v58, v59
	v_cvt_pk_bf16_f32 v58, v60, v61
	v_cvt_pk_bf16_f32 v59, v62, v63
	v_cvt_pk_bf16_f32 v60, v176, v177
	v_cvt_pk_bf16_f32 v61, v74, v75
	v_cvt_pk_bf16_f32 v62, v76, v77
	v_cvt_pk_bf16_f32 v63, v78, v79
	s_setprio 1
	s_waitcnt lgkmcnt(6)
	v_mfma_f32_32x32x16_bf16 v[32:47], v[140:143], v[48:51], v[32:47]
	s_waitcnt lgkmcnt(4)
	v_mfma_f32_32x32x16_bf16 v[32:47], v[136:139], v[56:59], v[32:47]
	s_waitcnt lgkmcnt(2)
	v_mfma_f32_32x32x16_bf16 v[32:47], v[132:135], v[52:55], v[32:47]
	s_waitcnt lgkmcnt(0)
	v_mfma_f32_32x32x16_bf16 v[32:47], v[10:13], v[60:63], v[32:47]
	s_setprio 0
	ds_read_b64_tr_b16 v[10:11], v173 offset:45120
	ds_read_b64_tr_b16 v[12:13], v173 offset:46272
	ds_read_b64_tr_b16 v[64:65], v173 offset:47424
	ds_read_b64_tr_b16 v[66:67], v173 offset:48576
	ds_read_b64_tr_b16 v[68:69], v173 offset:49728
	ds_read_b64_tr_b16 v[70:71], v173 offset:50880
	ds_read_b64_tr_b16 v[72:73], v173 offset:52032
	ds_read_b64_tr_b16 v[74:75], v173 offset:53184
	s_setprio 1
	s_waitcnt lgkmcnt(6)
	v_mfma_f32_32x32x16_bf16 v[16:31], v[10:13], v[48:51], v[16:31]
	s_waitcnt lgkmcnt(4)
	v_mfma_f32_32x32x16_bf16 v[16:31], v[64:67], v[56:59], v[16:31]
	s_waitcnt lgkmcnt(2)
	v_mfma_f32_32x32x16_bf16 v[16:31], v[68:71], v[52:55], v[16:31]
	s_waitcnt lgkmcnt(0)
	v_mfma_f32_32x32x16_bf16 v[16:31], v[72:75], v[60:63], v[16:31]
	s_setprio 0

; template <int MODE>
; DI void att_sm_head(f32x16 (&S)[2], float& mrefm, float& lrunm, f32x16 (&om)[2], bool latent, const MaskP& mk, int h) {
;     {
;         f32x16& s0 = S[0]; f32x16& s1 = S[1];
;         if (MODE == 1 && latent) {
;             const LAS float* rl = mk.rpbl + (mk.lt - mk.qrow + 7) * 31 + (15 - mk.qcol);
; #pragma unroll
;             for (int i = 0; i < 16; ++i) { const int kc = crow(i, h);
;                 { const bool ok = (kc >= mk.cs) && (kc < mk.cs + 16); const float bz = rl[ok ? kc : mk.qcol]; s0[i] = ok ? s0[i] + bz : -1e30f; }
;                 { const int kc2 = kc + 32; const bool ok = (kc2 >= mk.cs) && (kc2 < mk.cs + 16); const float bz = rl[ok ? kc2 : mk.qcol]; s1[i] = ok ? s1[i] + bz : -1e30f; } }
;         }
;         if (MODE == 2 && latent) {
;             const int kb = 64 * mk.lt;
; #pragma unroll
;             for (int i = 0; i < 16; ++i) { const int d0 = kb + crow(i, h) - mk.qpos, d1 = d0 + 32;
;                 if (d0 > 128 || d0 < -128) s0[i] = -1e30f; if (d1 > 128 || d1 < -128) s1[i] = -1e30f; }
;         }
;         float ma = fmaxf(fmaxf(s0[0], s0[1]), s0[2]), mb = fmaxf(fmaxf(s1[0], s1[1]), s1[2]);
; #pragma unroll
;         for (int i = 3; i < 15; i += 2) { ma = fmaxf(fmaxf(ma, s0[i]), s0[i + 1]); mb = fmaxf(fmaxf(mb, s1[i]), s1[i + 1]); }
;         ma = fmaxf(fmaxf(ma, s0[15]), fmaxf(mb, s1[15]));
;         { auto rr = __builtin_amdgcn_permlane32_swap(__float_as_uint(ma), __float_as_uint(ma), false, false); ma = fmaxf(__uint_as_float(rr[0]), __uint_as_float(rr[1])); }
;         const bool uninit = mrefm < -1e29f;
;         const bool need = uninit || (ma - mrefm > 8.0f);
;         if (__any(need)) {
;             const float mnew = need ? ma : mrefm;
;             const float f = uninit ? 1.0f : fast_exp2(mrefm - mnew);
;             mrefm = mnew; lrunm *= f;
; #pragma unroll
;             for (int e = 0; e < 2; ++e)
; #pragma unroll
;                 for (int i = 0; i < 16; ++i) om[e][i] *= f;
;         }
;     }
; }
; DI void att_sm_tail(f32x16 (&S)[2], bf16x8 (&pkm)[2][2], const float mrefm, float& lrunm) {
;     {
;         f32x16& s0 = S[0]; f32x16& s1 = S[1];
;         const f32x2 nm2 = {-mrefm, -mrefm};
;         f32x2 acc2 = {0.f, 0.f};
; #pragma unroll
;         for (int i = 0; i < 16; i += 2) {
;             f32x2 a = {s0[i], s0[i + 1]}, b = {s1[i], s1[i + 1]}; a += nm2; b += nm2;
.LA_slow0:
	s_bitcmp1_b32 s14, 0
	s_cselect_b32 s0, 0x3400, 0
	v_add_u32_e32 v0, s0, v171
	ds_read_b128 v[10:13], v0
	ds_read_b128 v[132:135], v0 offset:32
	ds_read_b128 v[64:67], v0 offset:6656
	ds_read_b128 v[136:139], v0 offset:64
	ds_read_b128 v[140:143], v0 offset:6688
	ds_read_b128 v[174:177], v0 offset:6720
	s_setprio 1
	s_waitcnt lgkmcnt(5)
	v_mfma_f32_32x32x16_bf16 v[48:63], v[10:13], v[104:107], 0
	s_waitcnt lgkmcnt(3)
	v_mfma_f32_32x32x16_bf16 v[64:79], v[64:67], v[104:107], 0
	v_mfma_f32_32x32x16_bf16 v[48:63], v[132:135], v[108:111], v[48:63]
	s_waitcnt lgkmcnt(1)
	v_mfma_f32_32x32x16_bf16 v[64:79], v[140:143], v[108:111], v[64:79]
	v_mfma_f32_32x32x16_bf16 v[48:63], v[136:139], v[112:115], v[48:63]
	s_waitcnt lgkmcnt(0)
	v_mfma_f32_32x32x16_bf16 v[64:79], v[174:177], v[112:115], v[64:79]
	s_setprio 0
	ds_read_b128 v[10:13], v0 offset:96
	ds_read_b128 v[132:135], v0 offset:128
	ds_read_b128 v[136:139], v0 offset:6752
	ds_read_b128 v[140:143], v0 offset:160
	ds_read_b128 v[174:177], v0 offset:6784
	ds_read_b128 v[178:181], v0 offset:6816
	s_setprio 1
	s_waitcnt lgkmcnt(5)
	v_mfma_f32_32x32x16_bf16 v[48:63], v[10:13], v[116:119], v[48:63]
	s_waitcnt lgkmcnt(3)
	v_mfma_f32_32x32x16_bf16 v[64:79], v[136:139], v[116:119], v[64:79]
	v_mfma_f32_32x32x16_bf16 v[48:63], v[132:135], v[120:123], v[48:63]
	s_waitcnt lgkmcnt(1)
	v_mfma_f32_32x32x16_bf16 v[64:79], v[174:177], v[120:123], v[64:79]
	v_mfma_f32_32x32x16_bf16 v[48:63], v[140:143], v[124:127], v[48:63]
	s_waitcnt lgkmcnt(0)
	v_mfma_f32_32x32x16_bf16 v[64:79], v[178:181], v[124:127], v[64:79]
	s_setprio 0
	ds_read_b64_tr_b16 v[136:137], v173 offset:28928
	ds_read_b64_tr_b16 v[138:139], v173 offset:30080
	ds_read_b64_tr_b16 v[132:133], v173 offset:31232
	ds_read_b64_tr_b16 v[134:135], v173 offset:32384
	ds_read_b64_tr_b16 v[140:141], v173 offset:26624
	ds_read_b64_tr_b16 v[142:143], v173 offset:27776
	ds_read_b64_tr_b16 v[10:11], v173 offset:33536
	ds_read_b64_tr_b16 v[12:13], v173 offset:34688
	s_nop 2
	v_max_f32_e32 v14, v65, v65
	v_max_f32_e32 v15, v64, v64
	v_max_f32_e32 v14, v15, v14
	v_max3_f32 v0, v48, v49, v50
	v_max3_f32 v14, v14, v66, v67
	v_max3_f32 v0, v0, v51, v52
	v_max3_f32 v14, v14, v68, v69
	v_max3_f32 v0, v0, v53, v54
	v_max3_f32 v14, v14, v70, v71
	v_max3_f32 v0, v0, v55, v56
	v_max3_f32 v14, v14, v72, v73
	v_max3_f32 v0, v0, v57, v58
	v_max3_f32 v14, v14, v74, v75
	v_max3_f32 v0, v0, v59, v60
	v_max3_f32 v14, v14, v76, v77
	v_max3_f32 v0, v0, v61, v62
	v_max3_f32 v14, v14, v78, v79
	v_max3_f32 v0, v0, v63, v14
	v_mov_b32_e32 v14, v0
	s_nop 1
	v_permlane32_swap_b32_e32 v0, v14
	v_max_f32_e32 v14, v14, v14
	v_max_f32_e32 v0, v0, v0
	v_max_f32_e32 v0, v0, v14
	v_sub_f32_e32 v14, v0, v164
	v_cmp_gt_f32_e64 s[6:7], s22, v164
	v_cmp_lt_f32_e32 vcc, s23, v14
	s_or_b64 vcc, s[6:7], vcc
	s_cbranch_vccz .LA_resc0
	v_cndmask_b32_e32 v14, v164, v0, vcc
	v_sub_f32_e32 v0, v164, v14
	v_exp_f32_e32 v0, v0
	v_mov_b32_e32 v164, v14
	v_cndmask_b32_e64 v0, v0, 1.0, s[6:7]
	v_mul_f32_e32 v172, v172, v0
	v_pk_mul_f32 v[46:47], v[46:47], v[0:1] op_sel_hi:[1,0]
	v_pk_mul_f32 v[44:45], v[44:45], v[0:1] op_sel_hi:[1,0]
	v_pk_mul_f32 v[42:43], v[42:43], v[0:1] op_sel_hi:[1,0]
	v_pk_mul_f32 v[40:41], v[40:41], v[0:1] op_sel_hi:[1,0]
	v_pk_mul_f32 v[38:39], v[38:39], v[0:1] op_sel_hi:[1,0]
	v_pk_mul_f32 v[36:37], v[36:37], v[0:1] op_sel_hi:[1,0]
	v_pk_mul_f32 v[34:35], v[34:35], v[0:1] op_sel_hi:[1,0]
	v_pk_mul_f32 v[32:33], v[32:33], v[0:1] op_sel_hi:[1,0]
	v_pk_mul_f32 v[30:31], v[30:31], v[0:1] op_sel_hi:[1,0]
	v_pk_mul_f32 v[28:29], v[28:29], v[0:1] op_sel_hi:[1,0]
	v_pk_mul_f32 v[26:27], v[26:27], v[0:1] op_sel_hi:[1,0]
	v_pk_mul_f32 v[24:25], v[24:25], v[0:1] op_sel_hi:[1,0]
	v_pk_mul_f32 v[22:23], v[22:23], v[0:1] op_sel_hi:[1,0]
	v_pk_mul_f32 v[20:21], v[20:21], v[0:1] op_sel_hi:[1,0]
	v_pk_mul_f32 v[18:19], v[18:19], v[0:1] op_sel_hi:[1,0]
	v_pk_mul_f32 v[16:17], v[16:17], v[0:1] op_sel_hi:[1,0]
.LA_resc0:
	v_pk_add_f32 v[14:15], v[48:49], v[164:165] op_sel_hi:[1,0] neg_lo:[0,1] neg_hi:[0,1]
	v_pk_add_f32 v[48:49], v[64:65], v[164:165] op_sel_hi:[1,0] neg_lo:[0,1] neg_hi:[0,1]
	v_exp_f32_e32 v14, v14
	v_exp_f32_e32 v15, v15
	v_exp_f32_e32 v64, v48
	v_exp_f32_e32 v65, v49
	v_pk_add_f32 v[48:49], v[50:51], v[164:165] op_sel_hi:[1,0] neg_lo:[0,1] neg_hi:[0,1]
	v_pk_add_f32 v[50:51], v[66:67], v[164:165] op_sel_hi:[1,0] neg_lo:[0,1] neg_hi:[0,1]
	v_exp_f32_e32 v66, v48
	v_exp_f32_e32 v67, v49
	v_exp_f32_e32 v174, v50
	v_exp_f32_e32 v175, v51
	v_pk_add_f32 v[50:51], v[52:53], v[164:165] op_sel_hi:[1,0] neg_lo:[0,1] neg_hi:[0,1]
	v_pk_add_f32 v[48:49], v[14:15], 0 op_sel_hi:[1,0]
	v_pk_add_f32 v[52:53], v[68:69], v[164:165] op_sel_hi:[1,0] neg_lo:[0,1] neg_hi:[0,1]
	v_exp_f32_e32 v50, v50
	v_exp_f32_e32 v51, v51
	v_pk_add_f32 v[48:49], v[64:65], v[48:49]
	v_exp_f32_e32 v68, v52
	v_exp_f32_e32 v69, v53
	v_pk_add_f32 v[52:53], v[54:55], v[164:165] op_sel_hi:[1,0] neg_lo:[0,1] neg_hi:[0,1]
	v_pk_add_f32 v[48:49], v[66:67], v[48:49]
	v_pk_add_f32 v[54:55], v[70:71], v[164:165] op_sel_hi:[1,0] neg_lo:[0,1] neg_hi:[0,1]
	v_exp_f32_e32 v52, v52
	v_exp_f32_e32 v53, v53
	v_pk_add_f32 v[48:49], v[174:175], v[48:49]
	v_exp_f32_e32 v70, v54
	v_exp_f32_e32 v71, v55
	v_pk_add_f32 v[54:55], v[56:57], v[164:165] op_sel_hi:[1,0] neg_lo:[0,1] neg_hi:[0,1]
	v_pk_add_f32 v[48:49], v[50:51], v[48:49]
	v_pk_add_f32 v[56:57], v[72:73], v[164:165] op_sel_hi:[1,0] neg_lo:[0,1] neg_hi:[0,1]
	v_exp_f32_e32 v72, v54
	v_exp_f32_e32 v73, v55
	v_pk_add_f32 v[48:49], v[68:69], v[48:49]
	v_exp_f32_e32 v176, v56
	v_exp_f32_e32 v177, v57
	v_pk_add_f32 v[54:55], v[58:59], v[164:165] op_sel_hi:[1,0] neg_lo:[0,1] neg_hi:[0,1]
; template <int MODE>
; DI void att_sm_head(f32x16 (&S)[2], float& mrefm, float& lrunm, f32x16 (&om)[2], bool latent, const MaskP& mk, int h) {
;     {
;         f32x16& s0 = S[0]; f32x16& s1 = S[1];
;         if (MODE == 1 && latent) {
;             const LAS float* rl = mk.rpbl + (mk.lt - mk.qrow + 7) * 31 + (15 - mk.qcol);
; #pragma unroll
;             for (int i = 0; i < 16; ++i) { const int kc = crow(i, h);
;                 { const bool ok = (kc >= mk.cs) && (kc < mk.cs + 16); const float bz = rl[ok ? kc : mk.qcol]; s0[i] = ok ? s0[i] + bz : -1e30f; }
;                 { const int kc2 = kc + 32; const bool ok = (kc2 >= mk.cs) && (kc2 < mk.cs + 16); const float bz = rl[ok ? kc2 : mk.qcol]; s1[i] = ok ? s1[i] + bz : -1e30f; } }
;         }
;         if (MODE == 2 && latent) {
;             const int kb = 64 * mk.lt;
; #pragma unroll
;             for (int i = 0; i < 16; ++i) { const int d0 = kb + crow(i, h) - mk.qpos, d1 = d0 + 32;
;                 if (d0 > 128 || d0 < -128) s0[i] = -1e30f; if (d1 > 128 || d1 < -128) s1[i] = -1e30f; }
;         }
;         float ma = fmaxf(fmaxf(s0[0], s0[1]), s0[2]), mb = fmaxf(fmaxf(s1[0], s1[1]), s1[2]);
; #pragma unroll
;         for (int i = 3; i < 15; i += 2) { ma = fmaxf(fmaxf(ma, s0[i]), s0[i + 1]); mb = fmaxf(fmaxf(mb, s1[i]), s1[i + 1]); }
;         ma = fmaxf(fmaxf(ma, s0[15]), fmaxf(mb, s1[15]));
;         { auto rr = __builtin_amdgcn_permlane32_swap(__float_as_uint(ma), __float_as_uint(ma), false, false); ma = fmaxf(__uint_as_float(rr[0]), __uint_as_float(rr[1])); }
;         const bool uninit = mrefm < -1e29f;
;         const bool need = uninit || (ma - mrefm > 8.0f);
;         if (__any(need)) {
;             const float mnew = need ? ma : mrefm;
;             const float f = uninit ? 1.0f : fast_exp2(mrefm - mnew);
;             mrefm = mnew; lrunm *= f;
; #pragma unroll
;             for (int e = 0; e < 2; ++e)
; #pragma unroll
;                 for (int i = 0; i < 16; ++i) om[e][i] *= f;
;         }
;     }
; }
; DI void att_sm_tail(f32x16 (&S)[2], bf16x8 (&pkm)[2][2], const float mrefm, float& lrunm) {
;     {
;         f32x16& s0 = S[0]; f32x16& s1 = S[1];
;         const f32x2 nm2 = {-mrefm, -mrefm};
;         f32x2 acc2 = {0.f, 0.f};
; #pragma unroll
;         for (int i = 0; i < 16; i += 2) {
;             f32x2 a = {s0[i], s0[i + 1]}, b = {s1[i], s1[i + 1]}; a += nm2; b += nm2;
	v_pk_add_f32 v[48:49], v[52:53], v[48:49]
	v_pk_add_f32 v[56:57], v[74:75], v[164:165] op_sel_hi:[1,0] neg_lo:[0,1] neg_hi:[0,1]
	v_exp_f32_e32 v58, v54
	v_exp_f32_e32 v59, v55
	v_pk_add_f32 v[48:49], v[70:71], v[48:49]
	v_exp_f32_e32 v74, v56
	v_exp_f32_e32 v75, v57
	v_pk_add_f32 v[54:55], v[60:61], v[164:165] op_sel_hi:[1,0] neg_lo:[0,1] neg_hi:[0,1]
	v_pk_add_f32 v[48:49], v[72:73], v[48:49]
	v_pk_add_f32 v[56:57], v[76:77], v[164:165] op_sel_hi:[1,0] neg_lo:[0,1] neg_hi:[0,1]
	v_exp_f32_e32 v60, v54
	v_exp_f32_e32 v61, v55
	v_pk_add_f32 v[48:49], v[176:177], v[48:49]
	v_exp_f32_e32 v76, v56
	v_exp_f32_e32 v77, v57
	v_pk_add_f32 v[54:55], v[62:63], v[164:165] op_sel_hi:[1,0] neg_lo:[0,1] neg_hi:[0,1]
	v_pk_add_f32 v[48:49], v[58:59], v[48:49]
	v_pk_add_f32 v[56:57], v[78:79], v[164:165] op_sel_hi:[1,0] neg_lo:[0,1] neg_hi:[0,1]
	v_exp_f32_e32 v62, v54
	v_exp_f32_e32 v63, v55
	v_pk_add_f32 v[48:49], v[74:75], v[48:49]
	v_exp_f32_e32 v78, v56
	v_exp_f32_e32 v79, v57
	v_pk_add_f32 v[48:49], v[60:61], v[48:49]
	v_cvt_pk_bf16_f32 v50, v50, v51
	v_pk_add_f32 v[48:49], v[76:77], v[48:49]
	v_cvt_pk_bf16_f32 v51, v52, v53
	v_pk_add_f32 v[48:49], v[62:63], v[48:49]
	v_cvt_pk_bf16_f32 v52, v64, v65
	v_pk_add_f32 v[48:49], v[78:79], v[48:49]
	v_cvt_pk_bf16_f32 v53, v174, v175
	v_add_f32_e32 v0, v48, v49
	v_add_f32_e32 v172, v172, v0
	v_cvt_pk_bf16_f32 v48, v14, v15
	v_cvt_pk_bf16_f32 v49, v66, v67
	v_cvt_pk_bf16_f32 v54, v68, v69
	v_cvt_pk_bf16_f32 v55, v70, v71
	v_cvt_pk_bf16_f32 v56, v72, v73
	v_cvt_pk_bf16_f32 v57, v58, v59
	v_cvt_pk_bf16_f32 v58, v60, v61
	v_cvt_pk_bf16_f32 v59, v62, v63
	v_cvt_pk_bf16_f32 v60, v176, v177
	v_cvt_pk_bf16_f32 v61, v74, v75
	v_cvt_pk_bf16_f32 v62, v76, v77
	v_cvt_pk_bf16_f32 v63, v78, v79
	s_setprio 1
	s_waitcnt lgkmcnt(2)
	v_mfma_f32_32x32x16_bf16 v[32:47], v[140:143], v[48:51], v[32:47]
	v_mfma_f32_32x32x16_bf16 v[32:47], v[136:139], v[56:59], v[32:47]
	v_mfma_f32_32x32x16_bf16 v[32:47], v[132:135], v[52:55], v[32:47]
	s_waitcnt lgkmcnt(0)
	v_mfma_f32_32x32x16_bf16 v[32:47], v[10:13], v[60:63], v[32:47]
	s_setprio 0
	ds_read_b64_tr_b16 v[10:11], v173 offset:28992
	ds_read_b64_tr_b16 v[12:13], v173 offset:30144
	ds_read_b64_tr_b16 v[64:65], v173 offset:31296
	ds_read_b64_tr_b16 v[66:67], v173 offset:32448
	ds_read_b64_tr_b16 v[68:69], v173 offset:26688
	ds_read_b64_tr_b16 v[70:71], v173 offset:27840
	ds_read_b64_tr_b16 v[72:73], v173 offset:33600
	ds_read_b64_tr_b16 v[74:75], v173 offset:34752
	s_setprio 1
	s_waitcnt lgkmcnt(2)
	v_mfma_f32_32x32x16_bf16 v[16:31], v[68:71], v[48:51], v[16:31]
	v_mfma_f32_32x32x16_bf16 v[16:31], v[10:13], v[56:59], v[16:31]
	v_mfma_f32_32x32x16_bf16 v[16:31], v[64:67], v[52:55], v[16:31]
	s_waitcnt lgkmcnt(0)
	v_mfma_f32_32x32x16_bf16 v[16:31], v[72:75], v[60:63], v[16:31]
	s_setprio 0
	s_branch .LBB0_659
.LA_slow1:
	v_add3_u32 v0, s16, v170, v156
	ds_read_b128 v[10:13], v0
	ds_read_b128 v[132:135], v0 offset:32
	ds_read_b128 v[64:67], v0 offset:6656
	ds_read_b128 v[136:139], v0 offset:64
	ds_read_b128 v[140:143], v0 offset:6688
	ds_read_b128 v[174:177], v0 offset:6720
	s_setprio 1
	s_waitcnt lgkmcnt(5)
	v_mfma_f32_32x32x16_bf16 v[48:63], v[10:13], v[104:107], 0
	s_waitcnt lgkmcnt(3)
	v_mfma_f32_32x32x16_bf16 v[64:79], v[64:67], v[104:107], 0
	v_mfma_f32_32x32x16_bf16 v[48:63], v[132:135], v[108:111], v[48:63]
	s_waitcnt lgkmcnt(1)
	v_mfma_f32_32x32x16_bf16 v[64:79], v[140:143], v[108:111], v[64:79]
	v_mfma_f32_32x32x16_bf16 v[48:63], v[136:139], v[112:115], v[48:63]
	s_waitcnt lgkmcnt(0)
	v_mfma_f32_32x32x16_bf16 v[64:79], v[174:177], v[112:115], v[64:79]
	s_setprio 0
	ds_read_b128 v[10:13], v0 offset:96
	ds_read_b128 v[132:135], v0 offset:128
	ds_read_b128 v[136:139], v0 offset:6752
	ds_read_b128 v[140:143], v0 offset:160
	ds_read_b128 v[174:177], v0 offset:6784
	ds_read_b128 v[178:181], v0 offset:6816
	s_setprio 1
	s_waitcnt lgkmcnt(5)
	v_mfma_f32_32x32x16_bf16 v[48:63], v[10:13], v[116:119], v[48:63]
	s_waitcnt lgkmcnt(3)
	v_mfma_f32_32x32x16_bf16 v[64:79], v[136:139], v[116:119], v[64:79]
	v_mfma_f32_32x32x16_bf16 v[48:63], v[132:135], v[120:123], v[48:63]
	s_waitcnt lgkmcnt(1)
	v_mfma_f32_32x32x16_bf16 v[64:79], v[174:177], v[120:123], v[64:79]
	v_mfma_f32_32x32x16_bf16 v[48:63], v[140:143], v[124:127], v[48:63]
	s_waitcnt lgkmcnt(0)
	v_mfma_f32_32x32x16_bf16 v[64:79], v[178:181], v[124:127], v[64:79]
	s_setprio 0
	ds_read_b64_tr_b16 v[140:141], v173 offset:35840
	ds_read_b64_tr_b16 v[142:143], v173 offset:36992
	ds_read_b64_tr_b16 v[136:137], v173 offset:38144
	ds_read_b64_tr_b16 v[138:139], v173 offset:39296
	ds_read_b64_tr_b16 v[132:133], v173 offset:40448
	ds_read_b64_tr_b16 v[134:135], v173 offset:41600
	ds_read_b64_tr_b16 v[10:11], v173 offset:42752
	ds_read_b64_tr_b16 v[12:13], v173 offset:43904
	s_nop 2
	v_max_f32_e32 v14, v65, v65
	v_max_f32_e32 v15, v64, v64
	v_max_f32_e32 v14, v15, v14
	v_max3_f32 v0, v48, v49, v50
	v_max3_f32 v14, v14, v66, v67
	v_max3_f32 v0, v0, v51, v52
	v_max3_f32 v14, v14, v68, v69
	v_max3_f32 v0, v0, v53, v54
	v_max3_f32 v14, v14, v70, v71
	v_max3_f32 v0, v0, v55, v56
	v_max3_f32 v14, v14, v72, v73
	v_max3_f32 v0, v0, v57, v58
	v_max3_f32 v14, v14, v74, v75
	v_max3_f32 v0, v0, v59, v60
	v_max3_f32 v14, v14, v76, v77
	v_max3_f32 v0, v0, v61, v62
	v_max3_f32 v14, v14, v78, v79
	v_max3_f32 v0, v0, v63, v14
	v_mov_b32_e32 v14, v0
	s_nop 1
	v_permlane32_swap_b32_e32 v0, v14
	v_max_f32_e32 v14, v14, v14
	v_max_f32_e32 v0, v0, v0
	v_max_f32_e32 v0, v0, v14
	v_sub_f32_e32 v14, v0, v164
	v_cmp_gt_f32_e64 s[6:7], s22, v164
	v_cmp_lt_f32_e32 vcc, s23, v14
	s_or_b64 vcc, s[6:7], vcc
	s_cbranch_vccz .LA_resc1
	v_cndmask_b32_e32 v14, v164, v0, vcc
	v_sub_f32_e32 v0, v164, v14
	v_exp_f32_e32 v0, v0
	v_mov_b32_e32 v164, v14
	v_cndmask_b32_e64 v0, v0, 1.0, s[6:7]
	v_mul_f32_e32 v172, v172, v0
	v_pk_mul_f32 v[46:47], v[46:47], v[0:1] op_sel_hi:[1,0]
	v_pk_mul_f32 v[44:45], v[44:45], v[0:1] op_sel_hi:[1,0]
	v_pk_mul_f32 v[42:43], v[42:43], v[0:1] op_sel_hi:[1,0]
	v_pk_mul_f32 v[40:41], v[40:41], v[0:1] op_sel_hi:[1,0]
	v_pk_mul_f32 v[38:39], v[38:39], v[0:1] op_sel_hi:[1,0]
	v_pk_mul_f32 v[36:37], v[36:37], v[0:1] op_sel_hi:[1,0]
	v_pk_mul_f32 v[34:35], v[34:35], v[0:1] op_sel_hi:[1,0]
	v_pk_mul_f32 v[32:33], v[32:33], v[0:1] op_sel_hi:[1,0]
	v_pk_mul_f32 v[30:31], v[30:31], v[0:1] op_sel_hi:[1,0]
	v_pk_mul_f32 v[28:29], v[28:29], v[0:1] op_sel_hi:[1,0]
	v_pk_mul_f32 v[26:27], v[26:27], v[0:1] op_sel_hi:[1,0]
	v_pk_mul_f32 v[24:25], v[24:25], v[0:1] op_sel_hi:[1,0]
	v_pk_mul_f32 v[22:23], v[22:23], v[0:1] op_sel_hi:[1,0]
	v_pk_mul_f32 v[20:21], v[20:21], v[0:1] op_sel_hi:[1,0]
	v_pk_mul_f32 v[18:19], v[18:19], v[0:1] op_sel_hi:[1,0]
	v_pk_mul_f32 v[16:17], v[16:17], v[0:1] op_sel_hi:[1,0]
; DI unsigned pk2(float lo, float hi) { f32x2 v = {lo, hi}; bf16x2_t b = __builtin_convertvector(v, bf16x2_t); return __builtin_bit_cast(unsigned, b); }
; DI float fast_exp2(float x) { return __builtin_amdgcn_exp2f(x); }
; DI void att_sm_tail(f32x16 (&S)[2], bf16x8 (&pkm)[2][2], const float mrefm, float& lrunm) {
;     {
;         f32x16& s0 = S[0]; f32x16& s1 = S[1];
;         const f32x2 nm2 = {-mrefm, -mrefm};
;         f32x2 acc2 = {0.f, 0.f};
; #pragma unroll
;         for (int i = 0; i < 16; i += 2) {
;             f32x2 a = {s0[i], s0[i + 1]}, b = {s1[i], s1[i + 1]}; a += nm2; b += nm2;
;             a.x = fast_exp2(a.x); a.y = fast_exp2(a.y); b.x = fast_exp2(b.x); b.y = fast_exp2(b.y);
;             acc2 += a; acc2 += b; s0[i] = a.x; s0[i + 1] = a.y; s1[i] = b.x; s1[i + 1] = b.y;
;         }
;         lrunm += acc2.x + acc2.y;
; #pragma unroll
;         for (int s = 0; s < 2; ++s) {
;             u32x4 w0, w1;
;             w0.x = pk2(s0[8 * s + 0], s0[8 * s + 1]); w0.y = pk2(s0[8 * s + 2], s0[8 * s + 3]); w0.z = pk2(s0[8 * s + 4], s0[8 * s + 5]); w0.w = pk2(s0[8 * s + 6], s0[8 * s + 7]);
;             w1.x = pk2(s1[8 * s + 0], s1[8 * s + 1]); w1.y = pk2(s1[8 * s + 2], s1[8 * s + 3]); w1.z = pk2(s1[8 * s + 4], s1[8 * s + 5]); w1.w = pk2(s1[8 * s + 6], s1[8 * s + 7]);
;             pkm[0][s] = __builtin_bit_cast(bf16x8, w0); pkm[1][s] = __builtin_bit_cast(bf16x8, w1);
;         }
;     }
; }
.LA_resc1:
	v_pk_add_f32 v[14:15], v[48:49], v[164:165] op_sel_hi:[1,0] neg_lo:[0,1] neg_hi:[0,1]
	v_pk_add_f32 v[48:49], v[64:65], v[164:165] op_sel_hi:[1,0] neg_lo:[0,1] neg_hi:[0,1]
	v_exp_f32_e32 v14, v14
	v_exp_f32_e32 v15, v15
	v_exp_f32_e32 v64, v48
	v_exp_f32_e32 v65, v49
	v_pk_add_f32 v[48:49], v[50:51], v[164:165] op_sel_hi:[1,0] neg_lo:[0,1] neg_hi:[0,1]
	v_pk_add_f32 v[50:51], v[66:67], v[164:165] op_sel_hi:[1,0] neg_lo:[0,1] neg_hi:[0,1]
	v_exp_f32_e32 v66, v48
	v_exp_f32_e32 v67, v49
	v_exp_f32_e32 v174, v50
	v_exp_f32_e32 v175, v51
	v_pk_add_f32 v[50:51], v[52:53], v[164:165] op_sel_hi:[1,0] neg_lo:[0,1] neg_hi:[0,1]
	v_pk_add_f32 v[48:49], v[14:15], 0 op_sel_hi:[1,0]
	v_pk_add_f32 v[52:53], v[68:69], v[164:165] op_sel_hi:[1,0] neg_lo:[0,1] neg_hi:[0,1]
	v_exp_f32_e32 v50, v50
	v_exp_f32_e32 v51, v51
	v_pk_add_f32 v[48:49], v[64:65], v[48:49]
	v_exp_f32_e32 v68, v52
	v_exp_f32_e32 v69, v53
	v_pk_add_f32 v[52:53], v[54:55], v[164:165] op_sel_hi:[1,0] neg_lo:[0,1] neg_hi:[0,1]
	v_pk_add_f32 v[48:49], v[66:67], v[48:49]
	v_pk_add_f32 v[54:55], v[70:71], v[164:165] op_sel_hi:[1,0] neg_lo:[0,1] neg_hi:[0,1]
	v_exp_f32_e32 v52, v52
	v_exp_f32_e32 v53, v53
	v_pk_add_f32 v[48:49], v[174:175], v[48:49]
	v_exp_f32_e32 v70, v54
	v_exp_f32_e32 v71, v55
	v_pk_add_f32 v[54:55], v[56:57], v[164:165] op_sel_hi:[1,0] neg_lo:[0,1] neg_hi:[0,1]
	v_pk_add_f32 v[48:49], v[50:51], v[48:49]
	v_pk_add_f32 v[56:57], v[72:73], v[164:165] op_sel_hi:[1,0] neg_lo:[0,1] neg_hi:[0,1]
	v_exp_f32_e32 v72, v54
	v_exp_f32_e32 v73, v55
	v_pk_add_f32 v[48:49], v[68:69], v[48:49]
	v_exp_f32_e32 v176, v56
	v_exp_f32_e32 v177, v57
	v_pk_add_f32 v[54:55], v[58:59], v[164:165] op_sel_hi:[1,0] neg_lo:[0,1] neg_hi:[0,1]
	v_pk_add_f32 v[48:49], v[52:53], v[48:49]
	v_pk_add_f32 v[56:57], v[74:75], v[164:165] op_sel_hi:[1,0] neg_lo:[0,1] neg_hi:[0,1]
	v_exp_f32_e32 v58, v54
	v_exp_f32_e32 v59, v55
	v_pk_add_f32 v[48:49], v[70:71], v[48:49]
	v_exp_f32_e32 v74, v56
	v_exp_f32_e32 v75, v57
	v_pk_add_f32 v[54:55], v[60:61], v[164:165] op_sel_hi:[1,0] neg_lo:[0,1] neg_hi:[0,1]
	v_pk_add_f32 v[48:49], v[72:73], v[48:49]
	v_pk_add_f32 v[56:57], v[76:77], v[164:165] op_sel_hi:[1,0] neg_lo:[0,1] neg_hi:[0,1]
	v_exp_f32_e32 v60, v54
	v_exp_f32_e32 v61, v55
	v_pk_add_f32 v[48:49], v[176:177], v[48:49]
	v_exp_f32_e32 v76, v56
	v_exp_f32_e32 v77, v57
	v_pk_add_f32 v[54:55], v[62:63], v[164:165] op_sel_hi:[1,0] neg_lo:[0,1] neg_hi:[0,1]
	v_pk_add_f32 v[48:49], v[58:59], v[48:49]
	v_pk_add_f32 v[56:57], v[78:79], v[164:165] op_sel_hi:[1,0] neg_lo:[0,1] neg_hi:[0,1]
	v_exp_f32_e32 v62, v54
	v_exp_f32_e32 v63, v55
	v_pk_add_f32 v[48:49], v[74:75], v[48:49]
	v_exp_f32_e32 v78, v56
	v_exp_f32_e32 v79, v57
	v_pk_add_f32 v[48:49], v[60:61], v[48:49]
	v_cvt_pk_bf16_f32 v50, v50, v51
	v_pk_add_f32 v[48:49], v[76:77], v[48:49]
	v_cvt_pk_bf16_f32 v51, v52, v53
	v_pk_add_f32 v[48:49], v[62:63], v[48:49]
	v_cvt_pk_bf16_f32 v52, v64, v65
	v_pk_add_f32 v[48:49], v[78:79], v[48:49]
	v_cvt_pk_bf16_f32 v53, v174, v175
	v_add_f32_e32 v0, v48, v49
	v_add_f32_e32 v172, v172, v0
	v_cvt_pk_bf16_f32 v48, v14, v15
	v_cvt_pk_bf16_f32 v49, v66, v67
	v_cvt_pk_bf16_f32 v54, v68, v69
	v_cvt_pk_bf16_f32 v55, v70, v71
	v_cvt_pk_bf16_f32 v56, v72, v73
	v_cvt_pk_bf16_f32 v57, v58, v59
	v_cvt_pk_bf16_f32 v58, v60, v61
	v_cvt_pk_bf16_f32 v59, v62, v63
	v_cvt_pk_bf16_f32 v60, v176, v177
	v_cvt_pk_bf16_f32 v61, v74, v75
	v_cvt_pk_bf16_f32 v62, v76, v77
	v_cvt_pk_bf16_f32 v63, v78, v79
	s_setprio 1
	s_waitcnt lgkmcnt(6)
	v_mfma_f32_32x32x16_bf16 v[32:47], v[140:143], v[48:51], v[32:47]
	s_waitcnt lgkmcnt(4)
	v_mfma_f32_32x32x16_bf16 v[32:47], v[136:139], v[56:59], v[32:47]
	s_waitcnt lgkmcnt(2)
	v_mfma_f32_32x32x16_bf16 v[32:47], v[132:135], v[52:55], v[32:47]
	s_waitcnt lgkmcnt(0)
	v_mfma_f32_32x32x16_bf16 v[32:47], v[10:13], v[60:63], v[32:47]
	s_setprio 0
	ds_read_b64_tr_b16 v[10:11], v173 offset:35904
	ds_read_b64_tr_b16 v[12:13], v173 offset:37056
	ds_read_b64_tr_b16 v[64:65], v173 offset:38208
	ds_read_b64_tr_b16 v[66:67], v173 offset:39360
	ds_read_b64_tr_b16 v[68:69], v173 offset:40512
	ds_read_b64_tr_b16 v[70:71], v173 offset:41664
	ds_read_b64_tr_b16 v[72:73], v173 offset:42816
	ds_read_b64_tr_b16 v[74:75], v173 offset:43968
	s_setprio 1
	s_waitcnt lgkmcnt(6)
	v_mfma_f32_32x32x16_bf16 v[16:31], v[10:13], v[48:51], v[16:31]
	s_waitcnt lgkmcnt(4)
	v_mfma_f32_32x32x16_bf16 v[16:31], v[64:67], v[56:59], v[16:31]
	s_waitcnt lgkmcnt(2)
	v_mfma_f32_32x32x16_bf16 v[16:31], v[68:71], v[52:55], v[16:31]
	s_waitcnt lgkmcnt(0)
	v_mfma_f32_32x32x16_bf16 v[16:31], v[72:75], v[60:63], v[16:31]
	s_setprio 0
	s_branch .LBB0_667
; #define LAS __attribute__((address_space(3)))
; template <int DQK, int NMAP>
; DI void att_qk(const LAS unsigned char* Kb, int r, int h, const bf16x8 (&qfm)[DQK / NMAP / 16], int mp, f32x16 (&S)[2]) {
;     constexpr int DQM = DQK / NMAP, NKS = DQM / 16, KP = DQK * 2 + 16, CH = (NKS > 4) ? 3 : NKS;
;     const LAS unsigned char* kp = Kb + r * KP + (mp * DQM + 8 * h) * 2;
;     const f32x16 z = {0.f, 0.f, 0.f, 0.f, 0.f, 0.f, 0.f, 0.f, 0.f, 0.f, 0.f, 0.f, 0.f, 0.f, 0.f, 0.f};
; #pragma unroll
;     for (int c = 0; c < NKS / CH; ++c) {
;         bf16x8 kf[2 * CH];
; #pragma unroll
;         for (int s = 0; s < CH; ++s) { kf[2 * s] = *(const LAS bf16x8*)(kp + 32 * (c * CH + s)); kf[2 * s + 1] = *(const LAS bf16x8*)(kp + 32 * KP + 32 * (c * CH + s)); }
;         __builtin_amdgcn_sched_barrier(0);
;         __builtin_amdgcn_s_setprio(1);
; #pragma unroll
;         for (int s = 0; s < CH; ++s) {
;             if (c == 0 && s == 0) { S[0] = __builtin_amdgcn_mfma_f32_32x32x16_bf16(kf[0], qfm[0], z, 0, 0, 0); S[1] = __builtin_amdgcn_mfma_f32_32x32x16_bf16(kf[1], qfm[0], z, 0, 0, 0); }
;             else { S[0] = __builtin_amdgcn_mfma_f32_32x32x16_bf16(kf[2 * s], qfm[c * CH + s], S[0], 0, 0, 0); S[1] = __builtin_amdgcn_mfma_f32_32x32x16_bf16(kf[2 * s + 1], qfm[c * CH + s], S[1], 0, 0, 0); }
;         }
;         __builtin_amdgcn_s_setprio(0);
;         __builtin_amdgcn_sched_barrier(0);
;     }
; }
; template <int MODE>
; DI void att_sm_head(f32x16 (&S)[2], float& mrefm, float& lrunm, f32x16 (&om)[2], bool latent, const MaskP& mk, int h) {
;     {
;         f32x16& s0 = S[0]; f32x16& s1 = S[1];
;         if (MODE == 1 && latent) {
;             const LAS float* rl = mk.rpbl + (mk.lt - mk.qrow + 7) * 31 + (15 - mk.qcol);
; #pragma unroll
;             for (int i = 0; i < 16; ++i) { const int kc = crow(i, h);
;                 { const bool ok = (kc >= mk.cs) && (kc < mk.cs + 16); const float bz = rl[ok ? kc : mk.qcol]; s0[i] = ok ? s0[i] + bz : -1e30f; }
;                 { const int kc2 = kc + 32; const bool ok = (kc2 >= mk.cs) && (kc2 < mk.cs + 16); const float bz = rl[ok ? kc2 : mk.qcol]; s1[i] = ok ? s1[i] + bz : -1e30f; } }
;         }
;         if (MODE == 2 && latent) {
;             const int kb = 64 * mk.lt;
; #pragma unroll
;             for (int i = 0; i < 16; ++i) { const int d0 = kb + crow(i, h) - mk.qpos, d1 = d0 + 32;
.LA_slow2:
	v_add3_u32 v0, s3, v170, v156
	ds_read_b128 v[10:13], v0
	ds_read_b128 v[132:135], v0 offset:32
	ds_read_b128 v[64:67], v0 offset:6656
	ds_read_b128 v[136:139], v0 offset:64
	ds_read_b128 v[140:143], v0 offset:6688
	ds_read_b128 v[174:177], v0 offset:6720
	s_setprio 1
	s_waitcnt lgkmcnt(5)
	v_mfma_f32_32x32x16_bf16 v[48:63], v[10:13], v[104:107], 0
	s_waitcnt lgkmcnt(3)
	v_mfma_f32_32x32x16_bf16 v[64:79], v[64:67], v[104:107], 0
	v_mfma_f32_32x32x16_bf16 v[48:63], v[132:135], v[108:111], v[48:63]
	s_waitcnt lgkmcnt(1)
	v_mfma_f32_32x32x16_bf16 v[64:79], v[140:143], v[108:111], v[64:79]
	v_mfma_f32_32x32x16_bf16 v[48:63], v[136:139], v[112:115], v[48:63]
	s_waitcnt lgkmcnt(0)
	v_mfma_f32_32x32x16_bf16 v[64:79], v[174:177], v[112:115], v[64:79]
	s_setprio 0
	ds_read_b128 v[10:13], v0 offset:96
	ds_read_b128 v[132:135], v0 offset:128
	ds_read_b128 v[136:139], v0 offset:6752
	ds_read_b128 v[140:143], v0 offset:160
	ds_read_b128 v[174:177], v0 offset:6784
	ds_read_b128 v[178:181], v0 offset:6816
	s_setprio 1
	s_waitcnt lgkmcnt(5)
	v_mfma_f32_32x32x16_bf16 v[48:63], v[10:13], v[116:119], v[48:63]
	s_waitcnt lgkmcnt(3)
	v_mfma_f32_32x32x16_bf16 v[64:79], v[136:139], v[116:119], v[64:79]
	v_mfma_f32_32x32x16_bf16 v[48:63], v[132:135], v[120:123], v[48:63]
	s_waitcnt lgkmcnt(1)
	v_mfma_f32_32x32x16_bf16 v[64:79], v[174:177], v[120:123], v[64:79]
	v_mfma_f32_32x32x16_bf16 v[48:63], v[140:143], v[124:127], v[48:63]
	s_waitcnt lgkmcnt(0)
	v_mfma_f32_32x32x16_bf16 v[64:79], v[178:181], v[124:127], v[64:79]
	s_setprio 0
	ds_read_b64_tr_b16 v[140:141], v173 offset:45056
	ds_read_b64_tr_b16 v[142:143], v173 offset:46208
	ds_read_b64_tr_b16 v[136:137], v173 offset:47360
	ds_read_b64_tr_b16 v[138:139], v173 offset:48512
	ds_read_b64_tr_b16 v[132:133], v173 offset:49664
	ds_read_b64_tr_b16 v[134:135], v173 offset:50816
	ds_read_b64_tr_b16 v[10:11], v173 offset:51968
	ds_read_b64_tr_b16 v[12:13], v173 offset:53120
	s_nop 2
	v_max_f32_e32 v14, v65, v65
	v_max_f32_e32 v15, v64, v64
	v_max_f32_e32 v14, v15, v14
	v_max3_f32 v0, v48, v49, v50
	v_max3_f32 v14, v14, v66, v67
	v_max3_f32 v0, v0, v51, v52
	v_max3_f32 v14, v14, v68, v69
	v_max3_f32 v0, v0, v53, v54
	v_max3_f32 v14, v14, v70, v71
	v_max3_f32 v0, v0, v55, v56
	v_max3_f32 v14, v14, v72, v73
	v_max3_f32 v0, v0, v57, v58
	v_max3_f32 v14, v14, v74, v75
	v_max3_f32 v0, v0, v59, v60
	v_max3_f32 v14, v14, v76, v77
	v_max3_f32 v0, v0, v61, v62
	v_max3_f32 v14, v14, v78, v79
	v_max3_f32 v0, v0, v63, v14
	v_mov_b32_e32 v14, v0
	s_nop 1
	v_permlane32_swap_b32_e32 v0, v14
	v_max_f32_e32 v14, v14, v14
	v_max_f32_e32 v0, v0, v0
	v_max_f32_e32 v0, v0, v14
	v_sub_f32_e32 v14, v0, v164
	v_cmp_gt_f32_e64 s[6:7], s22, v164
	v_cmp_lt_f32_e32 vcc, s23, v14
	s_or_b64 vcc, s[6:7], vcc
	s_cbranch_vccz .LA_resc2
	v_cndmask_b32_e32 v14, v164, v0, vcc
	v_sub_f32_e32 v0, v164, v14
	v_exp_f32_e32 v0, v0
	v_mov_b32_e32 v164, v14
	v_cndmask_b32_e64 v0, v0, 1.0, s[6:7]
	v_mul_f32_e32 v172, v172, v0
	v_pk_mul_f32 v[46:47], v[46:47], v[0:1] op_sel_hi:[1,0]
	v_pk_mul_f32 v[44:45], v[44:45], v[0:1] op_sel_hi:[1,0]
	v_pk_mul_f32 v[42:43], v[42:43], v[0:1] op_sel_hi:[1,0]
	v_pk_mul_f32 v[40:41], v[40:41], v[0:1] op_sel_hi:[1,0]
	v_pk_mul_f32 v[38:39], v[38:39], v[0:1] op_sel_hi:[1,0]
	v_pk_mul_f32 v[36:37], v[36:37], v[0:1] op_sel_hi:[1,0]
	v_pk_mul_f32 v[34:35], v[34:35], v[0:1] op_sel_hi:[1,0]
	v_pk_mul_f32 v[32:33], v[32:33], v[0:1] op_sel_hi:[1,0]
	v_pk_mul_f32 v[30:31], v[30:31], v[0:1] op_sel_hi:[1,0]
	v_pk_mul_f32 v[28:29], v[28:29], v[0:1] op_sel_hi:[1,0]
	v_pk_mul_f32 v[26:27], v[26:27], v[0:1] op_sel_hi:[1,0]
	v_pk_mul_f32 v[24:25], v[24:25], v[0:1] op_sel_hi:[1,0]
	v_pk_mul_f32 v[22:23], v[22:23], v[0:1] op_sel_hi:[1,0]
	v_pk_mul_f32 v[20:21], v[20:21], v[0:1] op_sel_hi:[1,0]
	v_pk_mul_f32 v[18:19], v[18:19], v[0:1] op_sel_hi:[1,0]
	v_pk_mul_f32 v[16:17], v[16:17], v[0:1] op_sel_hi:[1,0]
; DI unsigned pk2(float lo, float hi) { f32x2 v = {lo, hi}; bf16x2_t b = __builtin_convertvector(v, bf16x2_t); return __builtin_bit_cast(unsigned, b); }
; DI float fast_exp2(float x) { return __builtin_amdgcn_exp2f(x); }
; DI void att_sm_tail(f32x16 (&S)[2], bf16x8 (&pkm)[2][2], const float mrefm, float& lrunm) {
;     {
;         f32x16& s0 = S[0]; f32x16& s1 = S[1];
;         const f32x2 nm2 = {-mrefm, -mrefm};
;         f32x2 acc2 = {0.f, 0.f};
; #pragma unroll
;         for (int i = 0; i < 16; i += 2) {
;             f32x2 a = {s0[i], s0[i + 1]}, b = {s1[i], s1[i + 1]}; a += nm2; b += nm2;
;             a.x = fast_exp2(a.x); a.y = fast_exp2(a.y); b.x = fast_exp2(b.x); b.y = fast_exp2(b.y);
;             acc2 += a; acc2 += b; s0[i] = a.x; s0[i + 1] = a.y; s1[i] = b.x; s1[i + 1] = b.y;
;         }
;         lrunm += acc2.x + acc2.y;
; #pragma unroll
;         for (int s = 0; s < 2; ++s) {
;             u32x4 w0, w1;
;             w0.x = pk2(s0[8 * s + 0], s0[8 * s + 1]); w0.y = pk2(s0[8 * s + 2], s0[8 * s + 3]); w0.z = pk2(s0[8 * s + 4], s0[8 * s + 5]); w0.w = pk2(s0[8 * s + 6], s0[8 * s + 7]);
;             w1.x = pk2(s1[8 * s + 0], s1[8 * s + 1]); w1.y = pk2(s1[8 * s + 2], s1[8 * s + 3]); w1.z = pk2(s1[8 * s + 4], s1[8 * s + 5]); w1.w = pk2(s1[8 * s + 6], s1[8 * s + 7]);
;             pkm[0][s] = __builtin_bit_cast(bf16x8, w0); pkm[1][s] = __builtin_bit_cast(bf16x8, w1);
;         }
;     }
; }
.LA_resc2:
	v_pk_add_f32 v[14:15], v[48:49], v[164:165] op_sel_hi:[1,0] neg_lo:[0,1] neg_hi:[0,1]
	v_pk_add_f32 v[48:49], v[64:65], v[164:165] op_sel_hi:[1,0] neg_lo:[0,1] neg_hi:[0,1]
	v_exp_f32_e32 v14, v14
	v_exp_f32_e32 v15, v15
	v_exp_f32_e32 v64, v48
	v_exp_f32_e32 v65, v49
	v_pk_add_f32 v[48:49], v[50:51], v[164:165] op_sel_hi:[1,0] neg_lo:[0,1] neg_hi:[0,1]
	v_pk_add_f32 v[50:51], v[66:67], v[164:165] op_sel_hi:[1,0] neg_lo:[0,1] neg_hi:[0,1]
	v_exp_f32_e32 v66, v48
	v_exp_f32_e32 v67, v49
	v_exp_f32_e32 v174, v50
	v_exp_f32_e32 v175, v51
	v_pk_add_f32 v[50:51], v[52:53], v[164:165] op_sel_hi:[1,0] neg_lo:[0,1] neg_hi:[0,1]
	v_pk_add_f32 v[48:49], v[14:15], 0 op_sel_hi:[1,0]
	v_pk_add_f32 v[52:53], v[68:69], v[164:165] op_sel_hi:[1,0] neg_lo:[0,1] neg_hi:[0,1]
	v_exp_f32_e32 v50, v50
	v_exp_f32_e32 v51, v51
	v_pk_add_f32 v[48:49], v[64:65], v[48:49]
	v_exp_f32_e32 v68, v52
	v_exp_f32_e32 v69, v53
	v_pk_add_f32 v[52:53], v[54:55], v[164:165] op_sel_hi:[1,0] neg_lo:[0,1] neg_hi:[0,1]
	v_pk_add_f32 v[48:49], v[66:67], v[48:49]
	v_pk_add_f32 v[54:55], v[70:71], v[164:165] op_sel_hi:[1,0] neg_lo:[0,1] neg_hi:[0,1]
	v_exp_f32_e32 v52, v52
	v_exp_f32_e32 v53, v53
	v_pk_add_f32 v[48:49], v[174:175], v[48:49]
	v_exp_f32_e32 v70, v54
	v_exp_f32_e32 v71, v55
	v_pk_add_f32 v[54:55], v[56:57], v[164:165] op_sel_hi:[1,0] neg_lo:[0,1] neg_hi:[0,1]
	v_pk_add_f32 v[48:49], v[50:51], v[48:49]
	v_pk_add_f32 v[56:57], v[72:73], v[164:165] op_sel_hi:[1,0] neg_lo:[0,1] neg_hi:[0,1]
	v_exp_f32_e32 v72, v54
	v_exp_f32_e32 v73, v55
	v_pk_add_f32 v[48:49], v[68:69], v[48:49]
	v_exp_f32_e32 v176, v56
	v_exp_f32_e32 v177, v57
	v_pk_add_f32 v[54:55], v[58:59], v[164:165] op_sel_hi:[1,0] neg_lo:[0,1] neg_hi:[0,1]
	v_pk_add_f32 v[48:49], v[52:53], v[48:49]
	v_pk_add_f32 v[56:57], v[74:75], v[164:165] op_sel_hi:[1,0] neg_lo:[0,1] neg_hi:[0,1]
	v_exp_f32_e32 v58, v54
	v_exp_f32_e32 v59, v55
	v_pk_add_f32 v[48:49], v[70:71], v[48:49]
	v_exp_f32_e32 v74, v56
	v_exp_f32_e32 v75, v57
	v_pk_add_f32 v[54:55], v[60:61], v[164:165] op_sel_hi:[1,0] neg_lo:[0,1] neg_hi:[0,1]
	v_pk_add_f32 v[48:49], v[72:73], v[48:49]
	v_pk_add_f32 v[56:57], v[76:77], v[164:165] op_sel_hi:[1,0] neg_lo:[0,1] neg_hi:[0,1]
	v_exp_f32_e32 v60, v54
	v_exp_f32_e32 v61, v55
	v_pk_add_f32 v[48:49], v[176:177], v[48:49]
	v_exp_f32_e32 v76, v56
	v_exp_f32_e32 v77, v57
	v_pk_add_f32 v[54:55], v[62:63], v[164:165] op_sel_hi:[1,0] neg_lo:[0,1] neg_hi:[0,1]
	v_pk_add_f32 v[48:49], v[58:59], v[48:49]
	v_pk_add_f32 v[56:57], v[78:79], v[164:165] op_sel_hi:[1,0] neg_lo:[0,1] neg_hi:[0,1]
	v_exp_f32_e32 v62, v54
	v_exp_f32_e32 v63, v55
	v_pk_add_f32 v[48:49], v[74:75], v[48:49]
	v_exp_f32_e32 v78, v56
	v_exp_f32_e32 v79, v57
	v_pk_add_f32 v[48:49], v[60:61], v[48:49]
	v_cvt_pk_bf16_f32 v50, v50, v51
	v_pk_add_f32 v[48:49], v[76:77], v[48:49]
	v_cvt_pk_bf16_f32 v51, v52, v53
	v_pk_add_f32 v[48:49], v[62:63], v[48:49]
	v_cvt_pk_bf16_f32 v52, v64, v65
	v_pk_add_f32 v[48:49], v[78:79], v[48:49]
	v_cvt_pk_bf16_f32 v53, v174, v175
	v_add_f32_e32 v0, v48, v49
	v_add_f32_e32 v172, v172, v0
	v_cvt_pk_bf16_f32 v48, v14, v15
	v_cvt_pk_bf16_f32 v49, v66, v67
	v_cvt_pk_bf16_f32 v54, v68, v69
	v_cvt_pk_bf16_f32 v55, v70, v71
	v_cvt_pk_bf16_f32 v56, v72, v73
	v_cvt_pk_bf16_f32 v57, v58, v59
	v_cvt_pk_bf16_f32 v58, v60, v61
	v_cvt_pk_bf16_f32 v59, v62, v63
	v_cvt_pk_bf16_f32 v60, v176, v177
	v_cvt_pk_bf16_f32 v61, v74, v75
	v_cvt_pk_bf16_f32 v62, v76, v77
	v_cvt_pk_bf16_f32 v63, v78, v79
	s_setprio 1
	s_waitcnt lgkmcnt(6)
	v_mfma_f32_32x32x16_bf16 v[32:47], v[140:143], v[48:51], v[32:47]
	s_waitcnt lgkmcnt(4)
	v_mfma_f32_32x32x16_bf16 v[32:47], v[136:139], v[56:59], v[32:47]
	s_waitcnt lgkmcnt(2)
	v_mfma_f32_32x32x16_bf16 v[32:47], v[132:135], v[52:55], v[32:47]
	s_waitcnt lgkmcnt(0)
	v_mfma_f32_32x32x16_bf16 v[32:47], v[10:13], v[60:63], v[32:47]
	s_setprio 0
	ds_read_b64_tr_b16 v[10:11], v173 offset:45120
	ds_read_b64_tr_b16 v[12:13], v173 offset:46272
	ds_read_b64_tr_b16 v[64:65], v173 offset:47424
	ds_read_b64_tr_b16 v[66:67], v173 offset:48576
	ds_read_b64_tr_b16 v[68:69], v173 offset:49728
	ds_read_b64_tr_b16 v[70:71], v173 offset:50880
	ds_read_b64_tr_b16 v[72:73], v173 offset:52032
	ds_read_b64_tr_b16 v[74:75], v173 offset:53184
	s_setprio 1
	s_waitcnt lgkmcnt(6)
	v_mfma_f32_32x32x16_bf16 v[16:31], v[10:13], v[48:51], v[16:31]
	s_waitcnt lgkmcnt(4)
	v_mfma_f32_32x32x16_bf16 v[16:31], v[64:67], v[56:59], v[16:31]
	s_waitcnt lgkmcnt(2)
	v_mfma_f32_32x32x16_bf16 v[16:31], v[68:71], v[52:55], v[16:31]
	s_waitcnt lgkmcnt(0)
	v_mfma_f32_32x32x16_bf16 v[16:31], v[72:75], v[60:63], v[16:31]
	s_setprio 0
	s_branch .LBB0_675
